# K-loop load segments: M0-hazard s_nops replaced by the segment's own ds_reads, no s_setprio flips (fewer instructions in the loading wave)
# speedup vs baseline: 1.0008x; 1.0008x over previous
; #define PG8_STAGEA(bufoff, gbase, voff) PG8_STAGE_X(bufoff, gbase, voff, AUXA)
; #define PG8_STAGEB(bufoff, gbase, voff) PG8_STAGE_X(bufoff, gbase, voff, AUXB)
; #define PG8_LDA(dst, b, h) do { _Pragma("unroll") for (int m = 0; m < 4; ++m) _Pragma("unroll") for (int k = 0; k < 2; ++k) dst[m][k] = *(const PG8_LAS bf16x8*)(lds + PG8_SA(b, h) + aoff + m * 2048 + k * 1024); } while (0)
; #define PG8_LDB(dst, b, h) do { _Pragma("unroll") for (int n = 0; n < 2; ++n) _Pragma("unroll") for (int k = 0; k < 2; ++k) dst[n][k] = *(const PG8_LAS bf16x8*)(lds + PG8_SB(b, h) + boff + n * 2048 + k * 1024); } while (0)
; #define PG8_MMA(ai, bj, At, Bt) do { if (GEMM_PRIO_MODE == 0) __builtin_amdgcn_s_setprio(1); PG8_MMA_LOOPS \
;         acc[ai][bj][m][n] = __builtin_amdgcn_mfma_f32_16x16x32_bf16(Bt[n][k], At[m][k], acc[ai][bj][m][n], 0, 0, 0); if (GEMM_PRIO_MODE == 0) __builtin_amdgcn_s_setprio(0); } while (0)
; #define PG8_WAIT_V(n) asm volatile("s_waitcnt vmcnt(" #n ")" ::: "memory")
; #define PG8_WAIT_L(n) asm volatile("s_waitcnt lgkmcnt(" #n ")" ::: "memory")
;     ...
;         for (int t = t0; t < nt; t += 2) {
;             const bool last = (t == nt - 2);
;             const char* a1 = cA + (size_t)(t + 1) * kstepA;
;             const char* a2 = last ? nA : cA + (size_t)(t + 2) * kstepA; const char* b2 = last ? nB : cB + (size_t)(t + 2) * kstepB;
;             const char* a3 = a2 + kstepA; const char* b3 = b2 + kstepB;
;             if (last && has_next) S.a_ready(nxt);
;             if constexpr (SP2) {
;             PG8_LDB(B0, 0, 0); PG8_LDB(B1, 0, 1); PG8_SCHED; PG8_LDA(At, 0, 0); PG8_STAGEA(PG8_SA(1, 1), a1 + hstepA, voffA);
;     ...
;             const int relax = __builtin_amdgcn_readfirstlane((t == 0 && ui > 0) ? 1 : 0);
;             PG8_WAIT_VR(8, 24, relax); PG8_WAIT_L(0); PG8_BAR; PG8_MMA(0, 0, At, B0); PG8_MMA(0, 1, At, B1); PG8_BAR; PG8_SCHED;
;     ...
;             PG8_WAIT_V(8); PG8_WAIT_L(0); PG8_BAR; PG8_MMA(0, 0, At, B0); PG8_MMA(0, 1, At, B1); PG8_BAR; PG8_SCHED;
;     ...
;             PG8_LDA(At, 0, 1); PG8_STAGEB(PG8_SB(0, 0), b2, voffB); PG8_STAGEB(PG8_SB(0, 1), b2 + hstepB, voffB); PG8_STAGEA(PG8_SA(0, 0), a2, voffA);
;     ...
;             PG8_WAIT_VR(8, 24, relax); PG8_WAIT_L(0); PG8_BAR; PG8_MMA(1, 0, At, B0); PG8_MMA(1, 1, At, B1); PG8_BAR; PG8_SCHED;
;     ...
;             PG8_WAIT_V(8); PG8_WAIT_L(0); PG8_BAR; PG8_MMA(1, 0, At, B0); PG8_MMA(1, 1, At, B1); PG8_BAR; PG8_SCHED;
.LBB0_129:
	s_add_u32 s10, s8, 0xfff00080
	s_addc_u32 s11, s9, -1
	s_add_i32 s18, 0, 0x10000
	s_cmp_eq_u32 s27, 60
	s_cselect_b32 s15, s4, s11
	s_cselect_b32 s14, s5, s10
	s_cselect_b32 s11, s16, s1
	s_cselect_b32 s10, s17, s0
	s_add_i32 s20, 0, 0x14000
	s_waitcnt lgkmcnt(0)
	ds_read_b128 v[130:133], v226
	ds_read_b128 v[134:137], v226 offset:1024
	ds_read_b128 v[152:155], v226 offset:2048
	ds_read_b128 v[156:159], v226 offset:3072
	ds_read_b128 v[160:163], v226 offset:16384
	ds_read_b128 v[174:177], v226 offset:17408
	ds_read_b128 v[178:181], v226 offset:18432
	ds_read_b128 v[182:185], v226 offset:19456
	s_add_i32 m0, s51, 0xc000
	ds_read_b128 v[186:189], v172
	ds_read_b128 v[190:193], v172 offset:1024
	ds_read_b128 v[194:197], v172 offset:2048
	ds_read_b128 v[198:201], v172 offset:3072
	ds_read_b128 v[202:205], v172 offset:4096
	ds_read_b128 v[206:209], v172 offset:5120
	ds_read_b128 v[210:213], v172 offset:6144
	global_load_lds_dwordx4 v148, s[8:9]
	s_add_i32 m0, s51, 0xe000
	ds_read_b128 v[214:217], v172 offset:7168
	global_load_lds_dwordx4 v150, s[8:9]
	s_waitcnt vmcnt(8)
	s_waitcnt lgkmcnt(0)
	s_barrier
	v_mfma_f32_16x16x32_bf16 v[126:129], v[130:133], v[186:189], v[126:129]
	v_mfma_f32_16x16x32_bf16 v[122:125], v[152:155], v[186:189], v[122:125]
	v_mfma_f32_16x16x32_bf16 v[110:113], v[130:133], v[194:197], v[110:113]
	v_mfma_f32_16x16x32_bf16 v[106:109], v[152:155], v[194:197], v[106:109]
	v_mfma_f32_16x16x32_bf16 v[94:97], v[130:133], v[202:205], v[94:97]
	v_mfma_f32_16x16x32_bf16 v[90:93], v[152:155], v[202:205], v[90:93]
	v_mfma_f32_16x16x32_bf16 v[78:81], v[130:133], v[210:213], v[78:81]
	v_mfma_f32_16x16x32_bf16 v[74:77], v[152:155], v[210:213], v[74:77]
	v_mfma_f32_16x16x32_bf16 v[126:129], v[134:137], v[190:193], v[126:129]
	v_mfma_f32_16x16x32_bf16 v[122:125], v[156:159], v[190:193], v[122:125]
	v_mfma_f32_16x16x32_bf16 v[110:113], v[134:137], v[198:201], v[110:113]
	v_mfma_f32_16x16x32_bf16 v[106:109], v[156:159], v[198:201], v[106:109]
	v_mfma_f32_16x16x32_bf16 v[94:97], v[134:137], v[206:209], v[94:97]
	v_mfma_f32_16x16x32_bf16 v[90:93], v[156:159], v[206:209], v[90:93]
	v_mfma_f32_16x16x32_bf16 v[78:81], v[134:137], v[214:217], v[78:81]
	v_mfma_f32_16x16x32_bf16 v[74:77], v[156:159], v[214:217], v[74:77]
	v_mfma_f32_16x16x32_bf16 v[118:121], v[160:163], v[186:189], v[118:121]
	v_mfma_f32_16x16x32_bf16 v[114:117], v[178:181], v[186:189], v[114:117]
	v_mfma_f32_16x16x32_bf16 v[102:105], v[160:163], v[194:197], v[102:105]
	v_mfma_f32_16x16x32_bf16 v[98:101], v[178:181], v[194:197], v[98:101]
	v_mfma_f32_16x16x32_bf16 v[86:89], v[160:163], v[202:205], v[86:89]
	v_mfma_f32_16x16x32_bf16 v[82:85], v[178:181], v[202:205], v[82:85]
	v_mfma_f32_16x16x32_bf16 v[70:73], v[160:163], v[210:213], v[70:73]
	v_mfma_f32_16x16x32_bf16 v[66:69], v[178:181], v[210:213], v[66:69]
	v_mfma_f32_16x16x32_bf16 v[118:121], v[174:177], v[190:193], v[118:121]
	v_mfma_f32_16x16x32_bf16 v[114:117], v[182:185], v[190:193], v[114:117]
	v_mfma_f32_16x16x32_bf16 v[102:105], v[174:177], v[198:201], v[102:105]
	v_mfma_f32_16x16x32_bf16 v[98:101], v[182:185], v[198:201], v[98:101]
	v_mfma_f32_16x16x32_bf16 v[86:89], v[174:177], v[206:209], v[86:89]
	v_mfma_f32_16x16x32_bf16 v[82:85], v[182:185], v[206:209], v[82:85]
	v_mfma_f32_16x16x32_bf16 v[70:73], v[174:177], v[214:217], v[70:73]
	v_mfma_f32_16x16x32_bf16 v[66:69], v[182:185], v[214:217], v[66:69]
	s_barrier
	s_add_i32 s18, s18, s42
	s_mov_b32 m0, s18
	ds_read_b128 v[186:189], v172 offset:16384
	ds_read_b128 v[190:193], v172 offset:17408
	ds_read_b128 v[194:197], v172 offset:18432
	ds_read_b128 v[198:201], v172 offset:19456
	s_add_u32 s100, s14, 0x80
	s_addc_u32 s101, s15, 0
	global_load_lds_dwordx4 v142, s[10:11]
	s_add_i32 m0, s18, 0x2000
	s_add_u32 s18, s10, 0x100000
	s_addc_u32 s19, s11, 0
	s_add_i32 s20, s20, s42
	global_load_lds_dwordx4 v138, s[10:11]
	s_mov_b32 m0, s20
	ds_read_b128 v[214:217], v172 offset:23552
	global_load_lds_dwordx4 v142, s[18:19]
	s_add_i32 m0, s20, 0x2000
	ds_read_b128 v[210:213], v172 offset:22528
	global_load_lds_dwordx4 v138, s[18:19]
	s_mov_b32 m0, s51
	ds_read_b128 v[206:209], v172 offset:21504
	global_load_lds_dwordx4 v144, s[14:15]
	s_mov_b32 m0, s68
	ds_read_b128 v[202:205], v172 offset:20480
	global_load_lds_dwordx4 v140, s[14:15]
	s_waitcnt vmcnt(8)
	s_waitcnt lgkmcnt(0)
	s_barrier
	v_mfma_f32_16x16x32_bf16 v[62:65], v[130:133], v[186:189], v[62:65]
	v_mfma_f32_16x16x32_bf16 v[58:61], v[152:155], v[186:189], v[58:61]
	v_mfma_f32_16x16x32_bf16 v[46:49], v[130:133], v[194:197], v[46:49]
	v_mfma_f32_16x16x32_bf16 v[42:45], v[152:155], v[194:197], v[42:45]
	v_mfma_f32_16x16x32_bf16 v[30:33], v[130:133], v[202:205], v[30:33]
	v_mfma_f32_16x16x32_bf16 v[26:29], v[152:155], v[202:205], v[26:29]
	v_mfma_f32_16x16x32_bf16 v[12:15], v[130:133], v[210:213], v[12:15]
	v_mfma_f32_16x16x32_bf16 v[8:11], v[152:155], v[210:213], v[8:11]
	v_mfma_f32_16x16x32_bf16 v[62:65], v[134:137], v[190:193], v[62:65]
	v_mfma_f32_16x16x32_bf16 v[58:61], v[156:159], v[190:193], v[58:61]
	v_mfma_f32_16x16x32_bf16 v[46:49], v[134:137], v[198:201], v[46:49]
	v_mfma_f32_16x16x32_bf16 v[42:45], v[156:159], v[198:201], v[42:45]
	v_mfma_f32_16x16x32_bf16 v[30:33], v[134:137], v[206:209], v[30:33]
	v_mfma_f32_16x16x32_bf16 v[26:29], v[156:159], v[206:209], v[26:29]
	v_mfma_f32_16x16x32_bf16 v[12:15], v[134:137], v[214:217], v[12:15]
	v_mfma_f32_16x16x32_bf16 v[8:11], v[156:159], v[214:217], v[8:11]
	v_mfma_f32_16x16x32_bf16 v[54:57], v[160:163], v[186:189], v[54:57]
	v_mfma_f32_16x16x32_bf16 v[50:53], v[178:181], v[186:189], v[50:53]
	v_mfma_f32_16x16x32_bf16 v[38:41], v[160:163], v[194:197], v[38:41]
	v_mfma_f32_16x16x32_bf16 v[34:37], v[178:181], v[194:197], v[34:37]
	v_mfma_f32_16x16x32_bf16 v[22:25], v[160:163], v[202:205], v[22:25]
	v_mfma_f32_16x16x32_bf16 v[18:21], v[178:181], v[202:205], v[18:21]
	v_mfma_f32_16x16x32_bf16 v[4:7], v[160:163], v[210:213], v[4:7]
	v_mfma_f32_16x16x32_bf16 v[0:3], v[178:181], v[210:213], v[0:3]
	v_mfma_f32_16x16x32_bf16 v[54:57], v[174:177], v[190:193], v[54:57]
	v_mfma_f32_16x16x32_bf16 v[50:53], v[182:185], v[190:193], v[50:53]
	v_mfma_f32_16x16x32_bf16 v[38:41], v[174:177], v[198:201], v[38:41]
	v_mfma_f32_16x16x32_bf16 v[34:37], v[182:185], v[198:201], v[34:37]
	v_mfma_f32_16x16x32_bf16 v[22:25], v[174:177], v[206:209], v[22:25]
	v_mfma_f32_16x16x32_bf16 v[18:21], v[182:185], v[206:209], v[18:21]
	v_mfma_f32_16x16x32_bf16 v[4:7], v[174:177], v[214:217], v[4:7]
	v_mfma_f32_16x16x32_bf16 v[0:3], v[182:185], v[214:217], v[0:3]
	s_barrier
; #define PG8_STAGEA(bufoff, gbase, voff) PG8_STAGE_X(bufoff, gbase, voff, AUXA)
; #define PG8_STAGEB(bufoff, gbase, voff) PG8_STAGE_X(bufoff, gbase, voff, AUXB)
; #define PG8_LDA(dst, b, h) do { _Pragma("unroll") for (int m = 0; m < 4; ++m) _Pragma("unroll") for (int k = 0; k < 2; ++k) dst[m][k] = *(const PG8_LAS bf16x8*)(lds + PG8_SA(b, h) + aoff + m * 2048 + k * 1024); } while (0)
; #define PG8_LDB(dst, b, h) do { _Pragma("unroll") for (int n = 0; n < 2; ++n) _Pragma("unroll") for (int k = 0; k < 2; ++k) dst[n][k] = *(const PG8_LAS bf16x8*)(lds + PG8_SB(b, h) + boff + n * 2048 + k * 1024); } while (0)
; #define PG8_MMA(ai, bj, At, Bt) do { if (GEMM_PRIO_MODE == 0) __builtin_amdgcn_s_setprio(1); PG8_MMA_LOOPS \
;         acc[ai][bj][m][n] = __builtin_amdgcn_mfma_f32_16x16x32_bf16(Bt[n][k], At[m][k], acc[ai][bj][m][n], 0, 0, 0); if (GEMM_PRIO_MODE == 0) __builtin_amdgcn_s_setprio(0); } while (0)
; #define PG8_WAIT_V(n) asm volatile("s_waitcnt vmcnt(" #n ")" ::: "memory")
; #define PG8_WAIT_L(n) asm volatile("s_waitcnt lgkmcnt(" #n ")" ::: "memory")
; #define PG8_BAR __builtin_amdgcn_s_barrier()
; #define PG8_SCHED __builtin_amdgcn_sched_barrier(0)
;     ...
;             PG8_LDB(B0, 1, 0); PG8_LDB(B1, 1, 1); PG8_SCHED; PG8_LDA(At, 1, 0); PG8_STAGEA(PG8_SA(0, 1), a2 + hstepA, voffA);
;             PG8_WAIT_V(8); PG8_WAIT_L(0); PG8_BAR; PG8_MMA(0, 0, At, B0); PG8_MMA(0, 1, At, B1); PG8_BAR; PG8_SCHED;
;             PG8_LDA(At, 1, 1); PG8_STAGEB(PG8_SB(1, 0), b3, voffB); PG8_STAGEB(PG8_SB(1, 1), b3 + hstepB, voffB); PG8_STAGEA(PG8_SA(1, 0), a3, voffA);
;             PG8_WAIT_V(8); PG8_WAIT_L(0); PG8_BAR; PG8_MMA(1, 0, At, B0); PG8_MMA(1, 1, At, B1); PG8_BAR; PG8_SCHED;
	s_add_i32 s18, 0, 0x18000
	s_add_i32 s19, 0, 0x1c000
	ds_read_b128 v[130:133], v226 offset:32768
	ds_read_b128 v[134:137], v226 offset:33792
	ds_read_b128 v[152:155], v226 offset:34816
	ds_read_b128 v[156:159], v226 offset:35840
	ds_read_b128 v[160:163], v226 offset:49152
	ds_read_b128 v[174:177], v226 offset:50176
	ds_read_b128 v[178:181], v226 offset:51200
	ds_read_b128 v[182:185], v226 offset:52224
	s_add_u32 s14, s14, 0x100000
	s_addc_u32 s15, s15, 0
	s_mov_b32 m0, s69
	ds_read_b128 v[186:189], v172 offset:32768
	ds_read_b128 v[190:193], v172 offset:33792
	ds_read_b128 v[194:197], v172 offset:34816
	ds_read_b128 v[198:201], v172 offset:35840
	ds_read_b128 v[202:205], v172 offset:36864
	ds_read_b128 v[206:209], v172 offset:37888
	ds_read_b128 v[210:213], v172 offset:38912
	global_load_lds_dwordx4 v144, s[14:15]
	s_mov_b32 m0, s72
	ds_read_b128 v[214:217], v172 offset:39936
	global_load_lds_dwordx4 v140, s[14:15]
	s_waitcnt vmcnt(8)
	s_waitcnt lgkmcnt(0)
	s_nop 0
	s_barrier
	v_mfma_f32_16x16x32_bf16 v[126:129], v[130:133], v[186:189], v[126:129]
	v_mfma_f32_16x16x32_bf16 v[122:125], v[152:155], v[186:189], v[122:125]
	v_mfma_f32_16x16x32_bf16 v[110:113], v[130:133], v[194:197], v[110:113]
	v_mfma_f32_16x16x32_bf16 v[106:109], v[152:155], v[194:197], v[106:109]
	v_mfma_f32_16x16x32_bf16 v[94:97], v[130:133], v[202:205], v[94:97]
	v_mfma_f32_16x16x32_bf16 v[90:93], v[152:155], v[202:205], v[90:93]
	v_mfma_f32_16x16x32_bf16 v[78:81], v[130:133], v[210:213], v[78:81]
	v_mfma_f32_16x16x32_bf16 v[74:77], v[152:155], v[210:213], v[74:77]
	v_mfma_f32_16x16x32_bf16 v[126:129], v[134:137], v[190:193], v[126:129]
	v_mfma_f32_16x16x32_bf16 v[122:125], v[156:159], v[190:193], v[122:125]
	v_mfma_f32_16x16x32_bf16 v[110:113], v[134:137], v[198:201], v[110:113]
	v_mfma_f32_16x16x32_bf16 v[106:109], v[156:159], v[198:201], v[106:109]
	v_mfma_f32_16x16x32_bf16 v[94:97], v[134:137], v[206:209], v[94:97]
	v_mfma_f32_16x16x32_bf16 v[90:93], v[156:159], v[206:209], v[90:93]
	v_mfma_f32_16x16x32_bf16 v[78:81], v[134:137], v[214:217], v[78:81]
	v_mfma_f32_16x16x32_bf16 v[74:77], v[156:159], v[214:217], v[74:77]
	v_mfma_f32_16x16x32_bf16 v[118:121], v[160:163], v[186:189], v[118:121]
	v_mfma_f32_16x16x32_bf16 v[114:117], v[178:181], v[186:189], v[114:117]
	v_mfma_f32_16x16x32_bf16 v[102:105], v[160:163], v[194:197], v[102:105]
	v_mfma_f32_16x16x32_bf16 v[98:101], v[178:181], v[194:197], v[98:101]
	v_mfma_f32_16x16x32_bf16 v[86:89], v[160:163], v[202:205], v[86:89]
	v_mfma_f32_16x16x32_bf16 v[82:85], v[178:181], v[202:205], v[82:85]
	v_mfma_f32_16x16x32_bf16 v[70:73], v[160:163], v[210:213], v[70:73]
	v_mfma_f32_16x16x32_bf16 v[66:69], v[178:181], v[210:213], v[66:69]
	v_mfma_f32_16x16x32_bf16 v[118:121], v[174:177], v[190:193], v[118:121]
	v_mfma_f32_16x16x32_bf16 v[114:117], v[182:185], v[190:193], v[114:117]
	v_mfma_f32_16x16x32_bf16 v[102:105], v[174:177], v[198:201], v[102:105]
	v_mfma_f32_16x16x32_bf16 v[98:101], v[182:185], v[198:201], v[98:101]
	v_mfma_f32_16x16x32_bf16 v[86:89], v[174:177], v[206:209], v[86:89]
	v_mfma_f32_16x16x32_bf16 v[82:85], v[182:185], v[206:209], v[82:85]
	v_mfma_f32_16x16x32_bf16 v[70:73], v[174:177], v[214:217], v[70:73]
	v_mfma_f32_16x16x32_bf16 v[66:69], v[182:185], v[214:217], v[66:69]
	s_barrier
	s_add_i32 s14, s18, s42
	s_mov_b32 m0, s14
	ds_read_b128 v[186:189], v172 offset:49152
	ds_read_b128 v[190:193], v172 offset:50176
	ds_read_b128 v[194:197], v172 offset:51200
	ds_read_b128 v[198:201], v172 offset:52224
	s_add_u32 vcc_lo, s10, 0x80
	s_addc_u32 vcc_hi, s11, 0
	global_load_lds_dwordx4 v142, vcc
	s_add_i32 m0, s14, 0x2000
	s_add_u32 s10, s10, 0x100080
	s_addc_u32 s11, s11, 0
	s_add_i32 s14, s19, s42
	global_load_lds_dwordx4 v138, vcc
	s_mov_b32 m0, s14
	ds_read_b128 v[214:217], v172 offset:56320
	global_load_lds_dwordx4 v142, s[10:11]
	s_add_i32 m0, s14, 0x2000
	ds_read_b128 v[210:213], v172 offset:55296
	global_load_lds_dwordx4 v138, s[10:11]
	s_mov_b32 m0, s73
	ds_read_b128 v[206:209], v172 offset:54272
	global_load_lds_dwordx4 v144, s[100:101]
	s_mov_b32 m0, s82
	ds_read_b128 v[202:205], v172 offset:53248
	global_load_lds_dwordx4 v140, s[100:101]
	s_waitcnt vmcnt(8)
	s_waitcnt lgkmcnt(0)
	s_barrier
	v_mfma_f32_16x16x32_bf16 v[62:65], v[130:133], v[186:189], v[62:65]
	v_mfma_f32_16x16x32_bf16 v[58:61], v[152:155], v[186:189], v[58:61]
	v_mfma_f32_16x16x32_bf16 v[46:49], v[130:133], v[194:197], v[46:49]
	v_mfma_f32_16x16x32_bf16 v[42:45], v[152:155], v[194:197], v[42:45]
	v_mfma_f32_16x16x32_bf16 v[30:33], v[130:133], v[202:205], v[30:33]
	v_mfma_f32_16x16x32_bf16 v[26:29], v[152:155], v[202:205], v[26:29]
	v_mfma_f32_16x16x32_bf16 v[12:15], v[130:133], v[210:213], v[12:15]
	v_mfma_f32_16x16x32_bf16 v[8:11], v[152:155], v[210:213], v[8:11]
	v_mfma_f32_16x16x32_bf16 v[62:65], v[134:137], v[190:193], v[62:65]
	v_mfma_f32_16x16x32_bf16 v[58:61], v[156:159], v[190:193], v[58:61]
	v_mfma_f32_16x16x32_bf16 v[46:49], v[134:137], v[198:201], v[46:49]
	v_mfma_f32_16x16x32_bf16 v[42:45], v[156:159], v[198:201], v[42:45]
	v_mfma_f32_16x16x32_bf16 v[30:33], v[134:137], v[206:209], v[30:33]
	v_mfma_f32_16x16x32_bf16 v[26:29], v[156:159], v[206:209], v[26:29]
	v_mfma_f32_16x16x32_bf16 v[12:15], v[134:137], v[214:217], v[12:15]
	v_mfma_f32_16x16x32_bf16 v[8:11], v[156:159], v[214:217], v[8:11]
	v_mfma_f32_16x16x32_bf16 v[54:57], v[160:163], v[186:189], v[54:57]
	v_mfma_f32_16x16x32_bf16 v[50:53], v[178:181], v[186:189], v[50:53]
	v_mfma_f32_16x16x32_bf16 v[38:41], v[160:163], v[194:197], v[38:41]
	v_mfma_f32_16x16x32_bf16 v[34:37], v[178:181], v[194:197], v[34:37]
	v_mfma_f32_16x16x32_bf16 v[22:25], v[160:163], v[202:205], v[22:25]
	v_mfma_f32_16x16x32_bf16 v[18:21], v[178:181], v[202:205], v[18:21]
	v_mfma_f32_16x16x32_bf16 v[4:7], v[160:163], v[210:213], v[4:7]
	v_mfma_f32_16x16x32_bf16 v[0:3], v[178:181], v[210:213], v[0:3]
	v_mfma_f32_16x16x32_bf16 v[54:57], v[174:177], v[190:193], v[54:57]
	v_mfma_f32_16x16x32_bf16 v[50:53], v[182:185], v[190:193], v[50:53]
	v_mfma_f32_16x16x32_bf16 v[38:41], v[174:177], v[198:201], v[38:41]
	v_mfma_f32_16x16x32_bf16 v[34:37], v[182:185], v[198:201], v[34:37]
	v_mfma_f32_16x16x32_bf16 v[22:25], v[174:177], v[206:209], v[22:25]
	v_mfma_f32_16x16x32_bf16 v[18:21], v[182:185], v[206:209], v[18:21]
	v_mfma_f32_16x16x32_bf16 v[4:7], v[174:177], v[214:217], v[4:7]
	v_mfma_f32_16x16x32_bf16 v[0:3], v[182:185], v[214:217], v[0:3]
	s_barrier
	s_add_i32 s27, s27, 2
	s_add_u32 s8, s8, 0x100
	s_addc_u32 s9, s9, 0
	s_add_u32 s0, s0, 0x100
	s_addc_u32 s1, s1, 0
	s_cmp_gt_u32 s27, 61
	s_cbranch_scc0 .LBB0_129
	s_and_b64 vcc, exec, s[24:25]
	s_cbranch_vccz .LBB0_132
	s_barrier

; #define PG8_STAGEA(bufoff, gbase, voff) PG8_STAGE_X(bufoff, gbase, voff, AUXA)
; #define PG8_STR(x) PG8_STR2(x)
;     ...
;         const bool has_next = S.next(ui + 1, nxt);
;         const char* nA = has_next ? (const char*)g.A + (size_t)nxt.pm * tstepA : cA; const char* nB = has_next ? (const char*)g.Bt + (size_t)nxt.pn * tstepB : cB;
;         int t0 = 0;
;         if constexpr (SP2 && GEMM_RELAX == 1) { if (ui > 0) {
;             const char* a1 = cA + kstepA; const char* a2 = cA + 2 * kstepA; const char* b2 = cB + 2 * kstepB; const char* a3 = a2 + kstepA; const char* b3 = b2 + kstepB;
;             PG8_LDB(B0, 0, 0); PG8_LDB(B1, 0, 1); PG8_SCHED; PG8_LDA(At, 0, 0); PG8_STAGEA(PG8_SA(1, 1), a1 + hstepA, voffA);
;             PG8_WAIT_V(24); PG8_WAIT_L(0); PG8_BAR; PG8_MMA(0, 0, At, B0); PG8_MMA(0, 1, At, B1); PG8_BAR; PG8_SCHED;
;             PG8_LDA(At, 0, 1); PG8_STAGEB(PG8_SB(0, 0), b2, voffB); PG8_STAGEB(PG8_SB(0, 1), b2 + hstepB, voffB); PG8_STAGEA(PG8_SA(0, 0), a2, voffA);
;             PG8_WAIT_V(24); PG8_WAIT_L(0); PG8_BAR; PG8_MMA(1, 0, At, B0); PG8_MMA(1, 1, At, B1); PG8_BAR; PG8_SCHED;
;             PG8_LDB(B0, 1, 0); PG8_LDB(B1, 1, 1); PG8_SCHED; PG8_LDA(At, 1, 0); PG8_STAGEA(PG8_SA(0, 1), a2 + hstepA, voffA);
;             PG8_WAIT_V(8); PG8_WAIT_L(0); PG8_BAR; PG8_MMA(0, 0, At, B0); PG8_MMA(0, 1, At, B1); PG8_BAR; PG8_SCHED;
;             PG8_LDA(At, 1, 1); PG8_STAGEB(PG8_SB(1, 0), b3, voffB); PG8_STAGEB(PG8_SB(1, 1), b3 + hstepB, voffB); PG8_STAGEA(PG8_SA(1, 0), a3, voffA);
;             PG8_WAIT_V(8); PG8_WAIT_L(0); PG8_BAR; PG8_MMA(1, 0, At, B0); PG8_MMA(1, 1, At, B1); PG8_BAR; PG8_SCHED;
;             t0 = 2; } }
;     ...
;         asm volatile(".p2align " PG8_STR(GEMM_LOOP_ALIGN) ::: "memory");
;     ...
;         for (int t = t0; t < nt; t += 2) {
;             const bool last = (t == nt - 2);
;             const char* a1 = cA + (size_t)(t + 1) * kstepA;
;             const char* a2 = last ? nA : cA + (size_t)(t + 2) * kstepA; const char* b2 = last ? nB : cB + (size_t)(t + 2) * kstepB;
;             const char* a3 = a2 + kstepA; const char* b3 = b2 + kstepB;
;             if (last && has_next) S.a_ready(nxt);
;             if constexpr (SP2) {
;             PG8_LDB(B0, 0, 0); PG8_LDB(B1, 0, 1); PG8_SCHED; PG8_LDA(At, 0, 0); PG8_STAGEA(PG8_SA(1, 1), a1 + hstepA, voffA);
;     ...
;             const int relax = __builtin_amdgcn_readfirstlane((t == 0 && ui > 0) ? 1 : 0);
.LBB0_557:
	s_ashr_i32 s21, s20, 31
	s_lshl_b64 s[6:7], s[20:21], 21
	s_add_u32 s24, s60, s6
	s_addc_u32 s25, s61, s7
	s_and_b64 s[6:7], s[26:27], exec
	s_cselect_b32 s21, s25, s1
	s_cselect_b32 s82, s24, s0
	s_ashr_i32 s23, s22, 31
	s_lshl_b64 s[6:7], s[22:23], 21
	s_add_u32 s36, s4, s6
	s_addc_u32 s37, s5, s7
	s_and_b64 s[6:7], s[26:27], exec
	s_cselect_b32 s23, s37, s41
	s_cselect_b32 s83, s36, s40
	s_add_u32 s38, s0, 0x100080
	s_addc_u32 s39, s1, 0
	s_add_u32 s0, s40, 0x100
	s_addc_u32 s1, s41, 0
	s_mov_b32 s90, -2
	s_waitcnt lgkmcnt(0)
	s_waitcnt vmcnt(0)
	s_add_u32 s6, s38, 0xfff00080
	s_addc_u32 s7, s39, -1
	s_add_i32 s91, 0, 0x10000
	s_cmp_eq_u32 s90, 60
	s_cselect_b32 s41, s21, s7
	s_cselect_b32 s40, s82, s6
	s_cselect_b32 s17, s23, s1
	s_cselect_b32 s16, s83, s0
	s_add_i32 s94, 0, 0x14000
	v_add_u32_e32 v152, s91, v157
	v_add_u32_e32 v174, s94, v157
	ds_read_b128 v[130:133], v152
	ds_read_b128 v[134:137], v152 offset:1024
	ds_read_b128 v[148:151], v152 offset:2048
	ds_read_b128 v[152:155], v152 offset:3072
	ds_read_b128 v[162:165], v174
	ds_read_b128 v[166:169], v174 offset:1024
	ds_read_b128 v[170:173], v174 offset:2048
	ds_read_b128 v[174:177], v174 offset:3072
	v_lshl_add_u64 v[210:211], s[38:39], 0, v[144:145]
	s_add_i32 m0, s13, 0xc000
	ds_read_b128 v[178:181], v161
	ds_read_b128 v[182:185], v161 offset:1024
	ds_read_b128 v[186:189], v161 offset:2048
	ds_read_b128 v[190:193], v161 offset:3072
	ds_read_b128 v[194:197], v161 offset:4096
	ds_read_b128 v[198:201], v161 offset:5120
	ds_read_b128 v[202:205], v161 offset:6144
	ds_read_b128 v[206:209], v161 offset:7168
	global_load_lds_dwordx4 v[210:211], off
	v_lshl_add_u64 v[210:211], s[38:39], 0, v[146:147]
	s_add_i32 m0, s13, 0xe000
	s_nop 0
	global_load_lds_dwordx4 v[210:211], off
	s_waitcnt vmcnt(8)
	s_waitcnt lgkmcnt(0)
	s_barrier
	v_mfma_f32_16x16x32_bf16 v[126:129], v[130:133], v[178:181], 0
	v_mfma_f32_16x16x32_bf16 v[122:125], v[148:151], v[178:181], 0
	v_mfma_f32_16x16x32_bf16 v[110:113], v[130:133], v[186:189], 0
	v_mfma_f32_16x16x32_bf16 v[106:109], v[148:151], v[186:189], 0
	v_mfma_f32_16x16x32_bf16 v[94:97], v[130:133], v[194:197], 0
	v_mfma_f32_16x16x32_bf16 v[90:93], v[148:151], v[194:197], 0
	v_mfma_f32_16x16x32_bf16 v[78:81], v[130:133], v[202:205], 0
	v_mfma_f32_16x16x32_bf16 v[74:77], v[148:151], v[202:205], 0
	v_mfma_f32_16x16x32_bf16 v[126:129], v[134:137], v[182:185], v[126:129]
	v_mfma_f32_16x16x32_bf16 v[122:125], v[152:155], v[182:185], v[122:125]
	v_mfma_f32_16x16x32_bf16 v[110:113], v[134:137], v[190:193], v[110:113]
	v_mfma_f32_16x16x32_bf16 v[106:109], v[152:155], v[190:193], v[106:109]
	v_mfma_f32_16x16x32_bf16 v[94:97], v[134:137], v[198:201], v[94:97]
	v_mfma_f32_16x16x32_bf16 v[90:93], v[152:155], v[198:201], v[90:93]
	v_mfma_f32_16x16x32_bf16 v[78:81], v[134:137], v[206:209], v[78:81]
	v_mfma_f32_16x16x32_bf16 v[74:77], v[152:155], v[206:209], v[74:77]
	v_mfma_f32_16x16x32_bf16 v[118:121], v[162:165], v[178:181], 0
	v_mfma_f32_16x16x32_bf16 v[114:117], v[170:173], v[178:181], 0
	v_mfma_f32_16x16x32_bf16 v[102:105], v[162:165], v[186:189], 0
	v_mfma_f32_16x16x32_bf16 v[98:101], v[170:173], v[186:189], 0
	v_mfma_f32_16x16x32_bf16 v[86:89], v[162:165], v[194:197], 0
	v_mfma_f32_16x16x32_bf16 v[82:85], v[170:173], v[194:197], 0
	v_mfma_f32_16x16x32_bf16 v[70:73], v[162:165], v[202:205], 0
	v_mfma_f32_16x16x32_bf16 v[66:69], v[170:173], v[202:205], 0
	v_mfma_f32_16x16x32_bf16 v[118:121], v[166:169], v[182:185], v[118:121]
	v_mfma_f32_16x16x32_bf16 v[114:117], v[174:177], v[182:185], v[114:117]
	v_mfma_f32_16x16x32_bf16 v[102:105], v[166:169], v[190:193], v[102:105]
	v_mfma_f32_16x16x32_bf16 v[98:101], v[174:177], v[190:193], v[98:101]
	v_mfma_f32_16x16x32_bf16 v[86:89], v[166:169], v[198:201], v[86:89]
	v_mfma_f32_16x16x32_bf16 v[82:85], v[174:177], v[198:201], v[82:85]
	v_mfma_f32_16x16x32_bf16 v[70:73], v[166:169], v[206:209], v[70:73]
	v_mfma_f32_16x16x32_bf16 v[66:69], v[174:177], v[206:209], v[66:69]
	s_barrier
	s_add_i32 s6, s91, s12
	v_lshl_add_u64 v[210:211], s[16:17], 0, v[16:17]
	s_mov_b32 m0, s6
	ds_read_b128 v[178:181], v161 offset:16384
	ds_read_b128 v[182:185], v161 offset:17408
	ds_read_b128 v[186:189], v161 offset:18432
	ds_read_b128 v[190:193], v161 offset:19456
	ds_read_b128 v[194:197], v161 offset:20480
	ds_read_b128 v[198:201], v161 offset:21504
	ds_read_b128 v[202:205], v161 offset:22528
	ds_read_b128 v[206:209], v161 offset:23552
	global_load_lds_dwordx4 v[210:211], off
	s_add_i32 m0, s6, 0x2000
	s_add_u32 s6, s16, 0x100000
	v_lshl_add_u64 v[212:213], s[16:17], 0, v[138:139]
	s_addc_u32 s7, s17, 0
	s_add_i32 s91, s94, s12
	global_load_lds_dwordx4 v[212:213], off
	v_lshl_add_u64 v[214:215], s[6:7], 0, v[16:17]
	s_mov_b32 m0, s91
	v_lshl_add_u64 v[216:217], s[40:41], 0, v[140:141]
	global_load_lds_dwordx4 v[214:215], off
	v_lshl_add_u64 v[214:215], s[6:7], 0, v[138:139]
	s_add_i32 m0, s91, 0x2000
	s_nop 0
	global_load_lds_dwordx4 v[214:215], off
	v_lshl_add_u64 v[214:215], s[40:41], 0, v[142:143]
	s_mov_b32 m0, s13
	s_nop 0
	global_load_lds_dwordx4 v[214:215], off
	s_mov_b32 m0, s42
	s_nop 0
	global_load_lds_dwordx4 v[216:217], off
	s_waitcnt vmcnt(8)
	s_waitcnt lgkmcnt(0)
	s_barrier
; #define PG8_STAGEA(bufoff, gbase, voff) PG8_STAGE_X(bufoff, gbase, voff, AUXA)
; #define PG8_STAGEB(bufoff, gbase, voff) PG8_STAGE_X(bufoff, gbase, voff, AUXB)
; #define PG8_LDA(dst, b, h) do { _Pragma("unroll") for (int m = 0; m < 4; ++m) _Pragma("unroll") for (int k = 0; k < 2; ++k) dst[m][k] = *(const PG8_LAS bf16x8*)(lds + PG8_SA(b, h) + aoff + m * 2048 + k * 1024); } while (0)
; #define PG8_LDB(dst, b, h) do { _Pragma("unroll") for (int n = 0; n < 2; ++n) _Pragma("unroll") for (int k = 0; k < 2; ++k) dst[n][k] = *(const PG8_LAS bf16x8*)(lds + PG8_SB(b, h) + boff + n * 2048 + k * 1024); } while (0)
; #define PG8_MMA(ai, bj, At, Bt) do { if (GEMM_PRIO_MODE == 0) __builtin_amdgcn_s_setprio(1); PG8_MMA_LOOPS \
;         acc[ai][bj][m][n] = __builtin_amdgcn_mfma_f32_16x16x32_bf16(Bt[n][k], At[m][k], acc[ai][bj][m][n], 0, 0, 0); if (GEMM_PRIO_MODE == 0) __builtin_amdgcn_s_setprio(0); } while (0)
; #define PG8_WAIT_V(n) asm volatile("s_waitcnt vmcnt(" #n ")" ::: "memory")
;     ...
;             PG8_LDB(B0, 0, 0); PG8_LDB(B1, 0, 1); PG8_SCHED; PG8_LDA(At, 0, 0); PG8_STAGEA(PG8_SA(1, 1), a1 + hstepA, voffA);
;     ...
;             const int relax = __builtin_amdgcn_readfirstlane((t == 0 && ui > 0) ? 1 : 0);
;             PG8_WAIT_VR(8, 24, relax); PG8_WAIT_L(0); PG8_BAR; PG8_MMA(0, 0, At, B0); PG8_MMA(0, 1, At, B1); PG8_BAR; PG8_SCHED;
;     ...
;             PG8_WAIT_V(8); PG8_WAIT_L(0); PG8_BAR; PG8_MMA(0, 0, At, B0); PG8_MMA(0, 1, At, B1); PG8_BAR; PG8_SCHED;
;     ...
;             PG8_LDA(At, 0, 1); PG8_STAGEB(PG8_SB(0, 0), b2, voffB); PG8_STAGEB(PG8_SB(0, 1), b2 + hstepB, voffB); PG8_STAGEA(PG8_SA(0, 0), a2, voffA);
;     ...
;             PG8_WAIT_VR(8, 24, relax); PG8_WAIT_L(0); PG8_BAR; PG8_MMA(1, 0, At, B0); PG8_MMA(1, 1, At, B1); PG8_BAR; PG8_SCHED;
;     ...
;             PG8_WAIT_V(8); PG8_WAIT_L(0); PG8_BAR; PG8_MMA(1, 0, At, B0); PG8_MMA(1, 1, At, B1); PG8_BAR; PG8_SCHED;
;     ...
;             PG8_LDB(B0, 1, 0); PG8_LDB(B1, 1, 1); PG8_SCHED; PG8_LDA(At, 1, 0); PG8_STAGEA(PG8_SA(0, 1), a2 + hstepA, voffA);
;             PG8_WAIT_V(8); PG8_WAIT_L(0); PG8_BAR; PG8_MMA(0, 0, At, B0); PG8_MMA(0, 1, At, B1); PG8_BAR; PG8_SCHED;
;             PG8_LDA(At, 1, 1); PG8_STAGEB(PG8_SB(1, 0), b3, voffB); PG8_STAGEB(PG8_SB(1, 1), b3 + hstepB, voffB); PG8_STAGEA(PG8_SA(1, 0), a3, voffA);
;             PG8_WAIT_V(8); PG8_WAIT_L(0); PG8_BAR; PG8_MMA(1, 0, At, B0); PG8_MMA(1, 1, At, B1); PG8_BAR; PG8_SCHED;
	v_mfma_f32_16x16x32_bf16 v[62:65], v[130:133], v[178:181], 0
	v_mfma_f32_16x16x32_bf16 v[58:61], v[148:151], v[178:181], 0
	v_mfma_f32_16x16x32_bf16 v[46:49], v[130:133], v[186:189], 0
	v_mfma_f32_16x16x32_bf16 v[42:45], v[148:151], v[186:189], 0
	v_mfma_f32_16x16x32_bf16 v[30:33], v[130:133], v[194:197], 0
	v_mfma_f32_16x16x32_bf16 v[26:29], v[148:151], v[194:197], 0
	v_mfma_f32_16x16x32_bf16 v[12:15], v[130:133], v[202:205], 0
	v_mfma_f32_16x16x32_bf16 v[8:11], v[148:151], v[202:205], 0
	v_mfma_f32_16x16x32_bf16 v[62:65], v[134:137], v[182:185], v[62:65]
	v_mfma_f32_16x16x32_bf16 v[58:61], v[152:155], v[182:185], v[58:61]
	v_mfma_f32_16x16x32_bf16 v[46:49], v[134:137], v[190:193], v[46:49]
	v_mfma_f32_16x16x32_bf16 v[42:45], v[152:155], v[190:193], v[42:45]
	v_mfma_f32_16x16x32_bf16 v[30:33], v[134:137], v[198:201], v[30:33]
	v_mfma_f32_16x16x32_bf16 v[26:29], v[152:155], v[198:201], v[26:29]
	v_mfma_f32_16x16x32_bf16 v[12:15], v[134:137], v[206:209], v[12:15]
	v_mfma_f32_16x16x32_bf16 v[8:11], v[152:155], v[206:209], v[8:11]
	v_mfma_f32_16x16x32_bf16 v[54:57], v[162:165], v[178:181], 0
	v_mfma_f32_16x16x32_bf16 v[50:53], v[170:173], v[178:181], 0
	v_mfma_f32_16x16x32_bf16 v[38:41], v[162:165], v[186:189], 0
	v_mfma_f32_16x16x32_bf16 v[34:37], v[170:173], v[186:189], 0
	v_mfma_f32_16x16x32_bf16 v[22:25], v[162:165], v[194:197], 0
	v_mfma_f32_16x16x32_bf16 v[18:21], v[170:173], v[194:197], 0
	v_mfma_f32_16x16x32_bf16 v[4:7], v[162:165], v[202:205], 0
	v_mfma_f32_16x16x32_bf16 v[0:3], v[170:173], v[202:205], 0
	v_mfma_f32_16x16x32_bf16 v[54:57], v[166:169], v[182:185], v[54:57]
	v_mfma_f32_16x16x32_bf16 v[50:53], v[174:177], v[182:185], v[50:53]
	v_mfma_f32_16x16x32_bf16 v[38:41], v[166:169], v[190:193], v[38:41]
	v_mfma_f32_16x16x32_bf16 v[34:37], v[174:177], v[190:193], v[34:37]
	v_mfma_f32_16x16x32_bf16 v[22:25], v[166:169], v[198:201], v[22:25]
	v_mfma_f32_16x16x32_bf16 v[18:21], v[174:177], v[198:201], v[18:21]
	v_mfma_f32_16x16x32_bf16 v[4:7], v[166:169], v[206:209], v[4:7]
	v_mfma_f32_16x16x32_bf16 v[0:3], v[174:177], v[206:209], v[0:3]
	s_barrier
	s_add_i32 s91, 0, 0x18000
	s_add_i32 s94, 0, 0x1c000
	v_add_u32_e32 v152, s91, v157
	v_add_u32_e32 v174, s94, v157
	ds_read_b128 v[130:133], v152
	ds_read_b128 v[134:137], v152 offset:1024
	ds_read_b128 v[148:151], v152 offset:2048
	ds_read_b128 v[152:155], v152 offset:3072
	ds_read_b128 v[162:165], v174
	ds_read_b128 v[166:169], v174 offset:1024
	ds_read_b128 v[170:173], v174 offset:2048
	ds_read_b128 v[174:177], v174 offset:3072
	s_add_u32 s6, s40, 0x100000
	s_addc_u32 s7, s41, 0
	s_mov_b32 m0, s43
	v_lshl_add_u64 v[218:219], s[6:7], 0, v[142:143]
	ds_read_b128 v[178:181], v161 offset:32768
	ds_read_b128 v[182:185], v161 offset:33792
	ds_read_b128 v[186:189], v161 offset:34816
	ds_read_b128 v[190:193], v161 offset:35840
	ds_read_b128 v[194:197], v161 offset:36864
	ds_read_b128 v[198:201], v161 offset:37888
	ds_read_b128 v[202:205], v161 offset:38912
	ds_read_b128 v[206:209], v161 offset:39936
	global_load_lds_dwordx4 v[218:219], off
	v_lshl_add_u64 v[218:219], s[6:7], 0, v[140:141]
	s_mov_b32 m0, s50
	s_nop 0
	global_load_lds_dwordx4 v[218:219], off
	s_waitcnt vmcnt(8)
	s_waitcnt lgkmcnt(0)
	s_nop 0
	s_nop 0
	s_barrier
	v_mfma_f32_16x16x32_bf16 v[126:129], v[130:133], v[178:181], v[126:129]
	v_mfma_f32_16x16x32_bf16 v[122:125], v[148:151], v[178:181], v[122:125]
	v_mfma_f32_16x16x32_bf16 v[110:113], v[130:133], v[186:189], v[110:113]
	v_mfma_f32_16x16x32_bf16 v[106:109], v[148:151], v[186:189], v[106:109]
	v_mfma_f32_16x16x32_bf16 v[94:97], v[130:133], v[194:197], v[94:97]
	v_mfma_f32_16x16x32_bf16 v[90:93], v[148:151], v[194:197], v[90:93]
	v_mfma_f32_16x16x32_bf16 v[78:81], v[130:133], v[202:205], v[78:81]
	v_mfma_f32_16x16x32_bf16 v[74:77], v[148:151], v[202:205], v[74:77]
	v_mfma_f32_16x16x32_bf16 v[126:129], v[134:137], v[182:185], v[126:129]
	v_mfma_f32_16x16x32_bf16 v[122:125], v[152:155], v[182:185], v[122:125]
	v_mfma_f32_16x16x32_bf16 v[110:113], v[134:137], v[190:193], v[110:113]
	v_mfma_f32_16x16x32_bf16 v[106:109], v[152:155], v[190:193], v[106:109]
	v_mfma_f32_16x16x32_bf16 v[94:97], v[134:137], v[198:201], v[94:97]
	v_mfma_f32_16x16x32_bf16 v[90:93], v[152:155], v[198:201], v[90:93]
	v_mfma_f32_16x16x32_bf16 v[78:81], v[134:137], v[206:209], v[78:81]
	v_mfma_f32_16x16x32_bf16 v[74:77], v[152:155], v[206:209], v[74:77]
	v_mfma_f32_16x16x32_bf16 v[118:121], v[162:165], v[178:181], v[118:121]
	v_mfma_f32_16x16x32_bf16 v[114:117], v[170:173], v[178:181], v[114:117]
	v_mfma_f32_16x16x32_bf16 v[102:105], v[162:165], v[186:189], v[102:105]
	v_mfma_f32_16x16x32_bf16 v[98:101], v[170:173], v[186:189], v[98:101]
	v_mfma_f32_16x16x32_bf16 v[86:89], v[162:165], v[194:197], v[86:89]
	v_mfma_f32_16x16x32_bf16 v[82:85], v[170:173], v[194:197], v[82:85]
	v_mfma_f32_16x16x32_bf16 v[70:73], v[162:165], v[202:205], v[70:73]
	v_mfma_f32_16x16x32_bf16 v[66:69], v[170:173], v[202:205], v[66:69]
	v_mfma_f32_16x16x32_bf16 v[118:121], v[166:169], v[182:185], v[118:121]
	v_mfma_f32_16x16x32_bf16 v[114:117], v[174:177], v[182:185], v[114:117]
	v_mfma_f32_16x16x32_bf16 v[102:105], v[166:169], v[190:193], v[102:105]
	v_mfma_f32_16x16x32_bf16 v[98:101], v[174:177], v[190:193], v[98:101]
	v_mfma_f32_16x16x32_bf16 v[86:89], v[166:169], v[198:201], v[86:89]
	v_mfma_f32_16x16x32_bf16 v[82:85], v[174:177], v[198:201], v[82:85]
	v_mfma_f32_16x16x32_bf16 v[70:73], v[166:169], v[206:209], v[70:73]
	v_mfma_f32_16x16x32_bf16 v[66:69], v[174:177], v[206:209], v[66:69]
	s_barrier
; #define PG8_STAGEA(bufoff, gbase, voff) PG8_STAGE_X(bufoff, gbase, voff, AUXA)
; #define PG8_STAGEB(bufoff, gbase, voff) PG8_STAGE_X(bufoff, gbase, voff, AUXB)
; #define PG8_LDA(dst, b, h) do { _Pragma("unroll") for (int m = 0; m < 4; ++m) _Pragma("unroll") for (int k = 0; k < 2; ++k) dst[m][k] = *(const PG8_LAS bf16x8*)(lds + PG8_SA(b, h) + aoff + m * 2048 + k * 1024); } while (0)
; #define PG8_WAIT_V(n) asm volatile("s_waitcnt vmcnt(" #n ")" ::: "memory")
; #define PG8_WAIT_L(n) asm volatile("s_waitcnt lgkmcnt(" #n ")" ::: "memory")
;     ...
;         for (int t = t0; t < nt; t += 2) {
;             const bool last = (t == nt - 2);
;             const char* a1 = cA + (size_t)(t + 1) * kstepA;
;             const char* a2 = last ? nA : cA + (size_t)(t + 2) * kstepA; const char* b2 = last ? nB : cB + (size_t)(t + 2) * kstepB;
;             const char* a3 = a2 + kstepA; const char* b3 = b2 + kstepB;
;             if (last && has_next) S.a_ready(nxt);
;             if constexpr (SP2) {
;             PG8_LDB(B0, 0, 0); PG8_LDB(B1, 0, 1); PG8_SCHED; PG8_LDA(At, 0, 0); PG8_STAGEA(PG8_SA(1, 1), a1 + hstepA, voffA);
;     ...
;             const int relax = __builtin_amdgcn_readfirstlane((t == 0 && ui > 0) ? 1 : 0);
;             PG8_WAIT_VR(8, 24, relax); PG8_WAIT_L(0); PG8_BAR; PG8_MMA(0, 0, At, B0); PG8_MMA(0, 1, At, B1); PG8_BAR; PG8_SCHED;
;     ...
;             PG8_WAIT_V(8); PG8_WAIT_L(0); PG8_BAR; PG8_MMA(0, 0, At, B0); PG8_MMA(0, 1, At, B1); PG8_BAR; PG8_SCHED;
;     ...
;             PG8_LDA(At, 0, 1); PG8_STAGEB(PG8_SB(0, 0), b2, voffB); PG8_STAGEB(PG8_SB(0, 1), b2 + hstepB, voffB); PG8_STAGEA(PG8_SA(0, 0), a2, voffA);
;     ...
;             PG8_WAIT_VR(8, 24, relax); PG8_WAIT_L(0); PG8_BAR; PG8_MMA(1, 0, At, B0); PG8_MMA(1, 1, At, B1); PG8_BAR; PG8_SCHED;
;     ...
;             PG8_WAIT_V(8); PG8_WAIT_L(0); PG8_BAR; PG8_MMA(1, 0, At, B0); PG8_MMA(1, 1, At, B1); PG8_BAR; PG8_SCHED;
;     ...
;             PG8_LDB(B0, 1, 0); PG8_LDB(B1, 1, 1); PG8_SCHED; PG8_LDA(At, 1, 0); PG8_STAGEA(PG8_SA(0, 1), a2 + hstepA, voffA);
;             PG8_WAIT_V(8); PG8_WAIT_L(0); PG8_BAR; PG8_MMA(0, 0, At, B0); PG8_MMA(0, 1, At, B1); PG8_BAR; PG8_SCHED;
;             PG8_LDA(At, 1, 1); PG8_STAGEB(PG8_SB(1, 0), b3, voffB); PG8_STAGEB(PG8_SB(1, 1), b3 + hstepB, voffB); PG8_STAGEA(PG8_SA(1, 0), a3, voffA);
;             PG8_WAIT_V(8); PG8_WAIT_L(0); PG8_BAR; PG8_MMA(1, 0, At, B0); PG8_MMA(1, 1, At, B1); PG8_BAR; PG8_SCHED;
	s_add_i32 s6, s91, s12
	v_lshl_add_u64 v[210:211], v[210:211], 0, s[86:87]
	s_mov_b32 m0, s6
	ds_read_b128 v[178:181], v161 offset:49152
	ds_read_b128 v[182:185], v161 offset:50176
	ds_read_b128 v[186:189], v161 offset:51200
	ds_read_b128 v[190:193], v161 offset:52224
	ds_read_b128 v[194:197], v161 offset:53248
	ds_read_b128 v[198:201], v161 offset:54272
	ds_read_b128 v[202:205], v161 offset:55296
	ds_read_b128 v[206:209], v161 offset:56320
	global_load_lds_dwordx4 v[210:211], off
	s_add_i32 m0, s6, 0x2000
	s_add_u32 s6, s16, 0x100080
	v_lshl_add_u64 v[210:211], v[212:213], 0, s[86:87]
	s_addc_u32 s7, s17, 0
	s_add_i32 s16, s94, s12
	global_load_lds_dwordx4 v[210:211], off
	v_lshl_add_u64 v[210:211], s[6:7], 0, v[16:17]
	s_mov_b32 m0, s16
	s_nop 0
	global_load_lds_dwordx4 v[210:211], off
	v_lshl_add_u64 v[210:211], s[6:7], 0, v[138:139]
	s_add_i32 m0, s16, 0x2000
	s_nop 0
	global_load_lds_dwordx4 v[210:211], off
	v_lshl_add_u64 v[210:211], v[214:215], 0, s[86:87]
	s_mov_b32 m0, s68
	s_nop 0
	global_load_lds_dwordx4 v[210:211], off
	v_lshl_add_u64 v[210:211], v[216:217], 0, s[86:87]
	s_mov_b32 m0, s69
	s_nop 0
	global_load_lds_dwordx4 v[210:211], off
	s_waitcnt vmcnt(8)
	s_waitcnt lgkmcnt(0)
	s_nop 0
	s_nop 0
	s_nop 0
	s_barrier
	v_mfma_f32_16x16x32_bf16 v[62:65], v[130:133], v[178:181], v[62:65]
	v_mfma_f32_16x16x32_bf16 v[58:61], v[148:151], v[178:181], v[58:61]
	v_mfma_f32_16x16x32_bf16 v[46:49], v[130:133], v[186:189], v[46:49]
	v_mfma_f32_16x16x32_bf16 v[42:45], v[148:151], v[186:189], v[42:45]
	v_mfma_f32_16x16x32_bf16 v[30:33], v[130:133], v[194:197], v[30:33]
	v_mfma_f32_16x16x32_bf16 v[26:29], v[148:151], v[194:197], v[26:29]
	v_mfma_f32_16x16x32_bf16 v[12:15], v[130:133], v[202:205], v[12:15]
	v_mfma_f32_16x16x32_bf16 v[8:11], v[148:151], v[202:205], v[8:11]
	v_mfma_f32_16x16x32_bf16 v[62:65], v[134:137], v[182:185], v[62:65]
	v_mfma_f32_16x16x32_bf16 v[58:61], v[152:155], v[182:185], v[58:61]
	v_mfma_f32_16x16x32_bf16 v[46:49], v[134:137], v[190:193], v[46:49]
	v_mfma_f32_16x16x32_bf16 v[42:45], v[152:155], v[190:193], v[42:45]
	v_mfma_f32_16x16x32_bf16 v[30:33], v[134:137], v[198:201], v[30:33]
	v_mfma_f32_16x16x32_bf16 v[26:29], v[152:155], v[198:201], v[26:29]
	v_mfma_f32_16x16x32_bf16 v[12:15], v[134:137], v[206:209], v[12:15]
	v_mfma_f32_16x16x32_bf16 v[8:11], v[152:155], v[206:209], v[8:11]
	v_mfma_f32_16x16x32_bf16 v[54:57], v[162:165], v[178:181], v[54:57]
	v_mfma_f32_16x16x32_bf16 v[50:53], v[170:173], v[178:181], v[50:53]
	v_mfma_f32_16x16x32_bf16 v[38:41], v[162:165], v[186:189], v[38:41]
	v_mfma_f32_16x16x32_bf16 v[34:37], v[170:173], v[186:189], v[34:37]
	v_mfma_f32_16x16x32_bf16 v[22:25], v[162:165], v[194:197], v[22:25]
	v_mfma_f32_16x16x32_bf16 v[18:21], v[170:173], v[194:197], v[18:21]
	v_mfma_f32_16x16x32_bf16 v[4:7], v[162:165], v[202:205], v[4:7]
	v_mfma_f32_16x16x32_bf16 v[0:3], v[170:173], v[202:205], v[0:3]
	v_mfma_f32_16x16x32_bf16 v[54:57], v[166:169], v[182:185], v[54:57]
	v_mfma_f32_16x16x32_bf16 v[50:53], v[174:177], v[182:185], v[50:53]
	v_mfma_f32_16x16x32_bf16 v[38:41], v[166:169], v[190:193], v[38:41]
	v_mfma_f32_16x16x32_bf16 v[34:37], v[174:177], v[190:193], v[34:37]
	v_mfma_f32_16x16x32_bf16 v[22:25], v[166:169], v[198:201], v[22:25]
	v_mfma_f32_16x16x32_bf16 v[18:21], v[174:177], v[198:201], v[18:21]
	v_mfma_f32_16x16x32_bf16 v[4:7], v[166:169], v[206:209], v[4:7]
	v_mfma_f32_16x16x32_bf16 v[0:3], v[174:177], v[206:209], v[0:3]
	s_barrier
	s_add_i32 s90, s90, 2
	s_add_u32 s38, s38, 0x100
	s_addc_u32 s39, s39, 0
	s_add_u32 s0, s0, 0x100
	s_addc_u32 s1, s1, 0
	v_add_u32_e32 v220, 0x10000, v157
.LBB0_558:
	s_add_u32 s6, s38, 0xfff00080
	s_addc_u32 s7, s39, -1
	s_add_i32 s91, 0, 0x10000
	s_cmp_eq_u32 s90, 60
	s_cselect_b32 s41, s21, s7
	s_cselect_b32 s40, s82, s6
	s_cselect_b32 s17, s23, s1
	s_cselect_b32 s16, s83, s0
	s_add_i32 s94, 0, 0x14000
	ds_read_b128 v[130:133], v220
	ds_read_b128 v[134:137], v220 offset:1024
	ds_read_b128 v[148:151], v220 offset:2048
	ds_read_b128 v[152:155], v220 offset:3072
	ds_read_b128 v[162:165], v220 offset:16384
	ds_read_b128 v[166:169], v220 offset:17408
	ds_read_b128 v[170:173], v220 offset:18432
	ds_read_b128 v[174:177], v220 offset:19456
	s_add_i32 m0, s13, 0xc000
	ds_read_b128 v[178:181], v161
	ds_read_b128 v[182:185], v161 offset:1024
	ds_read_b128 v[186:189], v161 offset:2048
	ds_read_b128 v[190:193], v161 offset:3072
	ds_read_b128 v[194:197], v161 offset:4096
	ds_read_b128 v[198:201], v161 offset:5120
	ds_read_b128 v[202:205], v161 offset:6144
	global_load_lds_dwordx4 v144, s[38:39]
	s_add_i32 m0, s13, 0xe000
	ds_read_b128 v[206:209], v161 offset:7168
	global_load_lds_dwordx4 v146, s[38:39]
	s_waitcnt vmcnt(8)
	s_waitcnt lgkmcnt(0)
	s_nop 0
	s_barrier
; #define PG8_STAGEA(bufoff, gbase, voff) PG8_STAGE_X(bufoff, gbase, voff, AUXA)
; #define PG8_STAGEB(bufoff, gbase, voff) PG8_STAGE_X(bufoff, gbase, voff, AUXB)
; #define PG8_LDA(dst, b, h) do { _Pragma("unroll") for (int m = 0; m < 4; ++m) _Pragma("unroll") for (int k = 0; k < 2; ++k) dst[m][k] = *(const PG8_LAS bf16x8*)(lds + PG8_SA(b, h) + aoff + m * 2048 + k * 1024); } while (0)
; #define PG8_LDB(dst, b, h) do { _Pragma("unroll") for (int n = 0; n < 2; ++n) _Pragma("unroll") for (int k = 0; k < 2; ++k) dst[n][k] = *(const PG8_LAS bf16x8*)(lds + PG8_SB(b, h) + boff + n * 2048 + k * 1024); } while (0)
; #define PG8_MMA(ai, bj, At, Bt) do { if (GEMM_PRIO_MODE == 0) __builtin_amdgcn_s_setprio(1); PG8_MMA_LOOPS \
;         acc[ai][bj][m][n] = __builtin_amdgcn_mfma_f32_16x16x32_bf16(Bt[n][k], At[m][k], acc[ai][bj][m][n], 0, 0, 0); if (GEMM_PRIO_MODE == 0) __builtin_amdgcn_s_setprio(0); } while (0)
; #define PG8_WAIT_V(n) asm volatile("s_waitcnt vmcnt(" #n ")" ::: "memory")
; #define PG8_WAIT_VR(n, nr, flag) asm volatile("s_cmp_eq_u32 %0, 0\n\ts_cbranch_scc1 .Lpg8s%=\n\ts_waitcnt vmcnt(" #nr ")\n\ts_branch .Lpg8d%=\n.Lpg8s%=:\n\ts_waitcnt vmcnt(" #n ")\n.Lpg8d%=:" :: "s"(flag) : "memory", "scc")
; #define PG8_WAIT_L(n) asm volatile("s_waitcnt lgkmcnt(" #n ")" ::: "memory")
; #define PG8_BAR __builtin_amdgcn_s_barrier()
; #define PG8_SCHED __builtin_amdgcn_sched_barrier(0)
;     ...
;             PG8_LDB(B0, 0, 0); PG8_LDB(B1, 0, 1); PG8_SCHED; PG8_LDA(At, 0, 0); PG8_STAGEA(PG8_SA(1, 1), a1 + hstepA, voffA);
;     ...
;             const int relax = __builtin_amdgcn_readfirstlane((t == 0 && ui > 0) ? 1 : 0);
;             PG8_WAIT_VR(8, 24, relax); PG8_WAIT_L(0); PG8_BAR; PG8_MMA(0, 0, At, B0); PG8_MMA(0, 1, At, B1); PG8_BAR; PG8_SCHED;
;     ...
;             PG8_WAIT_V(8); PG8_WAIT_L(0); PG8_BAR; PG8_MMA(0, 0, At, B0); PG8_MMA(0, 1, At, B1); PG8_BAR; PG8_SCHED;
;     ...
;             PG8_LDA(At, 0, 1); PG8_STAGEB(PG8_SB(0, 0), b2, voffB); PG8_STAGEB(PG8_SB(0, 1), b2 + hstepB, voffB); PG8_STAGEA(PG8_SA(0, 0), a2, voffA);
;     ...
;             PG8_WAIT_VR(8, 24, relax); PG8_WAIT_L(0); PG8_BAR; PG8_MMA(1, 0, At, B0); PG8_MMA(1, 1, At, B1); PG8_BAR; PG8_SCHED;
;     ...
;             PG8_WAIT_V(8); PG8_WAIT_L(0); PG8_BAR; PG8_MMA(1, 0, At, B0); PG8_MMA(1, 1, At, B1); PG8_BAR; PG8_SCHED;
	v_mfma_f32_16x16x32_bf16 v[126:129], v[130:133], v[178:181], v[126:129]
	v_mfma_f32_16x16x32_bf16 v[122:125], v[148:151], v[178:181], v[122:125]
	v_mfma_f32_16x16x32_bf16 v[110:113], v[130:133], v[186:189], v[110:113]
	v_mfma_f32_16x16x32_bf16 v[106:109], v[148:151], v[186:189], v[106:109]
	v_mfma_f32_16x16x32_bf16 v[94:97], v[130:133], v[194:197], v[94:97]
	v_mfma_f32_16x16x32_bf16 v[90:93], v[148:151], v[194:197], v[90:93]
	v_mfma_f32_16x16x32_bf16 v[78:81], v[130:133], v[202:205], v[78:81]
	v_mfma_f32_16x16x32_bf16 v[74:77], v[148:151], v[202:205], v[74:77]
	v_mfma_f32_16x16x32_bf16 v[126:129], v[134:137], v[182:185], v[126:129]
	v_mfma_f32_16x16x32_bf16 v[122:125], v[152:155], v[182:185], v[122:125]
	v_mfma_f32_16x16x32_bf16 v[110:113], v[134:137], v[190:193], v[110:113]
	v_mfma_f32_16x16x32_bf16 v[106:109], v[152:155], v[190:193], v[106:109]
	v_mfma_f32_16x16x32_bf16 v[94:97], v[134:137], v[198:201], v[94:97]
	v_mfma_f32_16x16x32_bf16 v[90:93], v[152:155], v[198:201], v[90:93]
	v_mfma_f32_16x16x32_bf16 v[78:81], v[134:137], v[206:209], v[78:81]
	v_mfma_f32_16x16x32_bf16 v[74:77], v[152:155], v[206:209], v[74:77]
	v_mfma_f32_16x16x32_bf16 v[118:121], v[162:165], v[178:181], v[118:121]
	v_mfma_f32_16x16x32_bf16 v[114:117], v[170:173], v[178:181], v[114:117]
	v_mfma_f32_16x16x32_bf16 v[102:105], v[162:165], v[186:189], v[102:105]
	v_mfma_f32_16x16x32_bf16 v[98:101], v[170:173], v[186:189], v[98:101]
	v_mfma_f32_16x16x32_bf16 v[86:89], v[162:165], v[194:197], v[86:89]
	v_mfma_f32_16x16x32_bf16 v[82:85], v[170:173], v[194:197], v[82:85]
	v_mfma_f32_16x16x32_bf16 v[70:73], v[162:165], v[202:205], v[70:73]
	v_mfma_f32_16x16x32_bf16 v[66:69], v[170:173], v[202:205], v[66:69]
	v_mfma_f32_16x16x32_bf16 v[118:121], v[166:169], v[182:185], v[118:121]
	v_mfma_f32_16x16x32_bf16 v[114:117], v[174:177], v[182:185], v[114:117]
	v_mfma_f32_16x16x32_bf16 v[102:105], v[166:169], v[190:193], v[102:105]
	v_mfma_f32_16x16x32_bf16 v[98:101], v[174:177], v[190:193], v[98:101]
	v_mfma_f32_16x16x32_bf16 v[86:89], v[166:169], v[198:201], v[86:89]
	v_mfma_f32_16x16x32_bf16 v[82:85], v[174:177], v[198:201], v[82:85]
	v_mfma_f32_16x16x32_bf16 v[70:73], v[166:169], v[206:209], v[70:73]
	v_mfma_f32_16x16x32_bf16 v[66:69], v[174:177], v[206:209], v[66:69]
	s_barrier
	s_add_i32 s6, s91, s12
	s_mov_b32 m0, s6
	ds_read_b128 v[178:181], v161 offset:16384
	ds_read_b128 v[182:185], v161 offset:17408
	ds_read_b128 v[186:189], v161 offset:18432
	ds_read_b128 v[190:193], v161 offset:19456
	global_load_lds_dwordx4 v16, s[16:17]
	s_add_i32 m0, s6, 0x2000
	s_add_u32 s6, s16, 0x100000
	s_addc_u32 s7, s17, 0
	s_add_i32 s91, s94, s12
	global_load_lds_dwordx4 v138, s[16:17]
	s_mov_b32 m0, s91
	ds_read_b128 v[206:209], v161 offset:23552
	global_load_lds_dwordx4 v16, s[6:7]
	s_add_i32 m0, s91, 0x2000
	ds_read_b128 v[202:205], v161 offset:22528
	global_load_lds_dwordx4 v138, s[6:7]
	s_mov_b32 m0, s13
	ds_read_b128 v[198:201], v161 offset:21504
	global_load_lds_dwordx4 v142, s[40:41]
	s_mov_b32 m0, s42
	ds_read_b128 v[194:197], v161 offset:20480
	global_load_lds_dwordx4 v140, s[40:41]
	s_waitcnt vmcnt(8)
	s_waitcnt lgkmcnt(0)
	s_nop 0
	s_barrier
	v_mfma_f32_16x16x32_bf16 v[62:65], v[130:133], v[178:181], v[62:65]
	v_mfma_f32_16x16x32_bf16 v[58:61], v[148:151], v[178:181], v[58:61]
	v_mfma_f32_16x16x32_bf16 v[46:49], v[130:133], v[186:189], v[46:49]
	v_mfma_f32_16x16x32_bf16 v[42:45], v[148:151], v[186:189], v[42:45]
	v_mfma_f32_16x16x32_bf16 v[30:33], v[130:133], v[194:197], v[30:33]
	v_mfma_f32_16x16x32_bf16 v[26:29], v[148:151], v[194:197], v[26:29]
	v_mfma_f32_16x16x32_bf16 v[12:15], v[130:133], v[202:205], v[12:15]
	v_mfma_f32_16x16x32_bf16 v[8:11], v[148:151], v[202:205], v[8:11]
	v_mfma_f32_16x16x32_bf16 v[62:65], v[134:137], v[182:185], v[62:65]
	v_mfma_f32_16x16x32_bf16 v[58:61], v[152:155], v[182:185], v[58:61]
	v_mfma_f32_16x16x32_bf16 v[46:49], v[134:137], v[190:193], v[46:49]
	v_mfma_f32_16x16x32_bf16 v[42:45], v[152:155], v[190:193], v[42:45]
	v_mfma_f32_16x16x32_bf16 v[30:33], v[134:137], v[198:201], v[30:33]
	v_mfma_f32_16x16x32_bf16 v[26:29], v[152:155], v[198:201], v[26:29]
	v_mfma_f32_16x16x32_bf16 v[12:15], v[134:137], v[206:209], v[12:15]
	v_mfma_f32_16x16x32_bf16 v[8:11], v[152:155], v[206:209], v[8:11]
	v_mfma_f32_16x16x32_bf16 v[54:57], v[162:165], v[178:181], v[54:57]
	v_mfma_f32_16x16x32_bf16 v[50:53], v[170:173], v[178:181], v[50:53]
	v_mfma_f32_16x16x32_bf16 v[38:41], v[162:165], v[186:189], v[38:41]
	v_mfma_f32_16x16x32_bf16 v[34:37], v[170:173], v[186:189], v[34:37]
	v_mfma_f32_16x16x32_bf16 v[22:25], v[162:165], v[194:197], v[22:25]
	v_mfma_f32_16x16x32_bf16 v[18:21], v[170:173], v[194:197], v[18:21]
	v_mfma_f32_16x16x32_bf16 v[4:7], v[162:165], v[202:205], v[4:7]
	v_mfma_f32_16x16x32_bf16 v[0:3], v[170:173], v[202:205], v[0:3]
	v_mfma_f32_16x16x32_bf16 v[54:57], v[166:169], v[182:185], v[54:57]
	v_mfma_f32_16x16x32_bf16 v[50:53], v[174:177], v[182:185], v[50:53]
	v_mfma_f32_16x16x32_bf16 v[38:41], v[166:169], v[190:193], v[38:41]
	v_mfma_f32_16x16x32_bf16 v[34:37], v[174:177], v[190:193], v[34:37]
	v_mfma_f32_16x16x32_bf16 v[22:25], v[166:169], v[198:201], v[22:25]
	v_mfma_f32_16x16x32_bf16 v[18:21], v[174:177], v[198:201], v[18:21]
	v_mfma_f32_16x16x32_bf16 v[4:7], v[166:169], v[206:209], v[4:7]
	v_mfma_f32_16x16x32_bf16 v[0:3], v[174:177], v[206:209], v[0:3]
	s_barrier
; #define PG8_STAGEA(bufoff, gbase, voff) PG8_STAGE_X(bufoff, gbase, voff, AUXA)
; #define PG8_STAGEB(bufoff, gbase, voff) PG8_STAGE_X(bufoff, gbase, voff, AUXB)
; #define PG8_LDA(dst, b, h) do { _Pragma("unroll") for (int m = 0; m < 4; ++m) _Pragma("unroll") for (int k = 0; k < 2; ++k) dst[m][k] = *(const PG8_LAS bf16x8*)(lds + PG8_SA(b, h) + aoff + m * 2048 + k * 1024); } while (0)
; #define PG8_LDB(dst, b, h) do { _Pragma("unroll") for (int n = 0; n < 2; ++n) _Pragma("unroll") for (int k = 0; k < 2; ++k) dst[n][k] = *(const PG8_LAS bf16x8*)(lds + PG8_SB(b, h) + boff + n * 2048 + k * 1024); } while (0)
; #define PG8_MMA(ai, bj, At, Bt) do { if (GEMM_PRIO_MODE == 0) __builtin_amdgcn_s_setprio(1); PG8_MMA_LOOPS \
;         acc[ai][bj][m][n] = __builtin_amdgcn_mfma_f32_16x16x32_bf16(Bt[n][k], At[m][k], acc[ai][bj][m][n], 0, 0, 0); if (GEMM_PRIO_MODE == 0) __builtin_amdgcn_s_setprio(0); } while (0)
; #define PG8_WAIT_V(n) asm volatile("s_waitcnt vmcnt(" #n ")" ::: "memory")
; #define PG8_WAIT_L(n) asm volatile("s_waitcnt lgkmcnt(" #n ")" ::: "memory")
; #define PG8_BAR __builtin_amdgcn_s_barrier()
; #define PG8_SCHED __builtin_amdgcn_sched_barrier(0)
;     ...
;         for (int t = t0; t < nt; t += 2) {
;             const bool last = (t == nt - 2);
;             const char* a1 = cA + (size_t)(t + 1) * kstepA;
;             const char* a2 = last ? nA : cA + (size_t)(t + 2) * kstepA; const char* b2 = last ? nB : cB + (size_t)(t + 2) * kstepB;
;     ...
;             PG8_LDB(B0, 1, 0); PG8_LDB(B1, 1, 1); PG8_SCHED; PG8_LDA(At, 1, 0); PG8_STAGEA(PG8_SA(0, 1), a2 + hstepA, voffA);
;             PG8_WAIT_V(8); PG8_WAIT_L(0); PG8_BAR; PG8_MMA(0, 0, At, B0); PG8_MMA(0, 1, At, B1); PG8_BAR; PG8_SCHED;
;             PG8_LDA(At, 1, 1); PG8_STAGEB(PG8_SB(1, 0), b3, voffB); PG8_STAGEB(PG8_SB(1, 1), b3 + hstepB, voffB); PG8_STAGEA(PG8_SA(1, 0), a3, voffA);
;             PG8_WAIT_V(8); PG8_WAIT_L(0); PG8_BAR; PG8_MMA(1, 0, At, B0); PG8_MMA(1, 1, At, B1); PG8_BAR; PG8_SCHED;
	s_add_i32 s91, 0, 0x18000
	s_add_i32 s94, 0, 0x1c000
	ds_read_b128 v[130:133], v220 offset:32768
	ds_read_b128 v[134:137], v220 offset:33792
	ds_read_b128 v[148:151], v220 offset:34816
	ds_read_b128 v[152:155], v220 offset:35840
	ds_read_b128 v[162:165], v220 offset:49152
	ds_read_b128 v[166:169], v220 offset:50176
	ds_read_b128 v[170:173], v220 offset:51200
	ds_read_b128 v[174:177], v220 offset:52224
	s_add_u32 s6, s40, 0x100000
	s_addc_u32 s7, s41, 0
	s_mov_b32 m0, s43
	ds_read_b128 v[178:181], v161 offset:32768
	ds_read_b128 v[182:185], v161 offset:33792
	ds_read_b128 v[186:189], v161 offset:34816
	ds_read_b128 v[190:193], v161 offset:35840
	ds_read_b128 v[194:197], v161 offset:36864
	ds_read_b128 v[198:201], v161 offset:37888
	ds_read_b128 v[202:205], v161 offset:38912
	global_load_lds_dwordx4 v142, s[6:7]
	s_mov_b32 m0, s50
	ds_read_b128 v[206:209], v161 offset:39936
	global_load_lds_dwordx4 v140, s[6:7]
	s_waitcnt vmcnt(8)
	s_waitcnt lgkmcnt(0)
	s_nop 0
	s_barrier
	v_mfma_f32_16x16x32_bf16 v[126:129], v[130:133], v[178:181], v[126:129]
	v_mfma_f32_16x16x32_bf16 v[122:125], v[148:151], v[178:181], v[122:125]
	v_mfma_f32_16x16x32_bf16 v[110:113], v[130:133], v[186:189], v[110:113]
	v_mfma_f32_16x16x32_bf16 v[106:109], v[148:151], v[186:189], v[106:109]
	v_mfma_f32_16x16x32_bf16 v[94:97], v[130:133], v[194:197], v[94:97]
	v_mfma_f32_16x16x32_bf16 v[90:93], v[148:151], v[194:197], v[90:93]
	v_mfma_f32_16x16x32_bf16 v[78:81], v[130:133], v[202:205], v[78:81]
	v_mfma_f32_16x16x32_bf16 v[74:77], v[148:151], v[202:205], v[74:77]
	v_mfma_f32_16x16x32_bf16 v[126:129], v[134:137], v[182:185], v[126:129]
	v_mfma_f32_16x16x32_bf16 v[122:125], v[152:155], v[182:185], v[122:125]
	v_mfma_f32_16x16x32_bf16 v[110:113], v[134:137], v[190:193], v[110:113]
	v_mfma_f32_16x16x32_bf16 v[106:109], v[152:155], v[190:193], v[106:109]
	v_mfma_f32_16x16x32_bf16 v[94:97], v[134:137], v[198:201], v[94:97]
	v_mfma_f32_16x16x32_bf16 v[90:93], v[152:155], v[198:201], v[90:93]
	v_mfma_f32_16x16x32_bf16 v[78:81], v[134:137], v[206:209], v[78:81]
	v_mfma_f32_16x16x32_bf16 v[74:77], v[152:155], v[206:209], v[74:77]
	v_mfma_f32_16x16x32_bf16 v[118:121], v[162:165], v[178:181], v[118:121]
	v_mfma_f32_16x16x32_bf16 v[114:117], v[170:173], v[178:181], v[114:117]
	v_mfma_f32_16x16x32_bf16 v[102:105], v[162:165], v[186:189], v[102:105]
	v_mfma_f32_16x16x32_bf16 v[98:101], v[170:173], v[186:189], v[98:101]
	v_mfma_f32_16x16x32_bf16 v[86:89], v[162:165], v[194:197], v[86:89]
	v_mfma_f32_16x16x32_bf16 v[82:85], v[170:173], v[194:197], v[82:85]
	v_mfma_f32_16x16x32_bf16 v[70:73], v[162:165], v[202:205], v[70:73]
	v_mfma_f32_16x16x32_bf16 v[66:69], v[170:173], v[202:205], v[66:69]
	v_mfma_f32_16x16x32_bf16 v[118:121], v[166:169], v[182:185], v[118:121]
	v_mfma_f32_16x16x32_bf16 v[114:117], v[174:177], v[182:185], v[114:117]
	v_mfma_f32_16x16x32_bf16 v[102:105], v[166:169], v[190:193], v[102:105]
	v_mfma_f32_16x16x32_bf16 v[98:101], v[174:177], v[190:193], v[98:101]
	v_mfma_f32_16x16x32_bf16 v[86:89], v[166:169], v[198:201], v[86:89]
	v_mfma_f32_16x16x32_bf16 v[82:85], v[174:177], v[198:201], v[82:85]
	v_mfma_f32_16x16x32_bf16 v[70:73], v[166:169], v[206:209], v[70:73]
	v_mfma_f32_16x16x32_bf16 v[66:69], v[174:177], v[206:209], v[66:69]
	s_barrier
	s_add_i32 s6, s91, s12
	s_mov_b32 m0, s6
	ds_read_b128 v[178:181], v161 offset:49152
	ds_read_b128 v[182:185], v161 offset:50176
	ds_read_b128 v[186:189], v161 offset:51200
	ds_read_b128 v[190:193], v161 offset:52224
	ds_read_b128 v[194:197], v161 offset:53248
	s_add_u32 s100, s16, 0x80
	s_addc_u32 s101, s17, 0
	global_load_lds_dwordx4 v16, s[100:101]
	s_add_i32 m0, s6, 0x2000
	s_add_u32 s6, s16, 0x100080
	s_addc_u32 s7, s17, 0
	s_add_i32 s16, s94, s12
	global_load_lds_dwordx4 v138, s[100:101]
	s_mov_b32 m0, s16
	ds_read_b128 v[206:209], v161 offset:56320
	global_load_lds_dwordx4 v16, s[6:7]
	s_add_i32 m0, s16, 0x2000
	ds_read_b128 v[202:205], v161 offset:55296
	global_load_lds_dwordx4 v138, s[6:7]
	s_mov_b32 m0, s68
	s_nop 0
	s_add_u32 vcc_lo, s40, 0x80
	s_addc_u32 vcc_hi, s41, 0
	global_load_lds_dwordx4 v142, vcc
	s_mov_b32 m0, s69
	ds_read_b128 v[198:201], v161 offset:54272
	global_load_lds_dwordx4 v140, vcc
	s_waitcnt vmcnt(8)
	s_waitcnt lgkmcnt(0)
	s_barrier
	v_mfma_f32_16x16x32_bf16 v[62:65], v[130:133], v[178:181], v[62:65]
	v_mfma_f32_16x16x32_bf16 v[58:61], v[148:151], v[178:181], v[58:61]
	v_mfma_f32_16x16x32_bf16 v[46:49], v[130:133], v[186:189], v[46:49]
	v_mfma_f32_16x16x32_bf16 v[42:45], v[148:151], v[186:189], v[42:45]
	v_mfma_f32_16x16x32_bf16 v[30:33], v[130:133], v[194:197], v[30:33]
	v_mfma_f32_16x16x32_bf16 v[26:29], v[148:151], v[194:197], v[26:29]
	v_mfma_f32_16x16x32_bf16 v[12:15], v[130:133], v[202:205], v[12:15]
	v_mfma_f32_16x16x32_bf16 v[8:11], v[148:151], v[202:205], v[8:11]
	v_mfma_f32_16x16x32_bf16 v[62:65], v[134:137], v[182:185], v[62:65]
	v_mfma_f32_16x16x32_bf16 v[58:61], v[152:155], v[182:185], v[58:61]
	v_mfma_f32_16x16x32_bf16 v[46:49], v[134:137], v[190:193], v[46:49]
	v_mfma_f32_16x16x32_bf16 v[42:45], v[152:155], v[190:193], v[42:45]
	v_mfma_f32_16x16x32_bf16 v[30:33], v[134:137], v[198:201], v[30:33]
	v_mfma_f32_16x16x32_bf16 v[26:29], v[152:155], v[198:201], v[26:29]
	v_mfma_f32_16x16x32_bf16 v[12:15], v[134:137], v[206:209], v[12:15]
	v_mfma_f32_16x16x32_bf16 v[8:11], v[152:155], v[206:209], v[8:11]
	v_mfma_f32_16x16x32_bf16 v[54:57], v[162:165], v[178:181], v[54:57]
	v_mfma_f32_16x16x32_bf16 v[50:53], v[170:173], v[178:181], v[50:53]
	v_mfma_f32_16x16x32_bf16 v[38:41], v[162:165], v[186:189], v[38:41]
	v_mfma_f32_16x16x32_bf16 v[34:37], v[170:173], v[186:189], v[34:37]
	v_mfma_f32_16x16x32_bf16 v[22:25], v[162:165], v[194:197], v[22:25]
	v_mfma_f32_16x16x32_bf16 v[18:21], v[170:173], v[194:197], v[18:21]
	v_mfma_f32_16x16x32_bf16 v[4:7], v[162:165], v[202:205], v[4:7]
	v_mfma_f32_16x16x32_bf16 v[0:3], v[170:173], v[202:205], v[0:3]
	v_mfma_f32_16x16x32_bf16 v[54:57], v[166:169], v[182:185], v[54:57]
	v_mfma_f32_16x16x32_bf16 v[50:53], v[174:177], v[182:185], v[50:53]
	v_mfma_f32_16x16x32_bf16 v[38:41], v[166:169], v[190:193], v[38:41]
	v_mfma_f32_16x16x32_bf16 v[34:37], v[174:177], v[190:193], v[34:37]
	v_mfma_f32_16x16x32_bf16 v[22:25], v[166:169], v[198:201], v[22:25]
	v_mfma_f32_16x16x32_bf16 v[18:21], v[174:177], v[198:201], v[18:21]
	v_mfma_f32_16x16x32_bf16 v[4:7], v[166:169], v[206:209], v[4:7]
	v_mfma_f32_16x16x32_bf16 v[0:3], v[174:177], v[206:209], v[0:3]
	s_barrier
	s_add_i32 s90, s90, 2
	s_add_u32 s38, s38, 0x100
	s_addc_u32 s39, s39, 0
	s_add_u32 s0, s0, 0x100
	s_addc_u32 s1, s1, 0
	s_cmp_gt_u32 s90, 61
	s_cbranch_scc0 .LBB0_558
	s_and_b64 vcc, exec, s[18:19]
	s_cbranch_vccz .LBB0_561
	s_barrier

; #define PG8_STAGEA(bufoff, gbase, voff) PG8_STAGE_X(bufoff, gbase, voff, AUXA)
; #define PG8_STR(x) PG8_STR2(x)
;     ...
;         const bool has_next = S.next(ui + 1, nxt);
;         const char* nA = has_next ? (const char*)g.A + (size_t)nxt.pm * tstepA : cA; const char* nB = has_next ? (const char*)g.Bt + (size_t)nxt.pn * tstepB : cB;
;         int t0 = 0;
;         if constexpr (SP2 && GEMM_RELAX == 1) { if (ui > 0) {
;             const char* a1 = cA + kstepA; const char* a2 = cA + 2 * kstepA; const char* b2 = cB + 2 * kstepB; const char* a3 = a2 + kstepA; const char* b3 = b2 + kstepB;
;             PG8_LDB(B0, 0, 0); PG8_LDB(B1, 0, 1); PG8_SCHED; PG8_LDA(At, 0, 0); PG8_STAGEA(PG8_SA(1, 1), a1 + hstepA, voffA);
;             PG8_WAIT_V(24); PG8_WAIT_L(0); PG8_BAR; PG8_MMA(0, 0, At, B0); PG8_MMA(0, 1, At, B1); PG8_BAR; PG8_SCHED;
;             PG8_LDA(At, 0, 1); PG8_STAGEB(PG8_SB(0, 0), b2, voffB); PG8_STAGEB(PG8_SB(0, 1), b2 + hstepB, voffB); PG8_STAGEA(PG8_SA(0, 0), a2, voffA);
;             PG8_WAIT_V(24); PG8_WAIT_L(0); PG8_BAR; PG8_MMA(1, 0, At, B0); PG8_MMA(1, 1, At, B1); PG8_BAR; PG8_SCHED;
;             PG8_LDB(B0, 1, 0); PG8_LDB(B1, 1, 1); PG8_SCHED; PG8_LDA(At, 1, 0); PG8_STAGEA(PG8_SA(0, 1), a2 + hstepA, voffA);
;             PG8_WAIT_V(8); PG8_WAIT_L(0); PG8_BAR; PG8_MMA(0, 0, At, B0); PG8_MMA(0, 1, At, B1); PG8_BAR; PG8_SCHED;
;             PG8_LDA(At, 1, 1); PG8_STAGEB(PG8_SB(1, 0), b3, voffB); PG8_STAGEB(PG8_SB(1, 1), b3 + hstepB, voffB); PG8_STAGEA(PG8_SA(1, 0), a3, voffA);
;             PG8_WAIT_V(8); PG8_WAIT_L(0); PG8_BAR; PG8_MMA(1, 0, At, B0); PG8_MMA(1, 1, At, B1); PG8_BAR; PG8_SCHED;
;             t0 = 2; } }
;     ...
;         asm volatile(".p2align " PG8_STR(GEMM_LOOP_ALIGN) ::: "memory");
;     ...
;         for (int t = t0; t < nt; t += 2) {
;             const bool last = (t == nt - 2);
;             const char* a1 = cA + (size_t)(t + 1) * kstepA;
;             const char* a2 = last ? nA : cA + (size_t)(t + 2) * kstepA; const char* b2 = last ? nB : cB + (size_t)(t + 2) * kstepB;
;             const char* a3 = a2 + kstepA; const char* b3 = b2 + kstepB;
;             if (last && has_next) S.a_ready(nxt);
;             if constexpr (SP2) {
;             PG8_LDB(B0, 0, 0); PG8_LDB(B1, 0, 1); PG8_SCHED; PG8_LDA(At, 0, 0); PG8_STAGEA(PG8_SA(1, 1), a1 + hstepA, voffA);
;     ...
;             const int relax = __builtin_amdgcn_readfirstlane((t == 0 && ui > 0) ? 1 : 0);
.LBB0_711:
	s_ashr_i32 s25, s24, 31
	s_lshl_b64 s[0:1], s[24:25], 21
	s_add_u32 s26, s56, s0
	s_addc_u32 s27, s57, s1
	s_and_b64 s[0:1], s[10:11], exec
	s_cselect_b32 s0, s27, s13
	s_cselect_b32 s1, s26, s12
	s_ashr_i32 s23, s22, 31
	s_lshl_b64 s[6:7], s[22:23], 21
	s_add_u32 s36, s51, s6
	s_addc_u32 s37, s68, s7
	s_and_b64 s[6:7], s[10:11], exec
	s_cselect_b32 s23, s37, s43
	s_cselect_b32 s25, s36, s42
	s_add_u32 s40, s12, 0x100080
	s_addc_u32 s41, s13, 0
	s_add_u32 s12, s42, 0x100
	s_addc_u32 s13, s43, 0
	s_mov_b32 s39, -2
	s_add_u32 s6, s40, 0xfff00080
	s_addc_u32 s7, s41, -1
	s_add_i32 s95, 0, 0x10000
	s_cmp_eq_u32 s39, 60
	s_cselect_b32 s43, s0, s7
	s_cselect_b32 s42, s1, s6
	v_add_u32_e32 v144, s95, v146
	s_cselect_b32 s17, s23, s13
	s_cselect_b32 s16, s25, s12
	s_add_i32 vcc_lo, 0, 0x14000
	ds_read_b128 v[150:153], v144
	ds_read_b128 v[154:157], v144 offset:1024
	ds_read_b128 v[158:161], v144 offset:2048
	ds_read_b128 v[162:165], v144 offset:3072
	v_add_u32_e32 v144, vcc_lo, v146
	ds_read_b128 v[166:169], v144
	ds_read_b128 v[170:173], v144 offset:1024
	ds_read_b128 v[174:177], v144 offset:2048
	ds_read_b128 v[178:181], v144 offset:3072
	v_lshl_add_u64 v[144:145], s[40:41], 0, v[140:141]
	s_add_i32 m0, s69, 0xc000
	ds_read_b128 v[182:185], v148
	ds_read_b128 v[186:189], v148 offset:1024
	ds_read_b128 v[190:193], v148 offset:2048
	ds_read_b128 v[194:197], v148 offset:3072
	ds_read_b128 v[198:201], v148 offset:4096
	ds_read_b128 v[202:205], v148 offset:5120
	ds_read_b128 v[206:209], v148 offset:6144
	ds_read_b128 v[210:213], v148 offset:7168
	global_load_lds_dwordx4 v[144:145], off
	v_lshl_add_u64 v[144:145], s[40:41], 0, v[142:143]
	s_add_i32 m0, s69, 0xe000
	s_nop 0
	global_load_lds_dwordx4 v[144:145], off
	s_waitcnt vmcnt(8)
	s_waitcnt lgkmcnt(0)
	s_nop 0
	s_barrier
	v_mfma_f32_16x16x32_bf16 v[126:129], v[150:153], v[182:185], 0
	v_mfma_f32_16x16x32_bf16 v[122:125], v[158:161], v[182:185], 0
	v_mfma_f32_16x16x32_bf16 v[110:113], v[150:153], v[190:193], 0
	v_mfma_f32_16x16x32_bf16 v[106:109], v[158:161], v[190:193], 0
	v_mfma_f32_16x16x32_bf16 v[94:97], v[150:153], v[198:201], 0
	v_mfma_f32_16x16x32_bf16 v[90:93], v[158:161], v[198:201], 0
	v_mfma_f32_16x16x32_bf16 v[78:81], v[150:153], v[206:209], 0
	v_mfma_f32_16x16x32_bf16 v[74:77], v[158:161], v[206:209], 0
	v_mfma_f32_16x16x32_bf16 v[126:129], v[154:157], v[186:189], v[126:129]
	v_mfma_f32_16x16x32_bf16 v[122:125], v[162:165], v[186:189], v[122:125]
	v_mfma_f32_16x16x32_bf16 v[110:113], v[154:157], v[194:197], v[110:113]
	v_mfma_f32_16x16x32_bf16 v[106:109], v[162:165], v[194:197], v[106:109]
	v_mfma_f32_16x16x32_bf16 v[94:97], v[154:157], v[202:205], v[94:97]
	v_mfma_f32_16x16x32_bf16 v[90:93], v[162:165], v[202:205], v[90:93]
	v_mfma_f32_16x16x32_bf16 v[78:81], v[154:157], v[210:213], v[78:81]
	v_mfma_f32_16x16x32_bf16 v[74:77], v[162:165], v[210:213], v[74:77]
	v_mfma_f32_16x16x32_bf16 v[118:121], v[166:169], v[182:185], 0
	v_mfma_f32_16x16x32_bf16 v[114:117], v[174:177], v[182:185], 0
	v_mfma_f32_16x16x32_bf16 v[102:105], v[166:169], v[190:193], 0
	v_mfma_f32_16x16x32_bf16 v[98:101], v[174:177], v[190:193], 0
	v_mfma_f32_16x16x32_bf16 v[86:89], v[166:169], v[198:201], 0
	v_mfma_f32_16x16x32_bf16 v[82:85], v[174:177], v[198:201], 0
	v_mfma_f32_16x16x32_bf16 v[70:73], v[166:169], v[206:209], 0
	v_mfma_f32_16x16x32_bf16 v[66:69], v[174:177], v[206:209], 0
	v_mfma_f32_16x16x32_bf16 v[118:121], v[170:173], v[186:189], v[118:121]
	v_mfma_f32_16x16x32_bf16 v[114:117], v[178:181], v[186:189], v[114:117]
	v_mfma_f32_16x16x32_bf16 v[102:105], v[170:173], v[194:197], v[102:105]
	v_mfma_f32_16x16x32_bf16 v[98:101], v[178:181], v[194:197], v[98:101]
	v_mfma_f32_16x16x32_bf16 v[86:89], v[170:173], v[202:205], v[86:89]
	v_mfma_f32_16x16x32_bf16 v[82:85], v[178:181], v[202:205], v[82:85]
	v_mfma_f32_16x16x32_bf16 v[70:73], v[170:173], v[210:213], v[70:73]
	v_mfma_f32_16x16x32_bf16 v[66:69], v[178:181], v[210:213], v[66:69]
	s_barrier
	s_add_i32 s6, s95, s50
	v_lshl_add_u64 v[144:145], s[16:17], 0, v[134:135]
	s_mov_b32 m0, s6
	ds_read_b128 v[182:185], v148 offset:16384
	ds_read_b128 v[186:189], v148 offset:17408
	ds_read_b128 v[190:193], v148 offset:18432
	ds_read_b128 v[194:197], v148 offset:19456
	ds_read_b128 v[198:201], v148 offset:20480
	ds_read_b128 v[202:205], v148 offset:21504
	ds_read_b128 v[206:209], v148 offset:22528
	ds_read_b128 v[210:213], v148 offset:23552
	global_load_lds_dwordx4 v[144:145], off
	s_add_i32 m0, s6, 0x2000
	s_add_u32 s6, s16, 0x100000
	v_lshl_add_u64 v[214:215], s[16:17], 0, v[130:131]
	s_addc_u32 s7, s17, 0
	s_add_i32 s95, vcc_lo, s50
	global_load_lds_dwordx4 v[214:215], off
	v_lshl_add_u64 v[216:217], s[6:7], 0, v[134:135]
	s_mov_b32 m0, s95
	v_lshl_add_u64 v[218:219], s[42:43], 0, v[132:133]
	global_load_lds_dwordx4 v[216:217], off
	v_lshl_add_u64 v[216:217], s[6:7], 0, v[130:131]
	s_add_i32 m0, s95, 0x2000
	s_nop 0
	global_load_lds_dwordx4 v[216:217], off
	v_lshl_add_u64 v[216:217], s[42:43], 0, v[136:137]
	s_mov_b32 m0, s69
	s_nop 0
	global_load_lds_dwordx4 v[216:217], off
	s_mov_b32 m0, s72
	s_nop 0
	global_load_lds_dwordx4 v[218:219], off
	s_waitcnt vmcnt(8)
	s_waitcnt lgkmcnt(0)
	s_barrier
; #define PG8_STAGEA(bufoff, gbase, voff) PG8_STAGE_X(bufoff, gbase, voff, AUXA)
; #define PG8_STAGEB(bufoff, gbase, voff) PG8_STAGE_X(bufoff, gbase, voff, AUXB)
; #define PG8_LDA(dst, b, h) do { _Pragma("unroll") for (int m = 0; m < 4; ++m) _Pragma("unroll") for (int k = 0; k < 2; ++k) dst[m][k] = *(const PG8_LAS bf16x8*)(lds + PG8_SA(b, h) + aoff + m * 2048 + k * 1024); } while (0)
; #define PG8_LDB(dst, b, h) do { _Pragma("unroll") for (int n = 0; n < 2; ++n) _Pragma("unroll") for (int k = 0; k < 2; ++k) dst[n][k] = *(const PG8_LAS bf16x8*)(lds + PG8_SB(b, h) + boff + n * 2048 + k * 1024); } while (0)
; #define PG8_MMA(ai, bj, At, Bt) do { if (GEMM_PRIO_MODE == 0) __builtin_amdgcn_s_setprio(1); PG8_MMA_LOOPS \
;         acc[ai][bj][m][n] = __builtin_amdgcn_mfma_f32_16x16x32_bf16(Bt[n][k], At[m][k], acc[ai][bj][m][n], 0, 0, 0); if (GEMM_PRIO_MODE == 0) __builtin_amdgcn_s_setprio(0); } while (0)
; #define PG8_WAIT_V(n) asm volatile("s_waitcnt vmcnt(" #n ")" ::: "memory")
; #define PG8_WAIT_VR(n, nr, flag) asm volatile("s_cmp_eq_u32 %0, 0\n\ts_cbranch_scc1 .Lpg8s%=\n\ts_waitcnt vmcnt(" #nr ")\n\ts_branch .Lpg8d%=\n.Lpg8s%=:\n\ts_waitcnt vmcnt(" #n ")\n.Lpg8d%=:" :: "s"(flag) : "memory", "scc")
; #define PG8_WAIT_L(n) asm volatile("s_waitcnt lgkmcnt(" #n ")" ::: "memory")
; #define PG8_BAR __builtin_amdgcn_s_barrier()
; #define PG8_SCHED __builtin_amdgcn_sched_barrier(0)
;     ...
;             PG8_LDA(At, 0, 1); PG8_STAGEB(PG8_SB(0, 0), b2, voffB); PG8_STAGEB(PG8_SB(0, 1), b2 + hstepB, voffB); PG8_STAGEA(PG8_SA(0, 0), a2, voffA);
;     ...
;             PG8_WAIT_VR(8, 24, relax); PG8_WAIT_L(0); PG8_BAR; PG8_MMA(1, 0, At, B0); PG8_MMA(1, 1, At, B1); PG8_BAR; PG8_SCHED;
;     ...
;             PG8_WAIT_V(8); PG8_WAIT_L(0); PG8_BAR; PG8_MMA(1, 0, At, B0); PG8_MMA(1, 1, At, B1); PG8_BAR; PG8_SCHED;
;     ...
;             PG8_LDB(B0, 1, 0); PG8_LDB(B1, 1, 1); PG8_SCHED; PG8_LDA(At, 1, 0); PG8_STAGEA(PG8_SA(0, 1), a2 + hstepA, voffA);
;             PG8_WAIT_V(8); PG8_WAIT_L(0); PG8_BAR; PG8_MMA(0, 0, At, B0); PG8_MMA(0, 1, At, B1); PG8_BAR; PG8_SCHED;
;             PG8_LDA(At, 1, 1); PG8_STAGEB(PG8_SB(1, 0), b3, voffB); PG8_STAGEB(PG8_SB(1, 1), b3 + hstepB, voffB); PG8_STAGEA(PG8_SA(1, 0), a3, voffA);
;             PG8_WAIT_V(8); PG8_WAIT_L(0); PG8_BAR; PG8_MMA(1, 0, At, B0); PG8_MMA(1, 1, At, B1); PG8_BAR; PG8_SCHED;
	v_mfma_f32_16x16x32_bf16 v[62:65], v[150:153], v[182:185], 0
	v_mfma_f32_16x16x32_bf16 v[58:61], v[158:161], v[182:185], 0
	v_mfma_f32_16x16x32_bf16 v[46:49], v[150:153], v[190:193], 0
	v_mfma_f32_16x16x32_bf16 v[42:45], v[158:161], v[190:193], 0
	v_mfma_f32_16x16x32_bf16 v[30:33], v[150:153], v[198:201], 0
	v_mfma_f32_16x16x32_bf16 v[26:29], v[158:161], v[198:201], 0
	v_mfma_f32_16x16x32_bf16 v[12:15], v[150:153], v[206:209], 0
	v_mfma_f32_16x16x32_bf16 v[8:11], v[158:161], v[206:209], 0
	v_mfma_f32_16x16x32_bf16 v[62:65], v[154:157], v[186:189], v[62:65]
	v_mfma_f32_16x16x32_bf16 v[58:61], v[162:165], v[186:189], v[58:61]
	v_mfma_f32_16x16x32_bf16 v[46:49], v[154:157], v[194:197], v[46:49]
	v_mfma_f32_16x16x32_bf16 v[42:45], v[162:165], v[194:197], v[42:45]
	v_mfma_f32_16x16x32_bf16 v[30:33], v[154:157], v[202:205], v[30:33]
	v_mfma_f32_16x16x32_bf16 v[26:29], v[162:165], v[202:205], v[26:29]
	v_mfma_f32_16x16x32_bf16 v[12:15], v[154:157], v[210:213], v[12:15]
	v_mfma_f32_16x16x32_bf16 v[8:11], v[162:165], v[210:213], v[8:11]
	v_mfma_f32_16x16x32_bf16 v[54:57], v[166:169], v[182:185], 0
	v_mfma_f32_16x16x32_bf16 v[50:53], v[174:177], v[182:185], 0
	v_mfma_f32_16x16x32_bf16 v[38:41], v[166:169], v[190:193], 0
	v_mfma_f32_16x16x32_bf16 v[34:37], v[174:177], v[190:193], 0
	v_mfma_f32_16x16x32_bf16 v[22:25], v[166:169], v[198:201], 0
	v_mfma_f32_16x16x32_bf16 v[18:21], v[174:177], v[198:201], 0
	v_mfma_f32_16x16x32_bf16 v[4:7], v[166:169], v[206:209], 0
	v_mfma_f32_16x16x32_bf16 v[0:3], v[174:177], v[206:209], 0
	v_mfma_f32_16x16x32_bf16 v[54:57], v[170:173], v[186:189], v[54:57]
	v_mfma_f32_16x16x32_bf16 v[50:53], v[178:181], v[186:189], v[50:53]
	v_mfma_f32_16x16x32_bf16 v[38:41], v[170:173], v[194:197], v[38:41]
	v_mfma_f32_16x16x32_bf16 v[34:37], v[178:181], v[194:197], v[34:37]
	v_mfma_f32_16x16x32_bf16 v[22:25], v[170:173], v[202:205], v[22:25]
	v_mfma_f32_16x16x32_bf16 v[18:21], v[178:181], v[202:205], v[18:21]
	v_mfma_f32_16x16x32_bf16 v[4:7], v[170:173], v[210:213], v[4:7]
	v_mfma_f32_16x16x32_bf16 v[0:3], v[178:181], v[210:213], v[0:3]
	s_barrier
	s_add_i32 s95, 0, 0x18000
	v_add_u32_e32 v149, s95, v146
	s_add_i32 vcc_lo, 0, 0x1c000
	ds_read_b128 v[150:153], v149
	ds_read_b128 v[154:157], v149 offset:1024
	ds_read_b128 v[158:161], v149 offset:2048
	ds_read_b128 v[162:165], v149 offset:3072
	v_add_u32_e32 v149, vcc_lo, v146
	ds_read_b128 v[166:169], v149
	ds_read_b128 v[170:173], v149 offset:1024
	ds_read_b128 v[174:177], v149 offset:2048
	ds_read_b128 v[178:181], v149 offset:3072
	s_add_u32 s6, s42, 0x100000
	s_addc_u32 s7, s43, 0
	s_mov_b32 m0, s73
	v_lshl_add_u64 v[220:221], s[6:7], 0, v[136:137]
	ds_read_b128 v[182:185], v148 offset:32768
	ds_read_b128 v[186:189], v148 offset:33792
	ds_read_b128 v[190:193], v148 offset:34816
	ds_read_b128 v[194:197], v148 offset:35840
	ds_read_b128 v[198:201], v148 offset:36864
	ds_read_b128 v[202:205], v148 offset:37888
	ds_read_b128 v[206:209], v148 offset:38912
	ds_read_b128 v[210:213], v148 offset:39936
	global_load_lds_dwordx4 v[220:221], off
	v_lshl_add_u64 v[220:221], s[6:7], 0, v[132:133]
	s_mov_b32 m0, s82
	s_nop 0
	global_load_lds_dwordx4 v[220:221], off
	s_waitcnt vmcnt(8)
	s_waitcnt lgkmcnt(0)
	s_barrier
	v_mfma_f32_16x16x32_bf16 v[126:129], v[150:153], v[182:185], v[126:129]
	v_mfma_f32_16x16x32_bf16 v[122:125], v[158:161], v[182:185], v[122:125]
	v_mfma_f32_16x16x32_bf16 v[110:113], v[150:153], v[190:193], v[110:113]
	v_mfma_f32_16x16x32_bf16 v[106:109], v[158:161], v[190:193], v[106:109]
	v_mfma_f32_16x16x32_bf16 v[94:97], v[150:153], v[198:201], v[94:97]
	v_mfma_f32_16x16x32_bf16 v[90:93], v[158:161], v[198:201], v[90:93]
	v_mfma_f32_16x16x32_bf16 v[78:81], v[150:153], v[206:209], v[78:81]
	v_mfma_f32_16x16x32_bf16 v[74:77], v[158:161], v[206:209], v[74:77]
	v_mfma_f32_16x16x32_bf16 v[126:129], v[154:157], v[186:189], v[126:129]
	v_mfma_f32_16x16x32_bf16 v[122:125], v[162:165], v[186:189], v[122:125]
	v_mfma_f32_16x16x32_bf16 v[110:113], v[154:157], v[194:197], v[110:113]
	v_mfma_f32_16x16x32_bf16 v[106:109], v[162:165], v[194:197], v[106:109]
	v_mfma_f32_16x16x32_bf16 v[94:97], v[154:157], v[202:205], v[94:97]
	v_mfma_f32_16x16x32_bf16 v[90:93], v[162:165], v[202:205], v[90:93]
	v_mfma_f32_16x16x32_bf16 v[78:81], v[154:157], v[210:213], v[78:81]
	v_mfma_f32_16x16x32_bf16 v[74:77], v[162:165], v[210:213], v[74:77]
	v_mfma_f32_16x16x32_bf16 v[118:121], v[166:169], v[182:185], v[118:121]
	v_mfma_f32_16x16x32_bf16 v[114:117], v[174:177], v[182:185], v[114:117]
	v_mfma_f32_16x16x32_bf16 v[102:105], v[166:169], v[190:193], v[102:105]
	v_mfma_f32_16x16x32_bf16 v[98:101], v[174:177], v[190:193], v[98:101]
	v_mfma_f32_16x16x32_bf16 v[86:89], v[166:169], v[198:201], v[86:89]
	v_mfma_f32_16x16x32_bf16 v[82:85], v[174:177], v[198:201], v[82:85]
	v_mfma_f32_16x16x32_bf16 v[70:73], v[166:169], v[206:209], v[70:73]
	v_mfma_f32_16x16x32_bf16 v[66:69], v[174:177], v[206:209], v[66:69]
	v_mfma_f32_16x16x32_bf16 v[118:121], v[170:173], v[186:189], v[118:121]
	v_mfma_f32_16x16x32_bf16 v[114:117], v[178:181], v[186:189], v[114:117]
	v_mfma_f32_16x16x32_bf16 v[102:105], v[170:173], v[194:197], v[102:105]
	v_mfma_f32_16x16x32_bf16 v[98:101], v[178:181], v[194:197], v[98:101]
	v_mfma_f32_16x16x32_bf16 v[86:89], v[170:173], v[202:205], v[86:89]
	v_mfma_f32_16x16x32_bf16 v[82:85], v[178:181], v[202:205], v[82:85]
	v_mfma_f32_16x16x32_bf16 v[70:73], v[170:173], v[210:213], v[70:73]
	v_mfma_f32_16x16x32_bf16 v[66:69], v[178:181], v[210:213], v[66:69]
	s_barrier
; #define PG8_STAGEA(bufoff, gbase, voff) PG8_STAGE_X(bufoff, gbase, voff, AUXA)
; #define PG8_STAGEB(bufoff, gbase, voff) PG8_STAGE_X(bufoff, gbase, voff, AUXB)
; #define PG8_LDA(dst, b, h) do { _Pragma("unroll") for (int m = 0; m < 4; ++m) _Pragma("unroll") for (int k = 0; k < 2; ++k) dst[m][k] = *(const PG8_LAS bf16x8*)(lds + PG8_SA(b, h) + aoff + m * 2048 + k * 1024); } while (0)
; #define PG8_WAIT_V(n) asm volatile("s_waitcnt vmcnt(" #n ")" ::: "memory")
; #define PG8_WAIT_L(n) asm volatile("s_waitcnt lgkmcnt(" #n ")" ::: "memory")
;     ...
;         for (int t = t0; t < nt; t += 2) {
;             const bool last = (t == nt - 2);
;             const char* a1 = cA + (size_t)(t + 1) * kstepA;
;             const char* a2 = last ? nA : cA + (size_t)(t + 2) * kstepA; const char* b2 = last ? nB : cB + (size_t)(t + 2) * kstepB;
;             const char* a3 = a2 + kstepA; const char* b3 = b2 + kstepB;
;             if (last && has_next) S.a_ready(nxt);
;             if constexpr (SP2) {
;             PG8_LDB(B0, 0, 0); PG8_LDB(B1, 0, 1); PG8_SCHED; PG8_LDA(At, 0, 0); PG8_STAGEA(PG8_SA(1, 1), a1 + hstepA, voffA);
;     ...
;             const int relax = __builtin_amdgcn_readfirstlane((t == 0 && ui > 0) ? 1 : 0);
;             PG8_WAIT_VR(8, 24, relax); PG8_WAIT_L(0); PG8_BAR; PG8_MMA(0, 0, At, B0); PG8_MMA(0, 1, At, B1); PG8_BAR; PG8_SCHED;
;     ...
;             PG8_WAIT_V(8); PG8_WAIT_L(0); PG8_BAR; PG8_MMA(0, 0, At, B0); PG8_MMA(0, 1, At, B1); PG8_BAR; PG8_SCHED;
;     ...
;             PG8_LDA(At, 0, 1); PG8_STAGEB(PG8_SB(0, 0), b2, voffB); PG8_STAGEB(PG8_SB(0, 1), b2 + hstepB, voffB); PG8_STAGEA(PG8_SA(0, 0), a2, voffA);
;     ...
;             PG8_WAIT_VR(8, 24, relax); PG8_WAIT_L(0); PG8_BAR; PG8_MMA(1, 0, At, B0); PG8_MMA(1, 1, At, B1); PG8_BAR; PG8_SCHED;
;     ...
;             PG8_WAIT_V(8); PG8_WAIT_L(0); PG8_BAR; PG8_MMA(1, 0, At, B0); PG8_MMA(1, 1, At, B1); PG8_BAR; PG8_SCHED;
;     ...
;             PG8_LDB(B0, 1, 0); PG8_LDB(B1, 1, 1); PG8_SCHED; PG8_LDA(At, 1, 0); PG8_STAGEA(PG8_SA(0, 1), a2 + hstepA, voffA);
;             PG8_WAIT_V(8); PG8_WAIT_L(0); PG8_BAR; PG8_MMA(0, 0, At, B0); PG8_MMA(0, 1, At, B1); PG8_BAR; PG8_SCHED;
;             PG8_LDA(At, 1, 1); PG8_STAGEB(PG8_SB(1, 0), b3, voffB); PG8_STAGEB(PG8_SB(1, 1), b3 + hstepB, voffB); PG8_STAGEA(PG8_SA(1, 0), a3, voffA);
;             PG8_WAIT_V(8); PG8_WAIT_L(0); PG8_BAR; PG8_MMA(1, 0, At, B0); PG8_MMA(1, 1, At, B1); PG8_BAR; PG8_SCHED;
	s_add_i32 s6, s95, s50
	v_lshl_add_u64 v[144:145], v[144:145], 0, s[86:87]
	s_mov_b32 m0, s6
	ds_read_b128 v[182:185], v148 offset:49152
	ds_read_b128 v[186:189], v148 offset:50176
	ds_read_b128 v[190:193], v148 offset:51200
	ds_read_b128 v[194:197], v148 offset:52224
	ds_read_b128 v[198:201], v148 offset:53248
	ds_read_b128 v[202:205], v148 offset:54272
	ds_read_b128 v[206:209], v148 offset:55296
	ds_read_b128 v[210:213], v148 offset:56320
	global_load_lds_dwordx4 v[144:145], off
	s_add_i32 m0, s6, 0x2000
	s_add_u32 s6, s16, 0x100080
	v_lshl_add_u64 v[144:145], v[214:215], 0, s[86:87]
	s_addc_u32 s7, s17, 0
	s_add_i32 s16, vcc_lo, s50
	global_load_lds_dwordx4 v[144:145], off
	v_lshl_add_u64 v[144:145], s[6:7], 0, v[134:135]
	s_mov_b32 m0, s16
	s_nop 0
	global_load_lds_dwordx4 v[144:145], off
	v_lshl_add_u64 v[144:145], s[6:7], 0, v[130:131]
	s_add_i32 m0, s16, 0x2000
	s_nop 0
	global_load_lds_dwordx4 v[144:145], off
	v_lshl_add_u64 v[144:145], v[216:217], 0, s[86:87]
	s_mov_b32 m0, s83
	s_nop 0
	global_load_lds_dwordx4 v[144:145], off
	v_lshl_add_u64 v[144:145], v[218:219], 0, s[86:87]
	s_mov_b32 m0, s90
	s_nop 0
	global_load_lds_dwordx4 v[144:145], off
	s_waitcnt vmcnt(8)
	s_waitcnt lgkmcnt(0)
	s_nop 0
	s_nop 0
	s_nop 0
	s_barrier
	v_mfma_f32_16x16x32_bf16 v[62:65], v[150:153], v[182:185], v[62:65]
	v_mfma_f32_16x16x32_bf16 v[58:61], v[158:161], v[182:185], v[58:61]
	v_mfma_f32_16x16x32_bf16 v[46:49], v[150:153], v[190:193], v[46:49]
	v_mfma_f32_16x16x32_bf16 v[42:45], v[158:161], v[190:193], v[42:45]
	v_mfma_f32_16x16x32_bf16 v[30:33], v[150:153], v[198:201], v[30:33]
	v_mfma_f32_16x16x32_bf16 v[26:29], v[158:161], v[198:201], v[26:29]
	v_mfma_f32_16x16x32_bf16 v[12:15], v[150:153], v[206:209], v[12:15]
	v_mfma_f32_16x16x32_bf16 v[8:11], v[158:161], v[206:209], v[8:11]
	v_mfma_f32_16x16x32_bf16 v[62:65], v[154:157], v[186:189], v[62:65]
	v_mfma_f32_16x16x32_bf16 v[58:61], v[162:165], v[186:189], v[58:61]
	v_mfma_f32_16x16x32_bf16 v[46:49], v[154:157], v[194:197], v[46:49]
	v_mfma_f32_16x16x32_bf16 v[42:45], v[162:165], v[194:197], v[42:45]
	v_mfma_f32_16x16x32_bf16 v[30:33], v[154:157], v[202:205], v[30:33]
	v_mfma_f32_16x16x32_bf16 v[26:29], v[162:165], v[202:205], v[26:29]
	v_mfma_f32_16x16x32_bf16 v[12:15], v[154:157], v[210:213], v[12:15]
	v_mfma_f32_16x16x32_bf16 v[8:11], v[162:165], v[210:213], v[8:11]
	v_mfma_f32_16x16x32_bf16 v[54:57], v[166:169], v[182:185], v[54:57]
	v_mfma_f32_16x16x32_bf16 v[50:53], v[174:177], v[182:185], v[50:53]
	v_mfma_f32_16x16x32_bf16 v[38:41], v[166:169], v[190:193], v[38:41]
	v_mfma_f32_16x16x32_bf16 v[34:37], v[174:177], v[190:193], v[34:37]
	v_mfma_f32_16x16x32_bf16 v[22:25], v[166:169], v[198:201], v[22:25]
	v_mfma_f32_16x16x32_bf16 v[18:21], v[174:177], v[198:201], v[18:21]
	v_mfma_f32_16x16x32_bf16 v[4:7], v[166:169], v[206:209], v[4:7]
	v_mfma_f32_16x16x32_bf16 v[0:3], v[174:177], v[206:209], v[0:3]
	v_mfma_f32_16x16x32_bf16 v[54:57], v[170:173], v[186:189], v[54:57]
	v_mfma_f32_16x16x32_bf16 v[50:53], v[178:181], v[186:189], v[50:53]
	v_mfma_f32_16x16x32_bf16 v[38:41], v[170:173], v[194:197], v[38:41]
	v_mfma_f32_16x16x32_bf16 v[34:37], v[178:181], v[194:197], v[34:37]
	v_mfma_f32_16x16x32_bf16 v[22:25], v[170:173], v[202:205], v[22:25]
	v_mfma_f32_16x16x32_bf16 v[18:21], v[178:181], v[202:205], v[18:21]
	v_mfma_f32_16x16x32_bf16 v[4:7], v[170:173], v[210:213], v[4:7]
	v_mfma_f32_16x16x32_bf16 v[0:3], v[178:181], v[210:213], v[0:3]
	s_barrier
	s_add_i32 s39, s39, 2
	s_add_u32 s40, s40, 0x100
	s_addc_u32 s41, s41, 0
	s_add_u32 s12, s12, 0x100
	s_addc_u32 s13, s13, 0
	v_add_u32_e32 v222, 0x10000, v146
.LBB0_712:
	s_add_u32 s6, s40, 0xfff00080
	s_addc_u32 s7, s41, -1
	s_add_i32 s95, 0, 0x10000
	s_cmp_eq_u32 s39, 60
	s_cselect_b32 s43, s0, s7
	s_cselect_b32 s42, s1, s6
	s_cselect_b32 s17, s23, s13
	s_cselect_b32 s16, s25, s12
	s_add_i32 vcc_lo, 0, 0x14000
	ds_read_b128 v[150:153], v222
	ds_read_b128 v[154:157], v222 offset:1024
	ds_read_b128 v[158:161], v222 offset:2048
	ds_read_b128 v[162:165], v222 offset:3072
	ds_read_b128 v[166:169], v222 offset:16384
	ds_read_b128 v[170:173], v222 offset:17408
	ds_read_b128 v[174:177], v222 offset:18432
	ds_read_b128 v[178:181], v222 offset:19456
	s_add_i32 m0, s69, 0xc000
	ds_read_b128 v[182:185], v148
	ds_read_b128 v[186:189], v148 offset:1024
	ds_read_b128 v[190:193], v148 offset:2048
	ds_read_b128 v[194:197], v148 offset:3072
	ds_read_b128 v[198:201], v148 offset:4096
	ds_read_b128 v[202:205], v148 offset:5120
	ds_read_b128 v[206:209], v148 offset:6144
	global_load_lds_dwordx4 v140, s[40:41]
	s_add_i32 m0, s69, 0xe000
	ds_read_b128 v[210:213], v148 offset:7168
	global_load_lds_dwordx4 v142, s[40:41]
	s_waitcnt vmcnt(8)
	s_waitcnt lgkmcnt(0)
	s_nop 0
	s_barrier
; #define PG8_STAGEA(bufoff, gbase, voff) PG8_STAGE_X(bufoff, gbase, voff, AUXA)
; #define PG8_STAGEB(bufoff, gbase, voff) PG8_STAGE_X(bufoff, gbase, voff, AUXB)
; #define PG8_LDA(dst, b, h) do { _Pragma("unroll") for (int m = 0; m < 4; ++m) _Pragma("unroll") for (int k = 0; k < 2; ++k) dst[m][k] = *(const PG8_LAS bf16x8*)(lds + PG8_SA(b, h) + aoff + m * 2048 + k * 1024); } while (0)
; #define PG8_LDB(dst, b, h) do { _Pragma("unroll") for (int n = 0; n < 2; ++n) _Pragma("unroll") for (int k = 0; k < 2; ++k) dst[n][k] = *(const PG8_LAS bf16x8*)(lds + PG8_SB(b, h) + boff + n * 2048 + k * 1024); } while (0)
; #define PG8_MMA(ai, bj, At, Bt) do { if (GEMM_PRIO_MODE == 0) __builtin_amdgcn_s_setprio(1); PG8_MMA_LOOPS \
;         acc[ai][bj][m][n] = __builtin_amdgcn_mfma_f32_16x16x32_bf16(Bt[n][k], At[m][k], acc[ai][bj][m][n], 0, 0, 0); if (GEMM_PRIO_MODE == 0) __builtin_amdgcn_s_setprio(0); } while (0)
; #define PG8_WAIT_V(n) asm volatile("s_waitcnt vmcnt(" #n ")" ::: "memory")
; #define PG8_WAIT_VR(n, nr, flag) asm volatile("s_cmp_eq_u32 %0, 0\n\ts_cbranch_scc1 .Lpg8s%=\n\ts_waitcnt vmcnt(" #nr ")\n\ts_branch .Lpg8d%=\n.Lpg8s%=:\n\ts_waitcnt vmcnt(" #n ")\n.Lpg8d%=:" :: "s"(flag) : "memory", "scc")
; #define PG8_WAIT_L(n) asm volatile("s_waitcnt lgkmcnt(" #n ")" ::: "memory")
; #define PG8_BAR __builtin_amdgcn_s_barrier()
; #define PG8_SCHED __builtin_amdgcn_sched_barrier(0)
;     ...
;             PG8_LDB(B0, 0, 0); PG8_LDB(B1, 0, 1); PG8_SCHED; PG8_LDA(At, 0, 0); PG8_STAGEA(PG8_SA(1, 1), a1 + hstepA, voffA);
;     ...
;             const int relax = __builtin_amdgcn_readfirstlane((t == 0 && ui > 0) ? 1 : 0);
;             PG8_WAIT_VR(8, 24, relax); PG8_WAIT_L(0); PG8_BAR; PG8_MMA(0, 0, At, B0); PG8_MMA(0, 1, At, B1); PG8_BAR; PG8_SCHED;
;     ...
;             PG8_WAIT_V(8); PG8_WAIT_L(0); PG8_BAR; PG8_MMA(0, 0, At, B0); PG8_MMA(0, 1, At, B1); PG8_BAR; PG8_SCHED;
;     ...
;             PG8_LDA(At, 0, 1); PG8_STAGEB(PG8_SB(0, 0), b2, voffB); PG8_STAGEB(PG8_SB(0, 1), b2 + hstepB, voffB); PG8_STAGEA(PG8_SA(0, 0), a2, voffA);
;     ...
;             PG8_WAIT_VR(8, 24, relax); PG8_WAIT_L(0); PG8_BAR; PG8_MMA(1, 0, At, B0); PG8_MMA(1, 1, At, B1); PG8_BAR; PG8_SCHED;
;     ...
;             PG8_WAIT_V(8); PG8_WAIT_L(0); PG8_BAR; PG8_MMA(1, 0, At, B0); PG8_MMA(1, 1, At, B1); PG8_BAR; PG8_SCHED;
	v_mfma_f32_16x16x32_bf16 v[126:129], v[150:153], v[182:185], v[126:129]
	v_mfma_f32_16x16x32_bf16 v[122:125], v[158:161], v[182:185], v[122:125]
	v_mfma_f32_16x16x32_bf16 v[110:113], v[150:153], v[190:193], v[110:113]
	v_mfma_f32_16x16x32_bf16 v[106:109], v[158:161], v[190:193], v[106:109]
	v_mfma_f32_16x16x32_bf16 v[94:97], v[150:153], v[198:201], v[94:97]
	v_mfma_f32_16x16x32_bf16 v[90:93], v[158:161], v[198:201], v[90:93]
	v_mfma_f32_16x16x32_bf16 v[78:81], v[150:153], v[206:209], v[78:81]
	v_mfma_f32_16x16x32_bf16 v[74:77], v[158:161], v[206:209], v[74:77]
	v_mfma_f32_16x16x32_bf16 v[126:129], v[154:157], v[186:189], v[126:129]
	v_mfma_f32_16x16x32_bf16 v[122:125], v[162:165], v[186:189], v[122:125]
	v_mfma_f32_16x16x32_bf16 v[110:113], v[154:157], v[194:197], v[110:113]
	v_mfma_f32_16x16x32_bf16 v[106:109], v[162:165], v[194:197], v[106:109]
	v_mfma_f32_16x16x32_bf16 v[94:97], v[154:157], v[202:205], v[94:97]
	v_mfma_f32_16x16x32_bf16 v[90:93], v[162:165], v[202:205], v[90:93]
	v_mfma_f32_16x16x32_bf16 v[78:81], v[154:157], v[210:213], v[78:81]
	v_mfma_f32_16x16x32_bf16 v[74:77], v[162:165], v[210:213], v[74:77]
	v_mfma_f32_16x16x32_bf16 v[118:121], v[166:169], v[182:185], v[118:121]
	v_mfma_f32_16x16x32_bf16 v[114:117], v[174:177], v[182:185], v[114:117]
	v_mfma_f32_16x16x32_bf16 v[102:105], v[166:169], v[190:193], v[102:105]
	v_mfma_f32_16x16x32_bf16 v[98:101], v[174:177], v[190:193], v[98:101]
	v_mfma_f32_16x16x32_bf16 v[86:89], v[166:169], v[198:201], v[86:89]
	v_mfma_f32_16x16x32_bf16 v[82:85], v[174:177], v[198:201], v[82:85]
	v_mfma_f32_16x16x32_bf16 v[70:73], v[166:169], v[206:209], v[70:73]
	v_mfma_f32_16x16x32_bf16 v[66:69], v[174:177], v[206:209], v[66:69]
	v_mfma_f32_16x16x32_bf16 v[118:121], v[170:173], v[186:189], v[118:121]
	v_mfma_f32_16x16x32_bf16 v[114:117], v[178:181], v[186:189], v[114:117]
	v_mfma_f32_16x16x32_bf16 v[102:105], v[170:173], v[194:197], v[102:105]
	v_mfma_f32_16x16x32_bf16 v[98:101], v[178:181], v[194:197], v[98:101]
	v_mfma_f32_16x16x32_bf16 v[86:89], v[170:173], v[202:205], v[86:89]
	v_mfma_f32_16x16x32_bf16 v[82:85], v[178:181], v[202:205], v[82:85]
	v_mfma_f32_16x16x32_bf16 v[70:73], v[170:173], v[210:213], v[70:73]
	v_mfma_f32_16x16x32_bf16 v[66:69], v[178:181], v[210:213], v[66:69]
	s_barrier
	s_add_i32 s6, s95, s50
	s_mov_b32 m0, s6
	ds_read_b128 v[182:185], v148 offset:16384
	ds_read_b128 v[186:189], v148 offset:17408
	ds_read_b128 v[190:193], v148 offset:18432
	ds_read_b128 v[194:197], v148 offset:19456
	global_load_lds_dwordx4 v134, s[16:17]
	s_add_i32 m0, s6, 0x2000
	s_add_u32 s6, s16, 0x100000
	s_addc_u32 s7, s17, 0
	s_add_i32 s95, vcc_lo, s50
	global_load_lds_dwordx4 v130, s[16:17]
	s_mov_b32 m0, s95
	ds_read_b128 v[210:213], v148 offset:23552
	global_load_lds_dwordx4 v134, s[6:7]
	s_add_i32 m0, s95, 0x2000
	ds_read_b128 v[206:209], v148 offset:22528
	global_load_lds_dwordx4 v130, s[6:7]
	s_mov_b32 m0, s69
	ds_read_b128 v[202:205], v148 offset:21504
	global_load_lds_dwordx4 v136, s[42:43]
	s_mov_b32 m0, s72
	ds_read_b128 v[198:201], v148 offset:20480
	global_load_lds_dwordx4 v132, s[42:43]
	s_waitcnt vmcnt(8)
	s_waitcnt lgkmcnt(0)
	s_nop 0
	s_barrier
	v_mfma_f32_16x16x32_bf16 v[62:65], v[150:153], v[182:185], v[62:65]
	v_mfma_f32_16x16x32_bf16 v[58:61], v[158:161], v[182:185], v[58:61]
	v_mfma_f32_16x16x32_bf16 v[46:49], v[150:153], v[190:193], v[46:49]
	v_mfma_f32_16x16x32_bf16 v[42:45], v[158:161], v[190:193], v[42:45]
	v_mfma_f32_16x16x32_bf16 v[30:33], v[150:153], v[198:201], v[30:33]
	v_mfma_f32_16x16x32_bf16 v[26:29], v[158:161], v[198:201], v[26:29]
	v_mfma_f32_16x16x32_bf16 v[12:15], v[150:153], v[206:209], v[12:15]
	v_mfma_f32_16x16x32_bf16 v[8:11], v[158:161], v[206:209], v[8:11]
	v_mfma_f32_16x16x32_bf16 v[62:65], v[154:157], v[186:189], v[62:65]
	v_mfma_f32_16x16x32_bf16 v[58:61], v[162:165], v[186:189], v[58:61]
	v_mfma_f32_16x16x32_bf16 v[46:49], v[154:157], v[194:197], v[46:49]
	v_mfma_f32_16x16x32_bf16 v[42:45], v[162:165], v[194:197], v[42:45]
	v_mfma_f32_16x16x32_bf16 v[30:33], v[154:157], v[202:205], v[30:33]
	v_mfma_f32_16x16x32_bf16 v[26:29], v[162:165], v[202:205], v[26:29]
	v_mfma_f32_16x16x32_bf16 v[12:15], v[154:157], v[210:213], v[12:15]
	v_mfma_f32_16x16x32_bf16 v[8:11], v[162:165], v[210:213], v[8:11]
	v_mfma_f32_16x16x32_bf16 v[54:57], v[166:169], v[182:185], v[54:57]
	v_mfma_f32_16x16x32_bf16 v[50:53], v[174:177], v[182:185], v[50:53]
	v_mfma_f32_16x16x32_bf16 v[38:41], v[166:169], v[190:193], v[38:41]
	v_mfma_f32_16x16x32_bf16 v[34:37], v[174:177], v[190:193], v[34:37]
	v_mfma_f32_16x16x32_bf16 v[22:25], v[166:169], v[198:201], v[22:25]
	v_mfma_f32_16x16x32_bf16 v[18:21], v[174:177], v[198:201], v[18:21]
	v_mfma_f32_16x16x32_bf16 v[4:7], v[166:169], v[206:209], v[4:7]
	v_mfma_f32_16x16x32_bf16 v[0:3], v[174:177], v[206:209], v[0:3]
	v_mfma_f32_16x16x32_bf16 v[54:57], v[170:173], v[186:189], v[54:57]
	v_mfma_f32_16x16x32_bf16 v[50:53], v[178:181], v[186:189], v[50:53]
	v_mfma_f32_16x16x32_bf16 v[38:41], v[170:173], v[194:197], v[38:41]
	v_mfma_f32_16x16x32_bf16 v[34:37], v[178:181], v[194:197], v[34:37]
	v_mfma_f32_16x16x32_bf16 v[22:25], v[170:173], v[202:205], v[22:25]
	v_mfma_f32_16x16x32_bf16 v[18:21], v[178:181], v[202:205], v[18:21]
	v_mfma_f32_16x16x32_bf16 v[4:7], v[170:173], v[210:213], v[4:7]
	v_mfma_f32_16x16x32_bf16 v[0:3], v[178:181], v[210:213], v[0:3]
	s_barrier
; #define PG8_STAGEA(bufoff, gbase, voff) PG8_STAGE_X(bufoff, gbase, voff, AUXA)
; #define PG8_STAGEB(bufoff, gbase, voff) PG8_STAGE_X(bufoff, gbase, voff, AUXB)
; #define PG8_LDA(dst, b, h) do { _Pragma("unroll") for (int m = 0; m < 4; ++m) _Pragma("unroll") for (int k = 0; k < 2; ++k) dst[m][k] = *(const PG8_LAS bf16x8*)(lds + PG8_SA(b, h) + aoff + m * 2048 + k * 1024); } while (0)
; #define PG8_LDB(dst, b, h) do { _Pragma("unroll") for (int n = 0; n < 2; ++n) _Pragma("unroll") for (int k = 0; k < 2; ++k) dst[n][k] = *(const PG8_LAS bf16x8*)(lds + PG8_SB(b, h) + boff + n * 2048 + k * 1024); } while (0)
; #define PG8_MMA(ai, bj, At, Bt) do { if (GEMM_PRIO_MODE == 0) __builtin_amdgcn_s_setprio(1); PG8_MMA_LOOPS \
;         acc[ai][bj][m][n] = __builtin_amdgcn_mfma_f32_16x16x32_bf16(Bt[n][k], At[m][k], acc[ai][bj][m][n], 0, 0, 0); if (GEMM_PRIO_MODE == 0) __builtin_amdgcn_s_setprio(0); } while (0)
; #define PG8_WAIT_V(n) asm volatile("s_waitcnt vmcnt(" #n ")" ::: "memory")
; #define PG8_WAIT_L(n) asm volatile("s_waitcnt lgkmcnt(" #n ")" ::: "memory")
; #define PG8_BAR __builtin_amdgcn_s_barrier()
; #define PG8_SCHED __builtin_amdgcn_sched_barrier(0)
;     ...
;         for (int t = t0; t < nt; t += 2) {
;             const bool last = (t == nt - 2);
;             const char* a1 = cA + (size_t)(t + 1) * kstepA;
;             const char* a2 = last ? nA : cA + (size_t)(t + 2) * kstepA; const char* b2 = last ? nB : cB + (size_t)(t + 2) * kstepB;
;     ...
;             PG8_LDB(B0, 1, 0); PG8_LDB(B1, 1, 1); PG8_SCHED; PG8_LDA(At, 1, 0); PG8_STAGEA(PG8_SA(0, 1), a2 + hstepA, voffA);
;             PG8_WAIT_V(8); PG8_WAIT_L(0); PG8_BAR; PG8_MMA(0, 0, At, B0); PG8_MMA(0, 1, At, B1); PG8_BAR; PG8_SCHED;
;             PG8_LDA(At, 1, 1); PG8_STAGEB(PG8_SB(1, 0), b3, voffB); PG8_STAGEB(PG8_SB(1, 1), b3 + hstepB, voffB); PG8_STAGEA(PG8_SA(1, 0), a3, voffA);
;             PG8_WAIT_V(8); PG8_WAIT_L(0); PG8_BAR; PG8_MMA(1, 0, At, B0); PG8_MMA(1, 1, At, B1); PG8_BAR; PG8_SCHED;
	s_add_i32 s95, 0, 0x18000
	s_add_i32 vcc_lo, 0, 0x1c000
	ds_read_b128 v[150:153], v222 offset:32768
	ds_read_b128 v[154:157], v222 offset:33792
	ds_read_b128 v[158:161], v222 offset:34816
	ds_read_b128 v[162:165], v222 offset:35840
	ds_read_b128 v[166:169], v222 offset:49152
	ds_read_b128 v[170:173], v222 offset:50176
	ds_read_b128 v[174:177], v222 offset:51200
	ds_read_b128 v[178:181], v222 offset:52224
	s_add_u32 s6, s42, 0x100000
	s_addc_u32 s7, s43, 0
	s_mov_b32 m0, s73
	ds_read_b128 v[182:185], v148 offset:32768
	ds_read_b128 v[186:189], v148 offset:33792
	ds_read_b128 v[190:193], v148 offset:34816
	ds_read_b128 v[194:197], v148 offset:35840
	ds_read_b128 v[198:201], v148 offset:36864
	ds_read_b128 v[202:205], v148 offset:37888
	ds_read_b128 v[206:209], v148 offset:38912
	global_load_lds_dwordx4 v136, s[6:7]
	s_mov_b32 m0, s82
	ds_read_b128 v[210:213], v148 offset:39936
	global_load_lds_dwordx4 v132, s[6:7]
	s_waitcnt vmcnt(8)
	s_waitcnt lgkmcnt(0)
	s_nop 0
	s_barrier
	v_mfma_f32_16x16x32_bf16 v[126:129], v[150:153], v[182:185], v[126:129]
	v_mfma_f32_16x16x32_bf16 v[122:125], v[158:161], v[182:185], v[122:125]
	v_mfma_f32_16x16x32_bf16 v[110:113], v[150:153], v[190:193], v[110:113]
	v_mfma_f32_16x16x32_bf16 v[106:109], v[158:161], v[190:193], v[106:109]
	v_mfma_f32_16x16x32_bf16 v[94:97], v[150:153], v[198:201], v[94:97]
	v_mfma_f32_16x16x32_bf16 v[90:93], v[158:161], v[198:201], v[90:93]
	v_mfma_f32_16x16x32_bf16 v[78:81], v[150:153], v[206:209], v[78:81]
	v_mfma_f32_16x16x32_bf16 v[74:77], v[158:161], v[206:209], v[74:77]
	v_mfma_f32_16x16x32_bf16 v[126:129], v[154:157], v[186:189], v[126:129]
	v_mfma_f32_16x16x32_bf16 v[122:125], v[162:165], v[186:189], v[122:125]
	v_mfma_f32_16x16x32_bf16 v[110:113], v[154:157], v[194:197], v[110:113]
	v_mfma_f32_16x16x32_bf16 v[106:109], v[162:165], v[194:197], v[106:109]
	v_mfma_f32_16x16x32_bf16 v[94:97], v[154:157], v[202:205], v[94:97]
	v_mfma_f32_16x16x32_bf16 v[90:93], v[162:165], v[202:205], v[90:93]
	v_mfma_f32_16x16x32_bf16 v[78:81], v[154:157], v[210:213], v[78:81]
	v_mfma_f32_16x16x32_bf16 v[74:77], v[162:165], v[210:213], v[74:77]
	v_mfma_f32_16x16x32_bf16 v[118:121], v[166:169], v[182:185], v[118:121]
	v_mfma_f32_16x16x32_bf16 v[114:117], v[174:177], v[182:185], v[114:117]
	v_mfma_f32_16x16x32_bf16 v[102:105], v[166:169], v[190:193], v[102:105]
	v_mfma_f32_16x16x32_bf16 v[98:101], v[174:177], v[190:193], v[98:101]
	v_mfma_f32_16x16x32_bf16 v[86:89], v[166:169], v[198:201], v[86:89]
	v_mfma_f32_16x16x32_bf16 v[82:85], v[174:177], v[198:201], v[82:85]
	v_mfma_f32_16x16x32_bf16 v[70:73], v[166:169], v[206:209], v[70:73]
	v_mfma_f32_16x16x32_bf16 v[66:69], v[174:177], v[206:209], v[66:69]
	v_mfma_f32_16x16x32_bf16 v[118:121], v[170:173], v[186:189], v[118:121]
	v_mfma_f32_16x16x32_bf16 v[114:117], v[178:181], v[186:189], v[114:117]
	v_mfma_f32_16x16x32_bf16 v[102:105], v[170:173], v[194:197], v[102:105]
	v_mfma_f32_16x16x32_bf16 v[98:101], v[178:181], v[194:197], v[98:101]
	v_mfma_f32_16x16x32_bf16 v[86:89], v[170:173], v[202:205], v[86:89]
	v_mfma_f32_16x16x32_bf16 v[82:85], v[178:181], v[202:205], v[82:85]
	v_mfma_f32_16x16x32_bf16 v[70:73], v[170:173], v[210:213], v[70:73]
	v_mfma_f32_16x16x32_bf16 v[66:69], v[178:181], v[210:213], v[66:69]
	s_barrier
	s_add_i32 s6, s95, s50
	s_mov_b32 m0, s6
	ds_read_b128 v[182:185], v148 offset:49152
	ds_read_b128 v[186:189], v148 offset:50176
	ds_read_b128 v[190:193], v148 offset:51200
	ds_read_b128 v[194:197], v148 offset:52224
	ds_read_b128 v[198:201], v148 offset:53248
	s_add_u32 s100, s16, 0x80
	s_addc_u32 s101, s17, 0
	global_load_lds_dwordx4 v134, s[100:101]
	s_add_i32 m0, s6, 0x2000
	s_add_u32 s6, s16, 0x100080
	s_addc_u32 s7, s17, 0
	s_add_i32 s16, vcc_lo, s50
	global_load_lds_dwordx4 v130, s[100:101]
	s_mov_b32 m0, s16
	ds_read_b128 v[210:213], v148 offset:56320
	global_load_lds_dwordx4 v134, s[6:7]
	s_add_i32 m0, s16, 0x2000
	ds_read_b128 v[206:209], v148 offset:55296
	global_load_lds_dwordx4 v130, s[6:7]
	s_mov_b32 m0, s83
	s_nop 0
	s_add_u32 s100, s42, 0x80
	s_addc_u32 s101, s43, 0
	global_load_lds_dwordx4 v136, s[100:101]
	s_mov_b32 m0, s90
	ds_read_b128 v[202:205], v148 offset:54272
	global_load_lds_dwordx4 v132, s[100:101]
	s_waitcnt vmcnt(8)
	s_waitcnt lgkmcnt(0)
	s_barrier
	v_mfma_f32_16x16x32_bf16 v[62:65], v[150:153], v[182:185], v[62:65]
	v_mfma_f32_16x16x32_bf16 v[58:61], v[158:161], v[182:185], v[58:61]
	v_mfma_f32_16x16x32_bf16 v[46:49], v[150:153], v[190:193], v[46:49]
	v_mfma_f32_16x16x32_bf16 v[42:45], v[158:161], v[190:193], v[42:45]
	v_mfma_f32_16x16x32_bf16 v[30:33], v[150:153], v[198:201], v[30:33]
	v_mfma_f32_16x16x32_bf16 v[26:29], v[158:161], v[198:201], v[26:29]
	v_mfma_f32_16x16x32_bf16 v[12:15], v[150:153], v[206:209], v[12:15]
	v_mfma_f32_16x16x32_bf16 v[8:11], v[158:161], v[206:209], v[8:11]
	v_mfma_f32_16x16x32_bf16 v[62:65], v[154:157], v[186:189], v[62:65]
	v_mfma_f32_16x16x32_bf16 v[58:61], v[162:165], v[186:189], v[58:61]
	v_mfma_f32_16x16x32_bf16 v[46:49], v[154:157], v[194:197], v[46:49]
	v_mfma_f32_16x16x32_bf16 v[42:45], v[162:165], v[194:197], v[42:45]
	v_mfma_f32_16x16x32_bf16 v[30:33], v[154:157], v[202:205], v[30:33]
	v_mfma_f32_16x16x32_bf16 v[26:29], v[162:165], v[202:205], v[26:29]
	v_mfma_f32_16x16x32_bf16 v[12:15], v[154:157], v[210:213], v[12:15]
	v_mfma_f32_16x16x32_bf16 v[8:11], v[162:165], v[210:213], v[8:11]
	v_mfma_f32_16x16x32_bf16 v[54:57], v[166:169], v[182:185], v[54:57]
	v_mfma_f32_16x16x32_bf16 v[50:53], v[174:177], v[182:185], v[50:53]
	v_mfma_f32_16x16x32_bf16 v[38:41], v[166:169], v[190:193], v[38:41]
	v_mfma_f32_16x16x32_bf16 v[34:37], v[174:177], v[190:193], v[34:37]
	v_mfma_f32_16x16x32_bf16 v[22:25], v[166:169], v[198:201], v[22:25]
	v_mfma_f32_16x16x32_bf16 v[18:21], v[174:177], v[198:201], v[18:21]
	v_mfma_f32_16x16x32_bf16 v[4:7], v[166:169], v[206:209], v[4:7]
	v_mfma_f32_16x16x32_bf16 v[0:3], v[174:177], v[206:209], v[0:3]
	v_mfma_f32_16x16x32_bf16 v[54:57], v[170:173], v[186:189], v[54:57]
	v_mfma_f32_16x16x32_bf16 v[50:53], v[178:181], v[186:189], v[50:53]
	v_mfma_f32_16x16x32_bf16 v[38:41], v[170:173], v[194:197], v[38:41]
	v_mfma_f32_16x16x32_bf16 v[34:37], v[178:181], v[194:197], v[34:37]
	v_mfma_f32_16x16x32_bf16 v[22:25], v[170:173], v[202:205], v[22:25]
	v_mfma_f32_16x16x32_bf16 v[18:21], v[178:181], v[202:205], v[18:21]
	v_mfma_f32_16x16x32_bf16 v[4:7], v[170:173], v[210:213], v[4:7]
	v_mfma_f32_16x16x32_bf16 v[0:3], v[178:181], v[210:213], v[0:3]
	s_barrier
	s_add_i32 s39, s39, 2
	s_add_u32 s40, s40, 0x100
	s_addc_u32 s41, s41, 0
	s_add_u32 s12, s12, 0x100
	s_addc_u32 s13, s13, 0
	s_cmp_gt_u32 s39, 61
	s_cbranch_scc0 .LBB0_712
	s_and_b64 vcc, exec, s[18:19]
	s_cbranch_vccz .LBB0_715
	s_barrier

; #define PG8_STAGEA(bufoff, gbase, voff) PG8_STAGE_X(bufoff, gbase, voff, AUXA)
; #define PG8_STR(x) PG8_STR2(x)
;     ...
;         const bool has_next = S.next(ui + 1, nxt);
;         const char* nA = has_next ? (const char*)g.A + (size_t)nxt.pm * tstepA : cA; const char* nB = has_next ? (const char*)g.Bt + (size_t)nxt.pn * tstepB : cB;
;         int t0 = 0;
;         if constexpr (SP2 && GEMM_RELAX == 1) { if (ui > 0) {
;             const char* a1 = cA + kstepA; const char* a2 = cA + 2 * kstepA; const char* b2 = cB + 2 * kstepB; const char* a3 = a2 + kstepA; const char* b3 = b2 + kstepB;
;             PG8_LDB(B0, 0, 0); PG8_LDB(B1, 0, 1); PG8_SCHED; PG8_LDA(At, 0, 0); PG8_STAGEA(PG8_SA(1, 1), a1 + hstepA, voffA);
;             PG8_WAIT_V(24); PG8_WAIT_L(0); PG8_BAR; PG8_MMA(0, 0, At, B0); PG8_MMA(0, 1, At, B1); PG8_BAR; PG8_SCHED;
;             PG8_LDA(At, 0, 1); PG8_STAGEB(PG8_SB(0, 0), b2, voffB); PG8_STAGEB(PG8_SB(0, 1), b2 + hstepB, voffB); PG8_STAGEA(PG8_SA(0, 0), a2, voffA);
;             PG8_WAIT_V(24); PG8_WAIT_L(0); PG8_BAR; PG8_MMA(1, 0, At, B0); PG8_MMA(1, 1, At, B1); PG8_BAR; PG8_SCHED;
;             PG8_LDB(B0, 1, 0); PG8_LDB(B1, 1, 1); PG8_SCHED; PG8_LDA(At, 1, 0); PG8_STAGEA(PG8_SA(0, 1), a2 + hstepA, voffA);
;             PG8_WAIT_V(8); PG8_WAIT_L(0); PG8_BAR; PG8_MMA(0, 0, At, B0); PG8_MMA(0, 1, At, B1); PG8_BAR; PG8_SCHED;
;             PG8_LDA(At, 1, 1); PG8_STAGEB(PG8_SB(1, 0), b3, voffB); PG8_STAGEB(PG8_SB(1, 1), b3 + hstepB, voffB); PG8_STAGEA(PG8_SA(1, 0), a3, voffA);
;             PG8_WAIT_V(8); PG8_WAIT_L(0); PG8_BAR; PG8_MMA(1, 0, At, B0); PG8_MMA(1, 1, At, B1); PG8_BAR; PG8_SCHED;
;             t0 = 2; } }
;     ...
;         asm volatile(".p2align " PG8_STR(GEMM_LOOP_ALIGN) ::: "memory");
;     ...
;         for (int t = t0; t < nt; t += 2) {
;             const bool last = (t == nt - 2);
;             const char* a1 = cA + (size_t)(t + 1) * kstepA;
;             const char* a2 = last ? nA : cA + (size_t)(t + 2) * kstepA; const char* b2 = last ? nB : cB + (size_t)(t + 2) * kstepB;
;             const char* a3 = a2 + kstepA; const char* b3 = b2 + kstepB;
;             if (last && has_next) S.a_ready(nxt);
;             if constexpr (SP2) {
;             PG8_LDB(B0, 0, 0); PG8_LDB(B1, 0, 1); PG8_SCHED; PG8_LDA(At, 0, 0); PG8_STAGEA(PG8_SA(1, 1), a1 + hstepA, voffA);
;     ...
;             const int relax = __builtin_amdgcn_readfirstlane((t == 0 && ui > 0) ? 1 : 0);
.LBB0_847:
	s_ashr_i32 s11, s10, 31
	s_lshl_b64 s[18:19], s[10:11], 23
	s_add_u32 s18, s62, s18
	s_addc_u32 s19, s63, s19
	s_and_b64 s[22:23], s[20:21], exec
	s_cselect_b32 s11, s19, s1
	s_cselect_b32 s73, s18, s0
	s_ashr_i32 s15, s14, 31
	s_lshl_b64 s[22:23], s[14:15], 23
	s_add_u32 s22, s12, s22
	s_addc_u32 s23, s13, s23
	s_and_b64 s[24:25], s[20:21], exec
	s_cselect_b32 s15, s23, s17
	s_cselect_b32 s78, s22, s16
	s_add_u32 s24, s0, 0xc000
	s_addc_u32 s25, s1, 0
	s_add_u32 s0, s16, 0x10000
	s_addc_u32 s1, s17, 0
	s_mov_b32 s82, -2
	s_waitcnt lgkmcnt(0)
	s_add_u32 s16, s24, 0x4000
	s_addc_u32 s17, s25, 0
	s_cmpk_eq_i32 s82, 0xfc
	s_cselect_b32 s36, s73, s16
	s_cselect_b32 s37, s11, s17
	s_cselect_b32 s16, s78, s0
	s_cselect_b32 s17, s15, s1
	s_add_u32 s26, s36, 0x8000
	s_addc_u32 s27, s37, 0
	s_add_i32 s83, 0, 0x10000
	s_add_i32 s94, 0, 0x14000
	v_add_u32_e32 v152, s83, v157
	v_add_u32_e32 v174, s94, v157
	ds_read_b128 v[130:133], v152
	ds_read_b128 v[134:137], v152 offset:1024
	ds_read_b128 v[148:151], v152 offset:2048
	ds_read_b128 v[152:155], v152 offset:3072
	ds_read_b128 v[162:165], v174
	ds_read_b128 v[166:169], v174 offset:1024
	ds_read_b128 v[170:173], v174 offset:2048
	ds_read_b128 v[174:177], v174 offset:3072
	v_lshl_add_u64 v[210:211], s[24:25], 0, v[144:145]
	s_add_i32 m0, s39, 0xc000
	ds_read_b128 v[178:181], v161
	ds_read_b128 v[182:185], v161 offset:1024
	ds_read_b128 v[186:189], v161 offset:2048
	ds_read_b128 v[190:193], v161 offset:3072
	ds_read_b128 v[194:197], v161 offset:4096
	ds_read_b128 v[198:201], v161 offset:5120
	ds_read_b128 v[202:205], v161 offset:6144
	ds_read_b128 v[206:209], v161 offset:7168
	global_load_lds_dwordx4 v[210:211], off
	v_lshl_add_u64 v[210:211], s[24:25], 0, v[146:147]
	s_add_i32 m0, s39, 0xe000
	s_nop 0
	global_load_lds_dwordx4 v[210:211], off
	s_waitcnt vmcnt(8)
	s_waitcnt lgkmcnt(0)
	s_nop 0
	s_nop 0
	s_barrier
	v_mfma_f32_16x16x32_bf16 v[126:129], v[130:133], v[178:181], 0
	v_mfma_f32_16x16x32_bf16 v[122:125], v[148:151], v[178:181], 0
	v_mfma_f32_16x16x32_bf16 v[110:113], v[130:133], v[186:189], 0
	v_mfma_f32_16x16x32_bf16 v[106:109], v[148:151], v[186:189], 0
	v_mfma_f32_16x16x32_bf16 v[94:97], v[130:133], v[194:197], 0
	v_mfma_f32_16x16x32_bf16 v[90:93], v[148:151], v[194:197], 0
	v_mfma_f32_16x16x32_bf16 v[78:81], v[130:133], v[202:205], 0
	v_mfma_f32_16x16x32_bf16 v[74:77], v[148:151], v[202:205], 0
	v_mfma_f32_16x16x32_bf16 v[126:129], v[134:137], v[182:185], v[126:129]
	v_mfma_f32_16x16x32_bf16 v[122:125], v[152:155], v[182:185], v[122:125]
	v_mfma_f32_16x16x32_bf16 v[110:113], v[134:137], v[190:193], v[110:113]
	v_mfma_f32_16x16x32_bf16 v[106:109], v[152:155], v[190:193], v[106:109]
	v_mfma_f32_16x16x32_bf16 v[94:97], v[134:137], v[198:201], v[94:97]
	v_mfma_f32_16x16x32_bf16 v[90:93], v[152:155], v[198:201], v[90:93]
	v_mfma_f32_16x16x32_bf16 v[78:81], v[134:137], v[206:209], v[78:81]
	v_mfma_f32_16x16x32_bf16 v[74:77], v[152:155], v[206:209], v[74:77]
	v_mfma_f32_16x16x32_bf16 v[118:121], v[162:165], v[178:181], 0
	v_mfma_f32_16x16x32_bf16 v[114:117], v[170:173], v[178:181], 0
	v_mfma_f32_16x16x32_bf16 v[102:105], v[162:165], v[186:189], 0
	v_mfma_f32_16x16x32_bf16 v[98:101], v[170:173], v[186:189], 0
	v_mfma_f32_16x16x32_bf16 v[86:89], v[162:165], v[194:197], 0
	v_mfma_f32_16x16x32_bf16 v[82:85], v[170:173], v[194:197], 0
	v_mfma_f32_16x16x32_bf16 v[70:73], v[162:165], v[202:205], 0
	v_mfma_f32_16x16x32_bf16 v[66:69], v[170:173], v[202:205], 0
	v_mfma_f32_16x16x32_bf16 v[118:121], v[166:169], v[182:185], v[118:121]
	v_mfma_f32_16x16x32_bf16 v[114:117], v[174:177], v[182:185], v[114:117]
	v_mfma_f32_16x16x32_bf16 v[102:105], v[166:169], v[190:193], v[102:105]
	v_mfma_f32_16x16x32_bf16 v[98:101], v[174:177], v[190:193], v[98:101]
	v_mfma_f32_16x16x32_bf16 v[86:89], v[166:169], v[198:201], v[86:89]
	v_mfma_f32_16x16x32_bf16 v[82:85], v[174:177], v[198:201], v[82:85]
	v_mfma_f32_16x16x32_bf16 v[70:73], v[166:169], v[206:209], v[70:73]
	v_mfma_f32_16x16x32_bf16 v[66:69], v[174:177], v[206:209], v[66:69]
	s_barrier
	s_add_i32 s83, s83, s38
	v_lshl_add_u64 v[210:211], s[16:17], 0, v[16:17]
	s_mov_b32 m0, s83
	ds_read_b128 v[178:181], v161 offset:16384
	ds_read_b128 v[182:185], v161 offset:17408
	ds_read_b128 v[186:189], v161 offset:18432
	ds_read_b128 v[190:193], v161 offset:19456
	ds_read_b128 v[194:197], v161 offset:20480
	ds_read_b128 v[198:201], v161 offset:21504
	ds_read_b128 v[202:205], v161 offset:22528
	ds_read_b128 v[206:209], v161 offset:23552
	global_load_lds_dwordx4 v[210:211], off
	s_add_i32 m0, s83, 0x2000
	s_add_u32 s90, s16, 0x4000
	v_lshl_add_u64 v[210:211], s[16:17], 0, v[138:139]
	s_addc_u32 s91, s17, 0
	s_add_i32 s83, s94, s38
	global_load_lds_dwordx4 v[210:211], off
	v_lshl_add_u64 v[210:211], s[90:91], 0, v[16:17]
	s_mov_b32 m0, s83
	s_nop 0
	global_load_lds_dwordx4 v[210:211], off
	v_lshl_add_u64 v[210:211], s[90:91], 0, v[138:139]
	s_add_i32 m0, s83, 0x2000
	s_nop 0
	global_load_lds_dwordx4 v[210:211], off
	v_lshl_add_u64 v[210:211], s[36:37], 0, v[142:143]
	s_mov_b32 m0, s39
	s_nop 0
	global_load_lds_dwordx4 v[210:211], off
	v_lshl_add_u64 v[210:211], s[36:37], 0, v[140:141]
	s_mov_b32 m0, s40
	s_nop 0
	global_load_lds_dwordx4 v[210:211], off
	s_waitcnt vmcnt(8)
	s_waitcnt lgkmcnt(0)
	s_nop 0
	s_nop 0
	s_nop 0
	s_barrier
; #define PG8_STAGEA(bufoff, gbase, voff) PG8_STAGE_X(bufoff, gbase, voff, AUXA)
; #define PG8_STAGEB(bufoff, gbase, voff) PG8_STAGE_X(bufoff, gbase, voff, AUXB)
; #define PG8_LDA(dst, b, h) do { _Pragma("unroll") for (int m = 0; m < 4; ++m) _Pragma("unroll") for (int k = 0; k < 2; ++k) dst[m][k] = *(const PG8_LAS bf16x8*)(lds + PG8_SA(b, h) + aoff + m * 2048 + k * 1024); } while (0)
; #define PG8_LDB(dst, b, h) do { _Pragma("unroll") for (int n = 0; n < 2; ++n) _Pragma("unroll") for (int k = 0; k < 2; ++k) dst[n][k] = *(const PG8_LAS bf16x8*)(lds + PG8_SB(b, h) + boff + n * 2048 + k * 1024); } while (0)
; #define PG8_MMA(ai, bj, At, Bt) do { if (GEMM_PRIO_MODE == 0) __builtin_amdgcn_s_setprio(1); PG8_MMA_LOOPS \
;         acc[ai][bj][m][n] = __builtin_amdgcn_mfma_f32_16x16x32_bf16(Bt[n][k], At[m][k], acc[ai][bj][m][n], 0, 0, 0); if (GEMM_PRIO_MODE == 0) __builtin_amdgcn_s_setprio(0); } while (0)
; #define PG8_WAIT_V(n) asm volatile("s_waitcnt vmcnt(" #n ")" ::: "memory")
; #define PG8_WAIT_VR(n, nr, flag) asm volatile("s_cmp_eq_u32 %0, 0\n\ts_cbranch_scc1 .Lpg8s%=\n\ts_waitcnt vmcnt(" #nr ")\n\ts_branch .Lpg8d%=\n.Lpg8s%=:\n\ts_waitcnt vmcnt(" #n ")\n.Lpg8d%=:" :: "s"(flag) : "memory", "scc")
; #define PG8_WAIT_L(n) asm volatile("s_waitcnt lgkmcnt(" #n ")" ::: "memory")
; #define PG8_BAR __builtin_amdgcn_s_barrier()
; #define PG8_SCHED __builtin_amdgcn_sched_barrier(0)
;     ...
;             PG8_LDA(At, 0, 1); PG8_STAGEB(PG8_SB(0, 0), b2, voffB); PG8_STAGEB(PG8_SB(0, 1), b2 + hstepB, voffB); PG8_STAGEA(PG8_SA(0, 0), a2, voffA);
;     ...
;             PG8_WAIT_VR(8, 24, relax); PG8_WAIT_L(0); PG8_BAR; PG8_MMA(1, 0, At, B0); PG8_MMA(1, 1, At, B1); PG8_BAR; PG8_SCHED;
;     ...
;             PG8_WAIT_V(8); PG8_WAIT_L(0); PG8_BAR; PG8_MMA(1, 0, At, B0); PG8_MMA(1, 1, At, B1); PG8_BAR; PG8_SCHED;
;     ...
;             PG8_LDB(B0, 1, 0); PG8_LDB(B1, 1, 1); PG8_SCHED; PG8_LDA(At, 1, 0); PG8_STAGEA(PG8_SA(0, 1), a2 + hstepA, voffA);
;             PG8_WAIT_V(8); PG8_WAIT_L(0); PG8_BAR; PG8_MMA(0, 0, At, B0); PG8_MMA(0, 1, At, B1); PG8_BAR; PG8_SCHED;
;             PG8_LDA(At, 1, 1); PG8_STAGEB(PG8_SB(1, 0), b3, voffB); PG8_STAGEB(PG8_SB(1, 1), b3 + hstepB, voffB); PG8_STAGEA(PG8_SA(1, 0), a3, voffA);
;             PG8_WAIT_V(8); PG8_WAIT_L(0); PG8_BAR; PG8_MMA(1, 0, At, B0); PG8_MMA(1, 1, At, B1); PG8_BAR; PG8_SCHED;
	v_mfma_f32_16x16x32_bf16 v[62:65], v[130:133], v[178:181], 0
	v_mfma_f32_16x16x32_bf16 v[58:61], v[148:151], v[178:181], 0
	v_mfma_f32_16x16x32_bf16 v[46:49], v[130:133], v[186:189], 0
	v_mfma_f32_16x16x32_bf16 v[42:45], v[148:151], v[186:189], 0
	v_mfma_f32_16x16x32_bf16 v[30:33], v[130:133], v[194:197], 0
	v_mfma_f32_16x16x32_bf16 v[26:29], v[148:151], v[194:197], 0
	v_mfma_f32_16x16x32_bf16 v[12:15], v[130:133], v[202:205], 0
	v_mfma_f32_16x16x32_bf16 v[8:11], v[148:151], v[202:205], 0
	v_mfma_f32_16x16x32_bf16 v[62:65], v[134:137], v[182:185], v[62:65]
	v_mfma_f32_16x16x32_bf16 v[58:61], v[152:155], v[182:185], v[58:61]
	v_mfma_f32_16x16x32_bf16 v[46:49], v[134:137], v[190:193], v[46:49]
	v_mfma_f32_16x16x32_bf16 v[42:45], v[152:155], v[190:193], v[42:45]
	v_mfma_f32_16x16x32_bf16 v[30:33], v[134:137], v[198:201], v[30:33]
	v_mfma_f32_16x16x32_bf16 v[26:29], v[152:155], v[198:201], v[26:29]
	v_mfma_f32_16x16x32_bf16 v[12:15], v[134:137], v[206:209], v[12:15]
	v_mfma_f32_16x16x32_bf16 v[8:11], v[152:155], v[206:209], v[8:11]
	v_mfma_f32_16x16x32_bf16 v[54:57], v[162:165], v[178:181], 0
	v_mfma_f32_16x16x32_bf16 v[50:53], v[170:173], v[178:181], 0
	v_mfma_f32_16x16x32_bf16 v[38:41], v[162:165], v[186:189], 0
	v_mfma_f32_16x16x32_bf16 v[34:37], v[170:173], v[186:189], 0
	v_mfma_f32_16x16x32_bf16 v[22:25], v[162:165], v[194:197], 0
	v_mfma_f32_16x16x32_bf16 v[18:21], v[170:173], v[194:197], 0
	v_mfma_f32_16x16x32_bf16 v[4:7], v[162:165], v[202:205], 0
	v_mfma_f32_16x16x32_bf16 v[0:3], v[170:173], v[202:205], 0
	v_mfma_f32_16x16x32_bf16 v[54:57], v[166:169], v[182:185], v[54:57]
	v_mfma_f32_16x16x32_bf16 v[50:53], v[174:177], v[182:185], v[50:53]
	v_mfma_f32_16x16x32_bf16 v[38:41], v[166:169], v[190:193], v[38:41]
	v_mfma_f32_16x16x32_bf16 v[34:37], v[174:177], v[190:193], v[34:37]
	v_mfma_f32_16x16x32_bf16 v[22:25], v[166:169], v[198:201], v[22:25]
	v_mfma_f32_16x16x32_bf16 v[18:21], v[174:177], v[198:201], v[18:21]
	v_mfma_f32_16x16x32_bf16 v[4:7], v[166:169], v[206:209], v[4:7]
	v_mfma_f32_16x16x32_bf16 v[0:3], v[174:177], v[206:209], v[0:3]
	s_barrier
	s_add_i32 s83, 0, 0x18000
	s_add_i32 s90, 0, 0x1c000
	v_add_u32_e32 v152, s83, v157
	v_add_u32_e32 v174, s90, v157
	ds_read_b128 v[130:133], v152
	ds_read_b128 v[134:137], v152 offset:1024
	ds_read_b128 v[148:151], v152 offset:2048
	ds_read_b128 v[152:155], v152 offset:3072
	ds_read_b128 v[162:165], v174
	ds_read_b128 v[166:169], v174 offset:1024
	ds_read_b128 v[170:173], v174 offset:2048
	ds_read_b128 v[174:177], v174 offset:3072
	s_add_u32 s36, s36, 0x4000
	s_addc_u32 s37, s37, 0
	s_mov_b32 m0, s41
	v_lshl_add_u64 v[210:211], s[36:37], 0, v[142:143]
	ds_read_b128 v[178:181], v161 offset:32768
	ds_read_b128 v[182:185], v161 offset:33792
	ds_read_b128 v[186:189], v161 offset:34816
	ds_read_b128 v[190:193], v161 offset:35840
	ds_read_b128 v[194:197], v161 offset:36864
	ds_read_b128 v[198:201], v161 offset:37888
	ds_read_b128 v[202:205], v161 offset:38912
	ds_read_b128 v[206:209], v161 offset:39936
	global_load_lds_dwordx4 v[210:211], off
	v_lshl_add_u64 v[210:211], s[36:37], 0, v[140:141]
	s_mov_b32 m0, s42
	s_nop 0
	global_load_lds_dwordx4 v[210:211], off
	s_waitcnt vmcnt(8)
	s_waitcnt lgkmcnt(0)
	s_barrier
	v_mfma_f32_16x16x32_bf16 v[126:129], v[130:133], v[178:181], v[126:129]
	v_mfma_f32_16x16x32_bf16 v[122:125], v[148:151], v[178:181], v[122:125]
	v_mfma_f32_16x16x32_bf16 v[110:113], v[130:133], v[186:189], v[110:113]
	v_mfma_f32_16x16x32_bf16 v[106:109], v[148:151], v[186:189], v[106:109]
	v_mfma_f32_16x16x32_bf16 v[94:97], v[130:133], v[194:197], v[94:97]
	v_mfma_f32_16x16x32_bf16 v[90:93], v[148:151], v[194:197], v[90:93]
	v_mfma_f32_16x16x32_bf16 v[78:81], v[130:133], v[202:205], v[78:81]
	v_mfma_f32_16x16x32_bf16 v[74:77], v[148:151], v[202:205], v[74:77]
	v_mfma_f32_16x16x32_bf16 v[126:129], v[134:137], v[182:185], v[126:129]
	v_mfma_f32_16x16x32_bf16 v[122:125], v[152:155], v[182:185], v[122:125]
	v_mfma_f32_16x16x32_bf16 v[110:113], v[134:137], v[190:193], v[110:113]
	v_mfma_f32_16x16x32_bf16 v[106:109], v[152:155], v[190:193], v[106:109]
	v_mfma_f32_16x16x32_bf16 v[94:97], v[134:137], v[198:201], v[94:97]
	v_mfma_f32_16x16x32_bf16 v[90:93], v[152:155], v[198:201], v[90:93]
	v_mfma_f32_16x16x32_bf16 v[78:81], v[134:137], v[206:209], v[78:81]
	v_mfma_f32_16x16x32_bf16 v[74:77], v[152:155], v[206:209], v[74:77]
	v_mfma_f32_16x16x32_bf16 v[118:121], v[162:165], v[178:181], v[118:121]
	v_mfma_f32_16x16x32_bf16 v[114:117], v[170:173], v[178:181], v[114:117]
	v_mfma_f32_16x16x32_bf16 v[102:105], v[162:165], v[186:189], v[102:105]
	v_mfma_f32_16x16x32_bf16 v[98:101], v[170:173], v[186:189], v[98:101]
	v_mfma_f32_16x16x32_bf16 v[86:89], v[162:165], v[194:197], v[86:89]
	v_mfma_f32_16x16x32_bf16 v[82:85], v[170:173], v[194:197], v[82:85]
	v_mfma_f32_16x16x32_bf16 v[70:73], v[162:165], v[202:205], v[70:73]
	v_mfma_f32_16x16x32_bf16 v[66:69], v[170:173], v[202:205], v[66:69]
	v_mfma_f32_16x16x32_bf16 v[118:121], v[166:169], v[182:185], v[118:121]
	v_mfma_f32_16x16x32_bf16 v[114:117], v[174:177], v[182:185], v[114:117]
	v_mfma_f32_16x16x32_bf16 v[102:105], v[166:169], v[190:193], v[102:105]
	v_mfma_f32_16x16x32_bf16 v[98:101], v[174:177], v[190:193], v[98:101]
	v_mfma_f32_16x16x32_bf16 v[86:89], v[166:169], v[198:201], v[86:89]
	v_mfma_f32_16x16x32_bf16 v[82:85], v[174:177], v[198:201], v[82:85]
	v_mfma_f32_16x16x32_bf16 v[70:73], v[166:169], v[206:209], v[70:73]
	v_mfma_f32_16x16x32_bf16 v[66:69], v[174:177], v[206:209], v[66:69]
	s_barrier
; #define PG8_STAGEA(bufoff, gbase, voff) PG8_STAGE_X(bufoff, gbase, voff, AUXA)
; #define PG8_STAGEB(bufoff, gbase, voff) PG8_STAGE_X(bufoff, gbase, voff, AUXB)
; #define PG8_LDA(dst, b, h) do { _Pragma("unroll") for (int m = 0; m < 4; ++m) _Pragma("unroll") for (int k = 0; k < 2; ++k) dst[m][k] = *(const PG8_LAS bf16x8*)(lds + PG8_SA(b, h) + aoff + m * 2048 + k * 1024); } while (0)
; #define PG8_WAIT_V(n) asm volatile("s_waitcnt vmcnt(" #n ")" ::: "memory")
; #define PG8_WAIT_L(n) asm volatile("s_waitcnt lgkmcnt(" #n ")" ::: "memory")
;     ...
;         for (int t = t0; t < nt; t += 2) {
;             const bool last = (t == nt - 2);
;             const char* a1 = cA + (size_t)(t + 1) * kstepA;
;             const char* a2 = last ? nA : cA + (size_t)(t + 2) * kstepA; const char* b2 = last ? nB : cB + (size_t)(t + 2) * kstepB;
;             const char* a3 = a2 + kstepA; const char* b3 = b2 + kstepB;
;             if (last && has_next) S.a_ready(nxt);
;             if constexpr (SP2) {
;             PG8_LDB(B0, 0, 0); PG8_LDB(B1, 0, 1); PG8_SCHED; PG8_LDA(At, 0, 0); PG8_STAGEA(PG8_SA(1, 1), a1 + hstepA, voffA);
;     ...
;             const int relax = __builtin_amdgcn_readfirstlane((t == 0 && ui > 0) ? 1 : 0);
;             PG8_WAIT_VR(8, 24, relax); PG8_WAIT_L(0); PG8_BAR; PG8_MMA(0, 0, At, B0); PG8_MMA(0, 1, At, B1); PG8_BAR; PG8_SCHED;
;     ...
;             PG8_WAIT_V(8); PG8_WAIT_L(0); PG8_BAR; PG8_MMA(0, 0, At, B0); PG8_MMA(0, 1, At, B1); PG8_BAR; PG8_SCHED;
;     ...
;             PG8_LDA(At, 0, 1); PG8_STAGEB(PG8_SB(0, 0), b2, voffB); PG8_STAGEB(PG8_SB(0, 1), b2 + hstepB, voffB); PG8_STAGEA(PG8_SA(0, 0), a2, voffA);
;     ...
;             PG8_WAIT_VR(8, 24, relax); PG8_WAIT_L(0); PG8_BAR; PG8_MMA(1, 0, At, B0); PG8_MMA(1, 1, At, B1); PG8_BAR; PG8_SCHED;
;     ...
;             PG8_WAIT_V(8); PG8_WAIT_L(0); PG8_BAR; PG8_MMA(1, 0, At, B0); PG8_MMA(1, 1, At, B1); PG8_BAR; PG8_SCHED;
;     ...
;             PG8_LDB(B0, 1, 0); PG8_LDB(B1, 1, 1); PG8_SCHED; PG8_LDA(At, 1, 0); PG8_STAGEA(PG8_SA(0, 1), a2 + hstepA, voffA);
;             PG8_WAIT_V(8); PG8_WAIT_L(0); PG8_BAR; PG8_MMA(0, 0, At, B0); PG8_MMA(0, 1, At, B1); PG8_BAR; PG8_SCHED;
;             PG8_LDA(At, 1, 1); PG8_STAGEB(PG8_SB(1, 0), b3, voffB); PG8_STAGEB(PG8_SB(1, 1), b3 + hstepB, voffB); PG8_STAGEA(PG8_SA(1, 0), a3, voffA);
;             PG8_WAIT_V(8); PG8_WAIT_L(0); PG8_BAR; PG8_MMA(1, 0, At, B0); PG8_MMA(1, 1, At, B1); PG8_BAR; PG8_SCHED;
	s_add_u32 s36, s16, 0x8000
	s_addc_u32 s37, s17, 0
	s_add_i32 s83, s83, s38
	v_lshl_add_u64 v[210:211], s[36:37], 0, v[16:17]
	s_mov_b32 m0, s83
	ds_read_b128 v[178:181], v161 offset:49152
	ds_read_b128 v[182:185], v161 offset:50176
	ds_read_b128 v[186:189], v161 offset:51200
	ds_read_b128 v[190:193], v161 offset:52224
	ds_read_b128 v[194:197], v161 offset:53248
	ds_read_b128 v[198:201], v161 offset:54272
	ds_read_b128 v[202:205], v161 offset:55296
	ds_read_b128 v[206:209], v161 offset:56320
	global_load_lds_dwordx4 v[210:211], off
	s_add_i32 m0, s83, 0x2000
	s_add_u32 s16, s16, 0xc000
	v_lshl_add_u64 v[210:211], s[36:37], 0, v[138:139]
	s_addc_u32 s17, s17, 0
	s_add_i32 s36, s90, s38
	global_load_lds_dwordx4 v[210:211], off
	v_lshl_add_u64 v[210:211], s[16:17], 0, v[16:17]
	s_mov_b32 m0, s36
	s_nop 0
	global_load_lds_dwordx4 v[210:211], off
	v_lshl_add_u64 v[210:211], s[16:17], 0, v[138:139]
	s_add_i32 m0, s36, 0x2000
	s_nop 0
	global_load_lds_dwordx4 v[210:211], off
	v_lshl_add_u64 v[210:211], s[26:27], 0, v[142:143]
	s_mov_b32 m0, s50
	s_nop 0
	global_load_lds_dwordx4 v[210:211], off
	v_lshl_add_u64 v[210:211], s[26:27], 0, v[140:141]
	s_mov_b32 m0, s51
	s_nop 0
	global_load_lds_dwordx4 v[210:211], off
	s_waitcnt vmcnt(8)
	s_waitcnt lgkmcnt(0)
	s_barrier
	v_mfma_f32_16x16x32_bf16 v[62:65], v[130:133], v[178:181], v[62:65]
	v_mfma_f32_16x16x32_bf16 v[58:61], v[148:151], v[178:181], v[58:61]
	v_mfma_f32_16x16x32_bf16 v[46:49], v[130:133], v[186:189], v[46:49]
	v_mfma_f32_16x16x32_bf16 v[42:45], v[148:151], v[186:189], v[42:45]
	v_mfma_f32_16x16x32_bf16 v[30:33], v[130:133], v[194:197], v[30:33]
	v_mfma_f32_16x16x32_bf16 v[26:29], v[148:151], v[194:197], v[26:29]
	v_mfma_f32_16x16x32_bf16 v[12:15], v[130:133], v[202:205], v[12:15]
	v_mfma_f32_16x16x32_bf16 v[8:11], v[148:151], v[202:205], v[8:11]
	v_mfma_f32_16x16x32_bf16 v[62:65], v[134:137], v[182:185], v[62:65]
	v_mfma_f32_16x16x32_bf16 v[58:61], v[152:155], v[182:185], v[58:61]
	v_mfma_f32_16x16x32_bf16 v[46:49], v[134:137], v[190:193], v[46:49]
	v_mfma_f32_16x16x32_bf16 v[42:45], v[152:155], v[190:193], v[42:45]
	v_mfma_f32_16x16x32_bf16 v[30:33], v[134:137], v[198:201], v[30:33]
	v_mfma_f32_16x16x32_bf16 v[26:29], v[152:155], v[198:201], v[26:29]
	v_mfma_f32_16x16x32_bf16 v[12:15], v[134:137], v[206:209], v[12:15]
	v_mfma_f32_16x16x32_bf16 v[8:11], v[152:155], v[206:209], v[8:11]
	v_mfma_f32_16x16x32_bf16 v[54:57], v[162:165], v[178:181], v[54:57]
	v_mfma_f32_16x16x32_bf16 v[50:53], v[170:173], v[178:181], v[50:53]
	v_mfma_f32_16x16x32_bf16 v[38:41], v[162:165], v[186:189], v[38:41]
	v_mfma_f32_16x16x32_bf16 v[34:37], v[170:173], v[186:189], v[34:37]
	v_mfma_f32_16x16x32_bf16 v[22:25], v[162:165], v[194:197], v[22:25]
	v_mfma_f32_16x16x32_bf16 v[18:21], v[170:173], v[194:197], v[18:21]
	v_mfma_f32_16x16x32_bf16 v[4:7], v[162:165], v[202:205], v[4:7]
	v_mfma_f32_16x16x32_bf16 v[0:3], v[170:173], v[202:205], v[0:3]
	v_mfma_f32_16x16x32_bf16 v[54:57], v[166:169], v[182:185], v[54:57]
	v_mfma_f32_16x16x32_bf16 v[50:53], v[174:177], v[182:185], v[50:53]
	v_mfma_f32_16x16x32_bf16 v[38:41], v[166:169], v[190:193], v[38:41]
	v_mfma_f32_16x16x32_bf16 v[34:37], v[174:177], v[190:193], v[34:37]
	v_mfma_f32_16x16x32_bf16 v[22:25], v[166:169], v[198:201], v[22:25]
	v_mfma_f32_16x16x32_bf16 v[18:21], v[174:177], v[198:201], v[18:21]
	v_mfma_f32_16x16x32_bf16 v[4:7], v[166:169], v[206:209], v[4:7]
	v_mfma_f32_16x16x32_bf16 v[0:3], v[174:177], v[206:209], v[0:3]
	s_barrier
	s_add_i32 s82, s82, 2
	s_add_u32 s24, s24, 0x10000
	s_addc_u32 s25, s25, 0
	s_add_u32 s0, s0, 0x10000
	s_addc_u32 s1, s1, 0
	v_add_u32_e32 v212, 0x10000, v157
.LBB0_848:
	s_add_u32 s16, s24, 0x4000
	s_addc_u32 s17, s25, 0
	s_cmpk_eq_i32 s82, 0xfc
	s_cselect_b32 s36, s73, s16
	s_cselect_b32 s37, s11, s17
	s_cselect_b32 s16, s78, s0
	s_cselect_b32 s17, s15, s1
	s_add_u32 s26, s36, 0x8000
	s_addc_u32 s27, s37, 0
	s_add_i32 s83, 0, 0x10000
	s_add_i32 s94, 0, 0x14000
	ds_read_b128 v[130:133], v212
	ds_read_b128 v[134:137], v212 offset:1024
	ds_read_b128 v[148:151], v212 offset:2048
	ds_read_b128 v[152:155], v212 offset:3072
	ds_read_b128 v[162:165], v212 offset:16384
	ds_read_b128 v[166:169], v212 offset:17408
	ds_read_b128 v[170:173], v212 offset:18432
	ds_read_b128 v[174:177], v212 offset:19456
	s_add_i32 m0, s39, 0xc000
	ds_read_b128 v[178:181], v161
	ds_read_b128 v[182:185], v161 offset:1024
	ds_read_b128 v[186:189], v161 offset:2048
	ds_read_b128 v[190:193], v161 offset:3072
	ds_read_b128 v[194:197], v161 offset:4096
	ds_read_b128 v[198:201], v161 offset:5120
	ds_read_b128 v[202:205], v161 offset:6144
	global_load_lds_dwordx4 v144, s[24:25]
	s_add_i32 m0, s39, 0xe000
	ds_read_b128 v[206:209], v161 offset:7168
	global_load_lds_dwordx4 v146, s[24:25]
	s_waitcnt vmcnt(8)
	s_waitcnt lgkmcnt(0)
	s_barrier
; #define PG8_STAGEA(bufoff, gbase, voff) PG8_STAGE_X(bufoff, gbase, voff, AUXA)
; #define PG8_STAGEB(bufoff, gbase, voff) PG8_STAGE_X(bufoff, gbase, voff, AUXB)
; #define PG8_LDA(dst, b, h) do { _Pragma("unroll") for (int m = 0; m < 4; ++m) _Pragma("unroll") for (int k = 0; k < 2; ++k) dst[m][k] = *(const PG8_LAS bf16x8*)(lds + PG8_SA(b, h) + aoff + m * 2048 + k * 1024); } while (0)
; #define PG8_LDB(dst, b, h) do { _Pragma("unroll") for (int n = 0; n < 2; ++n) _Pragma("unroll") for (int k = 0; k < 2; ++k) dst[n][k] = *(const PG8_LAS bf16x8*)(lds + PG8_SB(b, h) + boff + n * 2048 + k * 1024); } while (0)
; #define PG8_MMA(ai, bj, At, Bt) do { if (GEMM_PRIO_MODE == 0) __builtin_amdgcn_s_setprio(1); PG8_MMA_LOOPS \
;         acc[ai][bj][m][n] = __builtin_amdgcn_mfma_f32_16x16x32_bf16(Bt[n][k], At[m][k], acc[ai][bj][m][n], 0, 0, 0); if (GEMM_PRIO_MODE == 0) __builtin_amdgcn_s_setprio(0); } while (0)
; #define PG8_WAIT_V(n) asm volatile("s_waitcnt vmcnt(" #n ")" ::: "memory")
; #define PG8_WAIT_VR(n, nr, flag) asm volatile("s_cmp_eq_u32 %0, 0\n\ts_cbranch_scc1 .Lpg8s%=\n\ts_waitcnt vmcnt(" #nr ")\n\ts_branch .Lpg8d%=\n.Lpg8s%=:\n\ts_waitcnt vmcnt(" #n ")\n.Lpg8d%=:" :: "s"(flag) : "memory", "scc")
; #define PG8_WAIT_L(n) asm volatile("s_waitcnt lgkmcnt(" #n ")" ::: "memory")
; #define PG8_BAR __builtin_amdgcn_s_barrier()
; #define PG8_SCHED __builtin_amdgcn_sched_barrier(0)
;     ...
;             PG8_LDB(B0, 0, 0); PG8_LDB(B1, 0, 1); PG8_SCHED; PG8_LDA(At, 0, 0); PG8_STAGEA(PG8_SA(1, 1), a1 + hstepA, voffA);
;     ...
;             const int relax = __builtin_amdgcn_readfirstlane((t == 0 && ui > 0) ? 1 : 0);
;             PG8_WAIT_VR(8, 24, relax); PG8_WAIT_L(0); PG8_BAR; PG8_MMA(0, 0, At, B0); PG8_MMA(0, 1, At, B1); PG8_BAR; PG8_SCHED;
;     ...
;             PG8_WAIT_V(8); PG8_WAIT_L(0); PG8_BAR; PG8_MMA(0, 0, At, B0); PG8_MMA(0, 1, At, B1); PG8_BAR; PG8_SCHED;
;     ...
;             PG8_LDA(At, 0, 1); PG8_STAGEB(PG8_SB(0, 0), b2, voffB); PG8_STAGEB(PG8_SB(0, 1), b2 + hstepB, voffB); PG8_STAGEA(PG8_SA(0, 0), a2, voffA);
;     ...
;             PG8_WAIT_VR(8, 24, relax); PG8_WAIT_L(0); PG8_BAR; PG8_MMA(1, 0, At, B0); PG8_MMA(1, 1, At, B1); PG8_BAR; PG8_SCHED;
;     ...
;             PG8_WAIT_V(8); PG8_WAIT_L(0); PG8_BAR; PG8_MMA(1, 0, At, B0); PG8_MMA(1, 1, At, B1); PG8_BAR; PG8_SCHED;
	v_mfma_f32_16x16x32_bf16 v[126:129], v[130:133], v[178:181], v[126:129]
	v_mfma_f32_16x16x32_bf16 v[122:125], v[148:151], v[178:181], v[122:125]
	v_mfma_f32_16x16x32_bf16 v[110:113], v[130:133], v[186:189], v[110:113]
	v_mfma_f32_16x16x32_bf16 v[106:109], v[148:151], v[186:189], v[106:109]
	v_mfma_f32_16x16x32_bf16 v[94:97], v[130:133], v[194:197], v[94:97]
	v_mfma_f32_16x16x32_bf16 v[90:93], v[148:151], v[194:197], v[90:93]
	v_mfma_f32_16x16x32_bf16 v[78:81], v[130:133], v[202:205], v[78:81]
	v_mfma_f32_16x16x32_bf16 v[74:77], v[148:151], v[202:205], v[74:77]
	v_mfma_f32_16x16x32_bf16 v[126:129], v[134:137], v[182:185], v[126:129]
	v_mfma_f32_16x16x32_bf16 v[122:125], v[152:155], v[182:185], v[122:125]
	v_mfma_f32_16x16x32_bf16 v[110:113], v[134:137], v[190:193], v[110:113]
	v_mfma_f32_16x16x32_bf16 v[106:109], v[152:155], v[190:193], v[106:109]
	v_mfma_f32_16x16x32_bf16 v[94:97], v[134:137], v[198:201], v[94:97]
	v_mfma_f32_16x16x32_bf16 v[90:93], v[152:155], v[198:201], v[90:93]
	v_mfma_f32_16x16x32_bf16 v[78:81], v[134:137], v[206:209], v[78:81]
	v_mfma_f32_16x16x32_bf16 v[74:77], v[152:155], v[206:209], v[74:77]
	v_mfma_f32_16x16x32_bf16 v[118:121], v[162:165], v[178:181], v[118:121]
	v_mfma_f32_16x16x32_bf16 v[114:117], v[170:173], v[178:181], v[114:117]
	v_mfma_f32_16x16x32_bf16 v[102:105], v[162:165], v[186:189], v[102:105]
	v_mfma_f32_16x16x32_bf16 v[98:101], v[170:173], v[186:189], v[98:101]
	v_mfma_f32_16x16x32_bf16 v[86:89], v[162:165], v[194:197], v[86:89]
	v_mfma_f32_16x16x32_bf16 v[82:85], v[170:173], v[194:197], v[82:85]
	v_mfma_f32_16x16x32_bf16 v[70:73], v[162:165], v[202:205], v[70:73]
	v_mfma_f32_16x16x32_bf16 v[66:69], v[170:173], v[202:205], v[66:69]
	v_mfma_f32_16x16x32_bf16 v[118:121], v[166:169], v[182:185], v[118:121]
	v_mfma_f32_16x16x32_bf16 v[114:117], v[174:177], v[182:185], v[114:117]
	v_mfma_f32_16x16x32_bf16 v[102:105], v[166:169], v[190:193], v[102:105]
	v_mfma_f32_16x16x32_bf16 v[98:101], v[174:177], v[190:193], v[98:101]
	v_mfma_f32_16x16x32_bf16 v[86:89], v[166:169], v[198:201], v[86:89]
	v_mfma_f32_16x16x32_bf16 v[82:85], v[174:177], v[198:201], v[82:85]
	v_mfma_f32_16x16x32_bf16 v[70:73], v[166:169], v[206:209], v[70:73]
	v_mfma_f32_16x16x32_bf16 v[66:69], v[174:177], v[206:209], v[66:69]
	s_barrier
	s_add_i32 s83, s83, s38
	s_mov_b32 m0, s83
	ds_read_b128 v[178:181], v161 offset:16384
	ds_read_b128 v[182:185], v161 offset:17408
	ds_read_b128 v[186:189], v161 offset:18432
	ds_read_b128 v[190:193], v161 offset:19456
	global_load_lds_dwordx4 v16, s[16:17]
	s_add_i32 m0, s83, 0x2000
	s_add_u32 s90, s16, 0x4000
	s_addc_u32 s91, s17, 0
	s_add_i32 s83, s94, s38
	global_load_lds_dwordx4 v138, s[16:17]
	s_mov_b32 m0, s83
	ds_read_b128 v[206:209], v161 offset:23552
	global_load_lds_dwordx4 v16, s[90:91]
	s_add_i32 m0, s83, 0x2000
	ds_read_b128 v[202:205], v161 offset:22528
	global_load_lds_dwordx4 v138, s[90:91]
	s_mov_b32 m0, s39
	ds_read_b128 v[198:201], v161 offset:21504
	global_load_lds_dwordx4 v142, s[36:37]
	s_mov_b32 m0, s40
	ds_read_b128 v[194:197], v161 offset:20480
	global_load_lds_dwordx4 v140, s[36:37]
	s_waitcnt vmcnt(8)
	s_waitcnt lgkmcnt(0)
	s_nop 0
	s_barrier
	v_mfma_f32_16x16x32_bf16 v[62:65], v[130:133], v[178:181], v[62:65]
	v_mfma_f32_16x16x32_bf16 v[58:61], v[148:151], v[178:181], v[58:61]
	v_mfma_f32_16x16x32_bf16 v[46:49], v[130:133], v[186:189], v[46:49]
	v_mfma_f32_16x16x32_bf16 v[42:45], v[148:151], v[186:189], v[42:45]
	v_mfma_f32_16x16x32_bf16 v[30:33], v[130:133], v[194:197], v[30:33]
	v_mfma_f32_16x16x32_bf16 v[26:29], v[148:151], v[194:197], v[26:29]
	v_mfma_f32_16x16x32_bf16 v[12:15], v[130:133], v[202:205], v[12:15]
	v_mfma_f32_16x16x32_bf16 v[8:11], v[148:151], v[202:205], v[8:11]
	v_mfma_f32_16x16x32_bf16 v[62:65], v[134:137], v[182:185], v[62:65]
	v_mfma_f32_16x16x32_bf16 v[58:61], v[152:155], v[182:185], v[58:61]
	v_mfma_f32_16x16x32_bf16 v[46:49], v[134:137], v[190:193], v[46:49]
	v_mfma_f32_16x16x32_bf16 v[42:45], v[152:155], v[190:193], v[42:45]
	v_mfma_f32_16x16x32_bf16 v[30:33], v[134:137], v[198:201], v[30:33]
	v_mfma_f32_16x16x32_bf16 v[26:29], v[152:155], v[198:201], v[26:29]
	v_mfma_f32_16x16x32_bf16 v[12:15], v[134:137], v[206:209], v[12:15]
	v_mfma_f32_16x16x32_bf16 v[8:11], v[152:155], v[206:209], v[8:11]
	v_mfma_f32_16x16x32_bf16 v[54:57], v[162:165], v[178:181], v[54:57]
	v_mfma_f32_16x16x32_bf16 v[50:53], v[170:173], v[178:181], v[50:53]
	v_mfma_f32_16x16x32_bf16 v[38:41], v[162:165], v[186:189], v[38:41]
	v_mfma_f32_16x16x32_bf16 v[34:37], v[170:173], v[186:189], v[34:37]
	v_mfma_f32_16x16x32_bf16 v[22:25], v[162:165], v[194:197], v[22:25]
	v_mfma_f32_16x16x32_bf16 v[18:21], v[170:173], v[194:197], v[18:21]
	v_mfma_f32_16x16x32_bf16 v[4:7], v[162:165], v[202:205], v[4:7]
	v_mfma_f32_16x16x32_bf16 v[0:3], v[170:173], v[202:205], v[0:3]
	v_mfma_f32_16x16x32_bf16 v[54:57], v[166:169], v[182:185], v[54:57]
	v_mfma_f32_16x16x32_bf16 v[50:53], v[174:177], v[182:185], v[50:53]
	v_mfma_f32_16x16x32_bf16 v[38:41], v[166:169], v[190:193], v[38:41]
	v_mfma_f32_16x16x32_bf16 v[34:37], v[174:177], v[190:193], v[34:37]
	v_mfma_f32_16x16x32_bf16 v[22:25], v[166:169], v[198:201], v[22:25]
	v_mfma_f32_16x16x32_bf16 v[18:21], v[174:177], v[198:201], v[18:21]
	v_mfma_f32_16x16x32_bf16 v[4:7], v[166:169], v[206:209], v[4:7]
	v_mfma_f32_16x16x32_bf16 v[0:3], v[174:177], v[206:209], v[0:3]
	s_barrier
; #define PG8_STAGEA(bufoff, gbase, voff) PG8_STAGE_X(bufoff, gbase, voff, AUXA)
; #define PG8_STAGEB(bufoff, gbase, voff) PG8_STAGE_X(bufoff, gbase, voff, AUXB)
; #define PG8_LDA(dst, b, h) do { _Pragma("unroll") for (int m = 0; m < 4; ++m) _Pragma("unroll") for (int k = 0; k < 2; ++k) dst[m][k] = *(const PG8_LAS bf16x8*)(lds + PG8_SA(b, h) + aoff + m * 2048 + k * 1024); } while (0)
; #define PG8_LDB(dst, b, h) do { _Pragma("unroll") for (int n = 0; n < 2; ++n) _Pragma("unroll") for (int k = 0; k < 2; ++k) dst[n][k] = *(const PG8_LAS bf16x8*)(lds + PG8_SB(b, h) + boff + n * 2048 + k * 1024); } while (0)
; #define PG8_MMA(ai, bj, At, Bt) do { if (GEMM_PRIO_MODE == 0) __builtin_amdgcn_s_setprio(1); PG8_MMA_LOOPS \
;         acc[ai][bj][m][n] = __builtin_amdgcn_mfma_f32_16x16x32_bf16(Bt[n][k], At[m][k], acc[ai][bj][m][n], 0, 0, 0); if (GEMM_PRIO_MODE == 0) __builtin_amdgcn_s_setprio(0); } while (0)
; #define PG8_WAIT_V(n) asm volatile("s_waitcnt vmcnt(" #n ")" ::: "memory")
; #define PG8_WAIT_L(n) asm volatile("s_waitcnt lgkmcnt(" #n ")" ::: "memory")
; #define PG8_BAR __builtin_amdgcn_s_barrier()
; #define PG8_SCHED __builtin_amdgcn_sched_barrier(0)
;     ...
;         for (int t = t0; t < nt; t += 2) {
;             const bool last = (t == nt - 2);
;             const char* a1 = cA + (size_t)(t + 1) * kstepA;
;             const char* a2 = last ? nA : cA + (size_t)(t + 2) * kstepA; const char* b2 = last ? nB : cB + (size_t)(t + 2) * kstepB;
;     ...
;             PG8_LDB(B0, 1, 0); PG8_LDB(B1, 1, 1); PG8_SCHED; PG8_LDA(At, 1, 0); PG8_STAGEA(PG8_SA(0, 1), a2 + hstepA, voffA);
;             PG8_WAIT_V(8); PG8_WAIT_L(0); PG8_BAR; PG8_MMA(0, 0, At, B0); PG8_MMA(0, 1, At, B1); PG8_BAR; PG8_SCHED;
;             PG8_LDA(At, 1, 1); PG8_STAGEB(PG8_SB(1, 0), b3, voffB); PG8_STAGEB(PG8_SB(1, 1), b3 + hstepB, voffB); PG8_STAGEA(PG8_SA(1, 0), a3, voffA);
;             PG8_WAIT_V(8); PG8_WAIT_L(0); PG8_BAR; PG8_MMA(1, 0, At, B0); PG8_MMA(1, 1, At, B1); PG8_BAR; PG8_SCHED;
	s_add_i32 s83, 0, 0x18000
	s_add_i32 s90, 0, 0x1c000
	ds_read_b128 v[130:133], v212 offset:32768
	ds_read_b128 v[134:137], v212 offset:33792
	ds_read_b128 v[148:151], v212 offset:34816
	ds_read_b128 v[152:155], v212 offset:35840
	ds_read_b128 v[162:165], v212 offset:49152
	ds_read_b128 v[166:169], v212 offset:50176
	ds_read_b128 v[170:173], v212 offset:51200
	ds_read_b128 v[174:177], v212 offset:52224
	s_add_u32 s36, s36, 0x4000
	s_addc_u32 s37, s37, 0
	s_mov_b32 m0, s41
	ds_read_b128 v[178:181], v161 offset:32768
	ds_read_b128 v[182:185], v161 offset:33792
	ds_read_b128 v[186:189], v161 offset:34816
	ds_read_b128 v[190:193], v161 offset:35840
	ds_read_b128 v[194:197], v161 offset:36864
	ds_read_b128 v[198:201], v161 offset:37888
	ds_read_b128 v[202:205], v161 offset:38912
	global_load_lds_dwordx4 v142, s[36:37]
	s_mov_b32 m0, s42
	ds_read_b128 v[206:209], v161 offset:39936
	global_load_lds_dwordx4 v140, s[36:37]
	s_waitcnt vmcnt(8)
	s_waitcnt lgkmcnt(0)
	s_nop 0
	s_barrier
	v_mfma_f32_16x16x32_bf16 v[126:129], v[130:133], v[178:181], v[126:129]
	v_mfma_f32_16x16x32_bf16 v[122:125], v[148:151], v[178:181], v[122:125]
	v_mfma_f32_16x16x32_bf16 v[110:113], v[130:133], v[186:189], v[110:113]
	v_mfma_f32_16x16x32_bf16 v[106:109], v[148:151], v[186:189], v[106:109]
	v_mfma_f32_16x16x32_bf16 v[94:97], v[130:133], v[194:197], v[94:97]
	v_mfma_f32_16x16x32_bf16 v[90:93], v[148:151], v[194:197], v[90:93]
	v_mfma_f32_16x16x32_bf16 v[78:81], v[130:133], v[202:205], v[78:81]
	v_mfma_f32_16x16x32_bf16 v[74:77], v[148:151], v[202:205], v[74:77]
	v_mfma_f32_16x16x32_bf16 v[126:129], v[134:137], v[182:185], v[126:129]
	v_mfma_f32_16x16x32_bf16 v[122:125], v[152:155], v[182:185], v[122:125]
	v_mfma_f32_16x16x32_bf16 v[110:113], v[134:137], v[190:193], v[110:113]
	v_mfma_f32_16x16x32_bf16 v[106:109], v[152:155], v[190:193], v[106:109]
	v_mfma_f32_16x16x32_bf16 v[94:97], v[134:137], v[198:201], v[94:97]
	v_mfma_f32_16x16x32_bf16 v[90:93], v[152:155], v[198:201], v[90:93]
	v_mfma_f32_16x16x32_bf16 v[78:81], v[134:137], v[206:209], v[78:81]
	v_mfma_f32_16x16x32_bf16 v[74:77], v[152:155], v[206:209], v[74:77]
	v_mfma_f32_16x16x32_bf16 v[118:121], v[162:165], v[178:181], v[118:121]
	v_mfma_f32_16x16x32_bf16 v[114:117], v[170:173], v[178:181], v[114:117]
	v_mfma_f32_16x16x32_bf16 v[102:105], v[162:165], v[186:189], v[102:105]
	v_mfma_f32_16x16x32_bf16 v[98:101], v[170:173], v[186:189], v[98:101]
	v_mfma_f32_16x16x32_bf16 v[86:89], v[162:165], v[194:197], v[86:89]
	v_mfma_f32_16x16x32_bf16 v[82:85], v[170:173], v[194:197], v[82:85]
	v_mfma_f32_16x16x32_bf16 v[70:73], v[162:165], v[202:205], v[70:73]
	v_mfma_f32_16x16x32_bf16 v[66:69], v[170:173], v[202:205], v[66:69]
	v_mfma_f32_16x16x32_bf16 v[118:121], v[166:169], v[182:185], v[118:121]
	v_mfma_f32_16x16x32_bf16 v[114:117], v[174:177], v[182:185], v[114:117]
	v_mfma_f32_16x16x32_bf16 v[102:105], v[166:169], v[190:193], v[102:105]
	v_mfma_f32_16x16x32_bf16 v[98:101], v[174:177], v[190:193], v[98:101]
	v_mfma_f32_16x16x32_bf16 v[86:89], v[166:169], v[198:201], v[86:89]
	v_mfma_f32_16x16x32_bf16 v[82:85], v[174:177], v[198:201], v[82:85]
	v_mfma_f32_16x16x32_bf16 v[70:73], v[166:169], v[206:209], v[70:73]
	v_mfma_f32_16x16x32_bf16 v[66:69], v[174:177], v[206:209], v[66:69]
	s_barrier
	s_add_u32 s36, s16, 0x8000
	s_addc_u32 s37, s17, 0
	s_add_i32 s83, s83, s38
	s_mov_b32 m0, s83
	ds_read_b128 v[178:181], v161 offset:49152
	ds_read_b128 v[182:185], v161 offset:50176
	ds_read_b128 v[186:189], v161 offset:51200
	ds_read_b128 v[190:193], v161 offset:52224
	global_load_lds_dwordx4 v16, s[36:37]
	s_add_i32 m0, s83, 0x2000
	s_add_u32 s16, s16, 0xc000
	s_addc_u32 s17, s17, 0
	global_load_lds_dwordx4 v138, s[36:37]
	s_add_i32 s36, s90, s38
	s_mov_b32 m0, s36
	ds_read_b128 v[206:209], v161 offset:56320
	global_load_lds_dwordx4 v16, s[16:17]
	s_add_i32 m0, s36, 0x2000
	ds_read_b128 v[202:205], v161 offset:55296
	global_load_lds_dwordx4 v138, s[16:17]
	s_mov_b32 m0, s50
	ds_read_b128 v[198:201], v161 offset:54272
	global_load_lds_dwordx4 v142, s[26:27]
	s_mov_b32 m0, s51
	ds_read_b128 v[194:197], v161 offset:53248
	global_load_lds_dwordx4 v140, s[26:27]
	s_waitcnt vmcnt(8)
	s_waitcnt lgkmcnt(0)
	s_barrier
	v_mfma_f32_16x16x32_bf16 v[62:65], v[130:133], v[178:181], v[62:65]
	v_mfma_f32_16x16x32_bf16 v[58:61], v[148:151], v[178:181], v[58:61]
	v_mfma_f32_16x16x32_bf16 v[46:49], v[130:133], v[186:189], v[46:49]
	v_mfma_f32_16x16x32_bf16 v[42:45], v[148:151], v[186:189], v[42:45]
	v_mfma_f32_16x16x32_bf16 v[30:33], v[130:133], v[194:197], v[30:33]
	v_mfma_f32_16x16x32_bf16 v[26:29], v[148:151], v[194:197], v[26:29]
	v_mfma_f32_16x16x32_bf16 v[12:15], v[130:133], v[202:205], v[12:15]
	v_mfma_f32_16x16x32_bf16 v[8:11], v[148:151], v[202:205], v[8:11]
	v_mfma_f32_16x16x32_bf16 v[62:65], v[134:137], v[182:185], v[62:65]
	v_mfma_f32_16x16x32_bf16 v[58:61], v[152:155], v[182:185], v[58:61]
	v_mfma_f32_16x16x32_bf16 v[46:49], v[134:137], v[190:193], v[46:49]
	v_mfma_f32_16x16x32_bf16 v[42:45], v[152:155], v[190:193], v[42:45]
	v_mfma_f32_16x16x32_bf16 v[30:33], v[134:137], v[198:201], v[30:33]
	v_mfma_f32_16x16x32_bf16 v[26:29], v[152:155], v[198:201], v[26:29]
	v_mfma_f32_16x16x32_bf16 v[12:15], v[134:137], v[206:209], v[12:15]
	v_mfma_f32_16x16x32_bf16 v[8:11], v[152:155], v[206:209], v[8:11]
	v_mfma_f32_16x16x32_bf16 v[54:57], v[162:165], v[178:181], v[54:57]
	v_mfma_f32_16x16x32_bf16 v[50:53], v[170:173], v[178:181], v[50:53]
	v_mfma_f32_16x16x32_bf16 v[38:41], v[162:165], v[186:189], v[38:41]
	v_mfma_f32_16x16x32_bf16 v[34:37], v[170:173], v[186:189], v[34:37]
	v_mfma_f32_16x16x32_bf16 v[22:25], v[162:165], v[194:197], v[22:25]
	v_mfma_f32_16x16x32_bf16 v[18:21], v[170:173], v[194:197], v[18:21]
	v_mfma_f32_16x16x32_bf16 v[4:7], v[162:165], v[202:205], v[4:7]
	v_mfma_f32_16x16x32_bf16 v[0:3], v[170:173], v[202:205], v[0:3]
	v_mfma_f32_16x16x32_bf16 v[54:57], v[166:169], v[182:185], v[54:57]
	v_mfma_f32_16x16x32_bf16 v[50:53], v[174:177], v[182:185], v[50:53]
	v_mfma_f32_16x16x32_bf16 v[38:41], v[166:169], v[190:193], v[38:41]
	v_mfma_f32_16x16x32_bf16 v[34:37], v[174:177], v[190:193], v[34:37]
	v_mfma_f32_16x16x32_bf16 v[22:25], v[166:169], v[198:201], v[22:25]
	v_mfma_f32_16x16x32_bf16 v[18:21], v[174:177], v[198:201], v[18:21]
	v_mfma_f32_16x16x32_bf16 v[4:7], v[166:169], v[206:209], v[4:7]
	v_mfma_f32_16x16x32_bf16 v[0:3], v[174:177], v[206:209], v[0:3]
	s_barrier
	s_add_i32 s82, s82, 2
	s_add_u32 s24, s24, 0x10000
	s_addc_u32 s25, s25, 0
	s_add_u32 s0, s0, 0x10000
	s_addc_u32 s1, s1, 0
	s_cmpk_gt_u32 s82, 0xfd
	s_cbranch_scc0 .LBB0_848
	s_and_b64 vcc, exec, s[8:9]
	s_cbranch_vccz .LBB0_851
	s_barrier
